# GEMM epilogue dwordx4 stores made write-through (sc0 sc1) so the grid barrier's L2 writeback has nothing left to flush
# baseline (speedup 1.0000x reference)
; __device__ __forceinline__ unsigned pk2(float lo, float hi) { f32x2 v = {lo, hi}; bf16x2_t b = __builtin_convertvector(v, bf16x2_t); return __builtin_bit_cast(unsigned, b); }
; __device__ __forceinline__ float bflo(unsigned w) { return __uint_as_float(w << 16); }
; __device__ __forceinline__ float bfhi(unsigned w) { return __uint_as_float(w & 0xffff0000u); }
; __device__ __forceinline__ float fast_sigmoid(float g) { return __builtin_amdgcn_rcpf(1.0f + __expf(-g)); }
;     __device__ __forceinline__ void operator()(const f32x4 (&acc)[2][2][4][2], const Unit& u, int wr, int wc, int fr, int fq) const {
;         const int row0 = u.pm * BM + wr * 64 + fr, col0 = u.pn * HALF + wc * 32 + 8 * fq;
;         const f32x4 bv0 = *(const f32x4*)(bias + col0), bv1 = *(const f32x4*)(bias + col0 + 4), bg0 = *(const f32x4*)(bias + DM + col0), bg1 = *(const f32x4*)(bias + DM + col0 + 4);
;         u32x4 cur = *(const u32x4*)(xb + (size_t)row0 * DM + col0), nxt = cur;
; #pragma unroll
;         for (int j = 0; j < 8; ++j) { const int ai = j >> 2, m = j & 3; const int row = row0 + ai * HALF + m * 16; const size_t off = (size_t)row * DM + col0; float ss = 0.f; f32x4 o[2];
;             if (j < 7) nxt = *(const u32x4*)(xb + (size_t)(row0 + ((j + 1) >> 2) * HALF + ((j + 1) & 3) * 16) * DM + col0);
; #pragma unroll
;             for (int n = 0; n < 2; ++n) {
;                 const f32x4 v = acc[ai][0][m][n] + (n ? bv1 : bv0), g = acc[ai][1][m][n] + (n ? bg1 : bg0);
;                 const unsigned w0 = n ? cur.z : cur.x, w1 = n ? cur.w : cur.y; o[n] = (f32x4){bflo(w0), bfhi(w0), bflo(w1), bfhi(w1)};
;                 o[n][0] += v[0] * fast_sigmoid(g[0]); o[n][1] += v[1] * fast_sigmoid(g[1]); o[n][2] += v[2] * fast_sigmoid(g[2]); o[n][3] += v[3] * fast_sigmoid(g[3]);
;                 ss += (o[n][0] * o[n][0] + o[n][1] * o[n][1]) + (o[n][2] * o[n][2] + o[n][3] * o[n][3]); }
;             { u32x4 w; w.x = pk2(o[0][0], o[0][1]); w.y = pk2(o[0][2], o[0][3]); w.z = pk2(o[1][0], o[1][1]); w.w = pk2(o[1][2], o[1][3]); *(u32x4*)(xb + off) = w; }
;             ss += __shfl_xor(ss, 16); ss += __shfl_xor(ss, 32); if (fq == 0) rsq[(size_t)row * 64 + u.pn * 4 + wc] = ss;
;             cur = nxt;
;             asm volatile("" ::: "memory"); }
.LBB0_266:
	v_lshl_or_b32 v164, s52, 7, v176
	v_ashrrev_i32_e32 v165, 31, v164
	v_lshlrev_b64 v[84:85], 2, v[164:165]
	v_lshl_add_u64 v[86:87], s[8:9], 0, v[84:85]
	v_lshl_add_u64 v[102:103], s[60:61], 0, v[84:85]
	global_load_dwordx4 v[88:91], v[86:87], off offset:16
	global_load_dwordx4 v[106:109], v[86:87], off
	s_nop 0
	global_load_dwordx4 v[84:87], v[102:103], off offset:16
	s_nop 0
	global_load_dwordx4 v[102:105], v[102:103], off
	v_lshl_add_u32 v166, s54, 8, v174
	v_ashrrev_i32_e32 v167, 31, v166
	v_lshlrev_b64 v[146:147], 12, v[166:167]
	v_lshl_add_u64 v[146:147], s[12:13], 0, v[146:147]
	v_lshlrev_b64 v[148:149], 1, v[164:165]
	v_lshl_add_u64 v[172:173], v[146:147], 0, v[148:149]
	global_load_dwordx4 v[150:153], v[172:173], off
	v_and_b32_e32 v147, 64, v251
	v_xor_b32_e32 v146, 16, v251
	v_add_u32_e32 v147, 64, v147
	v_cmp_lt_i32_e32 vcc, v146, v147
	v_or_b32_e32 v168, 16, v166
	v_ashrrev_i32_e32 v169, 31, v168
	v_cndmask_b32_e32 v146, v251, v146, vcc
	v_lshlrev_b32_e32 v178, 2, v146
	v_xor_b32_e32 v146, 32, v251
	v_cmp_lt_i32_e32 vcc, v146, v147
	s_lshl_b32 s52, s52, 2
	s_ashr_i32 s53, s52, 31
	v_cndmask_b32_e32 v146, v251, v146, vcc
	v_lshlrev_b32_e32 v179, 2, v146
	v_lshlrev_b64 v[146:147], 12, v[168:169]
	v_lshl_add_u64 v[146:147], s[12:13], 0, v[146:147]
	v_lshl_add_u64 v[170:171], v[146:147], 0, v[148:149]
	global_load_dwordx4 v[146:149], v[170:171], off
	s_waitcnt vmcnt(0)
	v_pk_add_f32 v[134:135], v[134:135], v[88:89]
	v_pk_add_f32 v[130:131], v[130:131], v[84:85]
	v_pk_add_f32 v[138:139], v[138:139], v[102:103]
	v_mul_f32_e32 v130, 0xbfb8aa3b, v130
	v_mul_f32_e32 v138, 0xbfb8aa3b, v138
	v_mul_f32_e32 v139, 0xbfb8aa3b, v139
	v_exp_f32_e32 v138, v138
	v_exp_f32_e32 v139, v139
	v_mul_f32_e32 v131, 0xbfb8aa3b, v131
	v_exp_f32_e32 v130, v130
	v_exp_f32_e32 v131, v131
	v_add_f32_e32 v138, 1.0, v138
	v_add_f32_e32 v139, 1.0, v139
	v_rcp_f32_e32 v138, v138
	v_rcp_f32_e32 v139, v139
	v_add_f32_e32 v130, 1.0, v130
	v_add_f32_e32 v131, 1.0, v131
	v_rcp_f32_e32 v130, v130
	v_rcp_f32_e32 v131, v131
	v_pk_add_f32 v[142:143], v[142:143], v[106:107]
	v_lshlrev_b32_e32 v180, 16, v150
	v_and_b32_e32 v181, 0xffff0000, v150
	v_pk_fma_f32 v[138:139], v[142:143], v[138:139], v[180:181]
	v_lshlrev_b32_e32 v142, 16, v151
	v_and_b32_e32 v143, 0xffff0000, v151
	v_pk_add_f32 v[132:133], v[132:133], v[86:87]
	v_lshlrev_b32_e32 v150, 16, v152
	v_and_b32_e32 v151, 0xffff0000, v152
	v_pk_add_f32 v[140:141], v[140:141], v[104:105]
	v_pk_fma_f32 v[134:135], v[134:135], v[130:131], v[150:151]
	v_mul_f32_e32 v130, 0xbfb8aa3b, v132
	v_mul_f32_e32 v131, 0xbfb8aa3b, v133
	v_mul_f32_e32 v140, 0xbfb8aa3b, v140
	v_mul_f32_e32 v141, 0xbfb8aa3b, v141
	v_exp_f32_e32 v130, v130
	v_exp_f32_e32 v131, v131
	v_exp_f32_e32 v140, v140
	v_exp_f32_e32 v141, v141
	v_add_f32_e32 v130, 1.0, v130
	v_add_f32_e32 v131, 1.0, v131
	v_add_f32_e32 v140, 1.0, v140
	v_add_f32_e32 v141, 1.0, v141
	v_rcp_f32_e32 v130, v130
	v_rcp_f32_e32 v131, v131
	v_rcp_f32_e32 v140, v140
	v_rcp_f32_e32 v141, v141
	v_pk_add_f32 v[136:137], v[136:137], v[90:91]
	v_lshlrev_b32_e32 v132, 16, v153
	v_and_b32_e32 v133, 0xffff0000, v153
	v_pk_add_f32 v[144:145], v[144:145], v[108:109]
	v_pk_fma_f32 v[136:137], v[136:137], v[130:131], v[132:133]
	v_pk_fma_f32 v[140:141], v[144:145], v[140:141], v[142:143]
	v_pk_mul_f32 v[130:131], v[134:135], v[134:135]
	v_pk_mul_f32 v[132:133], v[136:137], v[136:137]
	v_pk_mul_f32 v[142:143], v[138:139], v[138:139]
	v_pk_mul_f32 v[144:145], v[140:141], v[140:141]
	v_add_f32_e32 v132, v132, v133
	v_add_f32_e32 v130, v130, v131
	v_add_f32_e32 v130, v130, v132
	v_add_f32_e32 v131, v144, v145
	v_add_f32_e32 v132, v142, v143
	v_add_f32_e32 v131, v132, v131
	v_add_f32_e32 v142, v131, v130
	v_cvt_pk_bf16_f32 v130, v138, v139
	v_cvt_pk_bf16_f32 v131, v140, v141
	v_cvt_pk_bf16_f32 v132, v134, v135
	v_cvt_pk_bf16_f32 v133, v136, v137
	global_store_dwordx4 v[172:173], v[130:133], off sc0 sc1
	ds_bpermute_b32 v130, v178, v142
	s_waitcnt lgkmcnt(0)
	v_add_f32_e32 v130, v142, v130
	ds_bpermute_b32 v131, v179, v130
	s_and_saveexec_b64 s[16:17], s[4:5]
	s_cbranch_execz .LBB0_268
	v_lshlrev_b64 v[132:133], 8, v[166:167]
	v_lshl_add_u64 v[132:133], s[14:15], 0, v[132:133]
	v_lshl_add_u64 v[132:133], s[52:53], 2, v[132:133]
	s_lshl_b32 s18, s37, 2
	v_lshl_add_u64 v[132:133], v[132:133], 0, s[18:19]
	s_waitcnt lgkmcnt(0)
	v_add_f32_e32 v130, v130, v131
	global_store_dword v[132:133], v130, off
; __device__ __forceinline__ unsigned pk2(float lo, float hi) { f32x2 v = {lo, hi}; bf16x2_t b = __builtin_convertvector(v, bf16x2_t); return __builtin_bit_cast(unsigned, b); }
; __device__ __forceinline__ float bflo(unsigned w) { return __uint_as_float(w << 16); }
; __device__ __forceinline__ float bfhi(unsigned w) { return __uint_as_float(w & 0xffff0000u); }
; __device__ __forceinline__ float fast_sigmoid(float g) { return __builtin_amdgcn_rcpf(1.0f + __expf(-g)); }
;     __device__ __forceinline__ void operator()(const f32x4 (&acc)[2][2][4][2], const Unit& u, int wr, int wc, int fr, int fq) const {
;     ...
;         for (int j = 0; j < 8; ++j) { const int ai = j >> 2, m = j & 3; const int row = row0 + ai * HALF + m * 16; const size_t off = (size_t)row * DM + col0; float ss = 0.f; f32x4 o[2];
;             if (j < 7) nxt = *(const u32x4*)(xb + (size_t)(row0 + ((j + 1) >> 2) * HALF + ((j + 1) & 3) * 16) * DM + col0);
; #pragma unroll
;             for (int n = 0; n < 2; ++n) {
;                 const f32x4 v = acc[ai][0][m][n] + (n ? bv1 : bv0), g = acc[ai][1][m][n] + (n ? bg1 : bg0);
;                 const unsigned w0 = n ? cur.z : cur.x, w1 = n ? cur.w : cur.y; o[n] = (f32x4){bflo(w0), bfhi(w0), bflo(w1), bfhi(w1)};
;                 o[n][0] += v[0] * fast_sigmoid(g[0]); o[n][1] += v[1] * fast_sigmoid(g[1]); o[n][2] += v[2] * fast_sigmoid(g[2]); o[n][3] += v[3] * fast_sigmoid(g[3]);
;                 ss += (o[n][0] * o[n][0] + o[n][1] * o[n][1]) + (o[n][2] * o[n][2] + o[n][3] * o[n][3]); }
;             { u32x4 w; w.x = pk2(o[0][0], o[0][1]); w.y = pk2(o[0][2], o[0][3]); w.z = pk2(o[1][0], o[1][1]); w.w = pk2(o[1][2], o[1][3]); *(u32x4*)(xb + off) = w; }
;             ss += __shfl_xor(ss, 16); ss += __shfl_xor(ss, 32); if (fq == 0) rsq[(size_t)row * 64 + u.pn * 4 + wc] = ss;
;             cur = nxt;
;             asm volatile("" ::: "memory"); }
.LBB0_268:
	s_or_b64 exec, exec, s[16:17]
	v_or_b32_e32 v134, 32, v166
	v_ashrrev_i32_e32 v135, 31, v134
	s_waitcnt lgkmcnt(0)
	v_lshlrev_b64 v[130:131], 12, v[134:135]
	v_lshl_add_u64 v[130:131], s[12:13], 0, v[130:131]
	v_lshl_add_u64 v[136:137], v[164:165], 1, v[130:131]
	global_load_dwordx4 v[130:133], v[136:137], off
	v_pk_add_f32 v[122:123], v[122:123], v[102:103]
	v_pk_add_f32 v[114:115], v[114:115], v[84:85]
	v_mul_f32_e32 v122, 0xbfb8aa3b, v122
	v_exp_f32_e32 v138, v122
	v_mul_f32_e32 v122, 0xbfb8aa3b, v123
	v_exp_f32_e32 v139, v122
	v_pk_add_f32 v[122:123], v[124:125], v[104:105]
	v_add_f32_e32 v124, 1.0, v138
	v_rcp_f32_e32 v124, v124
	v_add_f32_e32 v125, 1.0, v139
	v_rcp_f32_e32 v125, v125
	v_pk_add_f32 v[126:127], v[126:127], v[106:107]
	v_lshlrev_b32_e32 v138, 16, v146
	v_and_b32_e32 v139, 0xffff0000, v146
	v_mul_f32_e32 v114, 0xbfb8aa3b, v114
	v_pk_fma_f32 v[124:125], v[126:127], v[124:125], v[138:139]
	v_exp_f32_e32 v138, v114
	v_mul_f32_e32 v114, 0xbfb8aa3b, v115
	v_exp_f32_e32 v139, v114
	v_pk_add_f32 v[114:115], v[116:117], v[86:87]
	v_mul_f32_e32 v122, 0xbfb8aa3b, v122
	v_mul_f32_e32 v114, 0xbfb8aa3b, v114
	v_mul_f32_e32 v115, 0xbfb8aa3b, v115
	v_mul_f32_e32 v123, 0xbfb8aa3b, v123
	v_exp_f32_e32 v114, v114
	v_exp_f32_e32 v115, v115
	v_exp_f32_e32 v122, v122
	v_exp_f32_e32 v123, v123
	v_add_f32_e32 v116, 1.0, v138
	v_add_f32_e32 v117, 1.0, v139
	v_rcp_f32_e32 v116, v116
	v_rcp_f32_e32 v117, v117
	v_add_f32_e32 v114, 1.0, v114
	v_add_f32_e32 v115, 1.0, v115
	v_add_f32_e32 v122, 1.0, v122
	v_add_f32_e32 v123, 1.0, v123
	v_rcp_f32_e32 v114, v114
	v_rcp_f32_e32 v115, v115
	v_rcp_f32_e32 v122, v122
	v_rcp_f32_e32 v123, v123
	v_pk_add_f32 v[118:119], v[118:119], v[88:89]
	v_lshlrev_b32_e32 v138, 16, v148
	v_and_b32_e32 v139, 0xffff0000, v148
	v_pk_add_f32 v[120:121], v[120:121], v[90:91]
	v_pk_fma_f32 v[118:119], v[118:119], v[116:117], v[138:139]
	v_lshlrev_b32_e32 v116, 16, v149
	v_and_b32_e32 v117, 0xffff0000, v149
	v_pk_add_f32 v[128:129], v[128:129], v[108:109]
	v_lshlrev_b32_e32 v126, 16, v147
	v_and_b32_e32 v127, 0xffff0000, v147
	v_pk_fma_f32 v[120:121], v[120:121], v[114:115], v[116:117]
	v_pk_fma_f32 v[122:123], v[128:129], v[122:123], v[126:127]
	v_pk_mul_f32 v[114:115], v[118:119], v[118:119]
	v_pk_mul_f32 v[116:117], v[120:121], v[120:121]
	v_pk_mul_f32 v[126:127], v[124:125], v[124:125]
	v_pk_mul_f32 v[128:129], v[122:123], v[122:123]
	v_add_f32_e32 v116, v116, v117
	v_add_f32_e32 v114, v114, v115
	v_add_f32_e32 v114, v114, v116
	v_add_f32_e32 v115, v128, v129
	v_add_f32_e32 v116, v126, v127
	v_add_f32_e32 v115, v116, v115
	v_add_f32_e32 v114, v115, v114
	ds_bpermute_b32 v115, v178, v114
	v_cvt_pk_bf16_f32 v116, v124, v125
	v_cvt_pk_bf16_f32 v117, v122, v123
	v_cvt_pk_bf16_f32 v118, v118, v119
	v_cvt_pk_bf16_f32 v119, v120, v121
	s_waitcnt lgkmcnt(0)
	v_add_f32_e32 v114, v114, v115
	ds_bpermute_b32 v115, v179, v114
	global_store_dwordx4 v[170:171], v[116:119], off sc0 sc1
	s_and_saveexec_b64 s[16:17], s[4:5]
	s_cbranch_execz .LBB0_270
	v_lshlrev_b64 v[116:117], 8, v[168:169]
	v_lshl_add_u64 v[116:117], s[14:15], 0, v[116:117]
	v_lshl_add_u64 v[116:117], s[52:53], 2, v[116:117]
	s_lshl_b32 s18, s37, 2
	v_lshl_add_u64 v[116:117], v[116:117], 0, s[18:19]
	s_waitcnt lgkmcnt(0)
	v_add_f32_e32 v114, v114, v115
	global_store_dword v[116:117], v114, off
.LBB0_270:
	s_or_b64 exec, exec, s[16:17]
	v_or_b32_e32 v118, 48, v166
	v_ashrrev_i32_e32 v119, 31, v118
	s_waitcnt lgkmcnt(0)
	v_lshlrev_b64 v[114:115], 12, v[118:119]
	v_lshl_add_u64 v[114:115], s[12:13], 0, v[114:115]
	v_lshl_add_u64 v[120:121], v[164:165], 1, v[114:115]
	global_load_dwordx4 v[114:117], v[120:121], off
	v_pk_add_f32 v[98:99], v[98:99], v[102:103]
	v_pk_add_f32 v[80:81], v[80:81], v[84:85]
	v_mul_f32_e32 v98, 0xbfb8aa3b, v98
	v_exp_f32_e32 v122, v98
	v_mul_f32_e32 v98, 0xbfb8aa3b, v99
	v_exp_f32_e32 v123, v98
	v_pk_add_f32 v[98:99], v[100:101], v[104:105]
	v_add_f32_e32 v100, 1.0, v122
	v_rcp_f32_e32 v100, v100
	v_add_f32_e32 v101, 1.0, v123
	v_rcp_f32_e32 v101, v101
	v_pk_add_f32 v[110:111], v[110:111], v[106:107]
	s_waitcnt vmcnt(2)
	v_lshlrev_b32_e32 v122, 16, v130
	v_and_b32_e32 v123, 0xffff0000, v130
	v_mul_f32_e32 v80, 0xbfb8aa3b, v80
	v_pk_fma_f32 v[100:101], v[110:111], v[100:101], v[122:123]
	v_exp_f32_e32 v122, v80
	v_mul_f32_e32 v80, 0xbfb8aa3b, v81
	v_exp_f32_e32 v123, v80
	v_pk_add_f32 v[80:81], v[82:83], v[86:87]
	v_mul_f32_e32 v98, 0xbfb8aa3b, v98
	v_mul_f32_e32 v80, 0xbfb8aa3b, v80
	v_mul_f32_e32 v81, 0xbfb8aa3b, v81
	v_mul_f32_e32 v99, 0xbfb8aa3b, v99
	v_exp_f32_e32 v80, v80
	v_exp_f32_e32 v81, v81
	v_exp_f32_e32 v98, v98
	v_exp_f32_e32 v99, v99
	v_add_f32_e32 v82, 1.0, v122
	v_add_f32_e32 v83, 1.0, v123
	v_rcp_f32_e32 v82, v82
	v_rcp_f32_e32 v83, v83
	v_add_f32_e32 v80, 1.0, v80
	v_add_f32_e32 v81, 1.0, v81
	v_add_f32_e32 v98, 1.0, v98
	v_add_f32_e32 v99, 1.0, v99
	v_rcp_f32_e32 v80, v80
	v_rcp_f32_e32 v81, v81
	v_rcp_f32_e32 v98, v98
	v_rcp_f32_e32 v99, v99
	v_pk_add_f32 v[92:93], v[92:93], v[88:89]
	v_lshlrev_b32_e32 v122, 16, v132
	v_and_b32_e32 v123, 0xffff0000, v132
	v_pk_add_f32 v[94:95], v[94:95], v[90:91]
	v_pk_fma_f32 v[82:83], v[92:93], v[82:83], v[122:123]
	v_lshlrev_b32_e32 v92, 16, v133
	v_and_b32_e32 v93, 0xffff0000, v133
	v_pk_add_f32 v[112:113], v[112:113], v[108:109]
	v_lshlrev_b32_e32 v110, 16, v131
	v_and_b32_e32 v111, 0xffff0000, v131
	v_pk_fma_f32 v[122:123], v[94:95], v[80:81], v[92:93]
	v_pk_fma_f32 v[98:99], v[112:113], v[98:99], v[110:111]
	v_pk_mul_f32 v[80:81], v[82:83], v[82:83]
	v_pk_mul_f32 v[92:93], v[122:123], v[122:123]
	v_pk_mul_f32 v[110:111], v[100:101], v[100:101]
	v_pk_mul_f32 v[112:113], v[98:99], v[98:99]
	v_add_f32_e32 v92, v92, v93
	v_add_f32_e32 v80, v80, v81
	v_add_f32_e32 v80, v80, v92
	v_add_f32_e32 v81, v112, v113
	v_add_f32_e32 v92, v110, v111
	v_add_f32_e32 v81, v92, v81
	v_add_f32_e32 v80, v81, v80
	ds_bpermute_b32 v81, v178, v80
	v_cvt_pk_bf16_f32 v92, v100, v101
	v_cvt_pk_bf16_f32 v93, v98, v99
	v_cvt_pk_bf16_f32 v94, v82, v83
	v_cvt_pk_bf16_f32 v95, v122, v123
	s_waitcnt lgkmcnt(0)
	v_add_f32_e32 v80, v80, v81
	ds_bpermute_b32 v81, v179, v80
	global_store_dwordx4 v[136:137], v[92:95], off sc0 sc1
	s_and_saveexec_b64 s[16:17], s[4:5]
	s_cbranch_execz .LBB0_272
	v_lshlrev_b64 v[82:83], 8, v[134:135]
	v_lshl_add_u64 v[82:83], s[14:15], 0, v[82:83]
	v_lshl_add_u64 v[82:83], s[52:53], 2, v[82:83]
	s_lshl_b32 s18, s37, 2
	v_lshl_add_u64 v[82:83], v[82:83], 0, s[18:19]
	s_waitcnt lgkmcnt(0)
	v_add_f32_e32 v80, v80, v81
	global_store_dword v[82:83], v80, off
; __device__ __forceinline__ unsigned pk2(float lo, float hi) { f32x2 v = {lo, hi}; bf16x2_t b = __builtin_convertvector(v, bf16x2_t); return __builtin_bit_cast(unsigned, b); }
; __device__ __forceinline__ float bflo(unsigned w) { return __uint_as_float(w << 16); }
; __device__ __forceinline__ float bfhi(unsigned w) { return __uint_as_float(w & 0xffff0000u); }
; __device__ __forceinline__ float fast_sigmoid(float g) { return __builtin_amdgcn_rcpf(1.0f + __expf(-g)); }
;     __device__ __forceinline__ void operator()(const f32x4 (&acc)[2][2][4][2], const Unit& u, int wr, int wc, int fr, int fq) const {
;     ...
;         for (int j = 0; j < 8; ++j) { const int ai = j >> 2, m = j & 3; const int row = row0 + ai * HALF + m * 16; const size_t off = (size_t)row * DM + col0; float ss = 0.f; f32x4 o[2];
;             if (j < 7) nxt = *(const u32x4*)(xb + (size_t)(row0 + ((j + 1) >> 2) * HALF + ((j + 1) & 3) * 16) * DM + col0);
; #pragma unroll
;             for (int n = 0; n < 2; ++n) {
;                 const f32x4 v = acc[ai][0][m][n] + (n ? bv1 : bv0), g = acc[ai][1][m][n] + (n ? bg1 : bg0);
;                 const unsigned w0 = n ? cur.z : cur.x, w1 = n ? cur.w : cur.y; o[n] = (f32x4){bflo(w0), bfhi(w0), bflo(w1), bfhi(w1)};
;                 o[n][0] += v[0] * fast_sigmoid(g[0]); o[n][1] += v[1] * fast_sigmoid(g[1]); o[n][2] += v[2] * fast_sigmoid(g[2]); o[n][3] += v[3] * fast_sigmoid(g[3]);
;                 ss += (o[n][0] * o[n][0] + o[n][1] * o[n][1]) + (o[n][2] * o[n][2] + o[n][3] * o[n][3]); }
;             { u32x4 w; w.x = pk2(o[0][0], o[0][1]); w.y = pk2(o[0][2], o[0][3]); w.z = pk2(o[1][0], o[1][1]); w.w = pk2(o[1][2], o[1][3]); *(u32x4*)(xb + off) = w; }
;             ss += __shfl_xor(ss, 16); ss += __shfl_xor(ss, 32); if (fq == 0) rsq[(size_t)row * 64 + u.pn * 4 + wc] = ss;
;             cur = nxt;
;             asm volatile("" ::: "memory"); }
.LBB0_272:
	s_or_b64 exec, exec, s[16:17]
	v_add_u32_e32 v92, 0x80, v166
	v_ashrrev_i32_e32 v93, 31, v92
	s_waitcnt lgkmcnt(0)
	v_lshlrev_b64 v[80:81], 12, v[92:93]
	v_lshl_add_u64 v[80:81], s[12:13], 0, v[80:81]
	v_lshl_add_u64 v[94:95], v[164:165], 1, v[80:81]
	global_load_dwordx4 v[80:83], v[94:95], off
	v_pk_add_f32 v[72:73], v[72:73], v[102:103]
	v_pk_add_f32 v[64:65], v[64:65], v[84:85]
	v_mul_f32_e32 v72, 0xbfb8aa3b, v72
	v_exp_f32_e32 v98, v72
	v_mul_f32_e32 v72, 0xbfb8aa3b, v73
	v_exp_f32_e32 v99, v72
	v_pk_add_f32 v[72:73], v[74:75], v[104:105]
	v_add_f32_e32 v74, 1.0, v98
	v_rcp_f32_e32 v74, v74
	v_add_f32_e32 v75, 1.0, v99
	v_rcp_f32_e32 v75, v75
	v_pk_add_f32 v[76:77], v[76:77], v[106:107]
	s_waitcnt vmcnt(2)
	v_lshlrev_b32_e32 v98, 16, v114
	v_and_b32_e32 v99, 0xffff0000, v114
	v_mul_f32_e32 v64, 0xbfb8aa3b, v64
	v_pk_fma_f32 v[74:75], v[76:77], v[74:75], v[98:99]
	v_exp_f32_e32 v98, v64
	v_mul_f32_e32 v64, 0xbfb8aa3b, v65
	v_exp_f32_e32 v99, v64
	v_pk_add_f32 v[64:65], v[66:67], v[86:87]
	v_mul_f32_e32 v72, 0xbfb8aa3b, v72
	v_mul_f32_e32 v64, 0xbfb8aa3b, v64
	v_mul_f32_e32 v65, 0xbfb8aa3b, v65
	v_mul_f32_e32 v73, 0xbfb8aa3b, v73
	v_exp_f32_e32 v64, v64
	v_exp_f32_e32 v65, v65
	v_exp_f32_e32 v72, v72
	v_exp_f32_e32 v73, v73
	v_add_f32_e32 v66, 1.0, v98
	v_add_f32_e32 v67, 1.0, v99
	v_rcp_f32_e32 v66, v66
	v_rcp_f32_e32 v67, v67
	v_add_f32_e32 v64, 1.0, v64
	v_add_f32_e32 v65, 1.0, v65
	v_add_f32_e32 v72, 1.0, v72
	v_add_f32_e32 v73, 1.0, v73
	v_rcp_f32_e32 v64, v64
	v_rcp_f32_e32 v65, v65
	v_rcp_f32_e32 v72, v72
	v_rcp_f32_e32 v73, v73
	v_pk_add_f32 v[68:69], v[68:69], v[88:89]
	v_lshlrev_b32_e32 v98, 16, v116
	v_and_b32_e32 v99, 0xffff0000, v116
	v_pk_add_f32 v[70:71], v[70:71], v[90:91]
	v_pk_fma_f32 v[68:69], v[68:69], v[66:67], v[98:99]
	v_lshlrev_b32_e32 v66, 16, v117
	v_and_b32_e32 v67, 0xffff0000, v117
	v_pk_add_f32 v[78:79], v[78:79], v[108:109]
	v_lshlrev_b32_e32 v76, 16, v115
	v_and_b32_e32 v77, 0xffff0000, v115
	v_pk_fma_f32 v[70:71], v[70:71], v[64:65], v[66:67]
	v_pk_fma_f32 v[72:73], v[78:79], v[72:73], v[76:77]
	v_pk_mul_f32 v[64:65], v[68:69], v[68:69]
	v_pk_mul_f32 v[66:67], v[70:71], v[70:71]
	v_pk_mul_f32 v[76:77], v[74:75], v[74:75]
	v_pk_mul_f32 v[78:79], v[72:73], v[72:73]
	v_add_f32_e32 v66, v66, v67
	v_add_f32_e32 v64, v64, v65
	v_add_f32_e32 v64, v64, v66
	v_add_f32_e32 v65, v78, v79
	v_add_f32_e32 v66, v76, v77
	v_add_f32_e32 v65, v66, v65
	v_add_f32_e32 v64, v65, v64
	ds_bpermute_b32 v65, v178, v64
	v_cvt_pk_bf16_f32 v66, v74, v75
	v_cvt_pk_bf16_f32 v67, v72, v73
	v_cvt_pk_bf16_f32 v68, v68, v69
	v_cvt_pk_bf16_f32 v69, v70, v71
	s_waitcnt lgkmcnt(0)
	v_add_f32_e32 v64, v64, v65
	ds_bpermute_b32 v65, v179, v64
	global_store_dwordx4 v[120:121], v[66:69], off sc0 sc1
	s_and_saveexec_b64 s[16:17], s[4:5]
	s_cbranch_execz .LBB0_274
	v_lshlrev_b64 v[66:67], 8, v[118:119]
	v_lshl_add_u64 v[66:67], s[14:15], 0, v[66:67]
	v_lshl_add_u64 v[66:67], s[52:53], 2, v[66:67]
	s_lshl_b32 s18, s37, 2
	v_lshl_add_u64 v[66:67], v[66:67], 0, s[18:19]
	s_waitcnt lgkmcnt(0)
	v_add_f32_e32 v64, v64, v65
	global_store_dword v[66:67], v64, off
.LBB0_274:
	s_or_b64 exec, exec, s[16:17]
	v_or_b32_e32 v68, 16, v92
	v_ashrrev_i32_e32 v69, 31, v68
	s_waitcnt lgkmcnt(0)
	v_lshlrev_b64 v[64:65], 12, v[68:69]
	v_lshl_add_u64 v[64:65], s[12:13], 0, v[64:65]
	v_lshl_add_u64 v[70:71], v[164:165], 1, v[64:65]
	global_load_dwordx4 v[64:67], v[70:71], off
	v_pk_add_f32 v[56:57], v[56:57], v[102:103]
	v_pk_add_f32 v[48:49], v[48:49], v[84:85]
	v_mul_f32_e32 v56, 0xbfb8aa3b, v56
	v_exp_f32_e32 v72, v56
	v_mul_f32_e32 v56, 0xbfb8aa3b, v57
	v_exp_f32_e32 v73, v56
	v_pk_add_f32 v[56:57], v[58:59], v[104:105]
	v_add_f32_e32 v58, 1.0, v72
	v_rcp_f32_e32 v58, v58
	v_add_f32_e32 v59, 1.0, v73
	v_rcp_f32_e32 v59, v59
	v_pk_add_f32 v[60:61], v[60:61], v[106:107]
	s_waitcnt vmcnt(2)
	v_lshlrev_b32_e32 v72, 16, v80
	v_and_b32_e32 v73, 0xffff0000, v80
	v_mul_f32_e32 v48, 0xbfb8aa3b, v48
	v_pk_fma_f32 v[58:59], v[60:61], v[58:59], v[72:73]
	v_exp_f32_e32 v72, v48
	v_mul_f32_e32 v48, 0xbfb8aa3b, v49
	v_exp_f32_e32 v73, v48
	v_pk_add_f32 v[48:49], v[50:51], v[86:87]
	v_mul_f32_e32 v56, 0xbfb8aa3b, v56
	v_mul_f32_e32 v48, 0xbfb8aa3b, v48
	v_mul_f32_e32 v49, 0xbfb8aa3b, v49
	v_mul_f32_e32 v57, 0xbfb8aa3b, v57
	v_exp_f32_e32 v48, v48
	v_exp_f32_e32 v49, v49
	v_exp_f32_e32 v56, v56
	v_exp_f32_e32 v57, v57
	v_add_f32_e32 v50, 1.0, v72
	v_add_f32_e32 v51, 1.0, v73
	v_rcp_f32_e32 v50, v50
	v_rcp_f32_e32 v51, v51
	v_add_f32_e32 v48, 1.0, v48
	v_add_f32_e32 v49, 1.0, v49
	v_add_f32_e32 v56, 1.0, v56
	v_add_f32_e32 v57, 1.0, v57
	v_rcp_f32_e32 v48, v48
	v_rcp_f32_e32 v49, v49
	v_rcp_f32_e32 v56, v56
	v_rcp_f32_e32 v57, v57
	v_pk_add_f32 v[52:53], v[52:53], v[88:89]
	v_lshlrev_b32_e32 v72, 16, v82
	v_and_b32_e32 v73, 0xffff0000, v82
	v_pk_add_f32 v[54:55], v[54:55], v[90:91]
	v_pk_fma_f32 v[52:53], v[52:53], v[50:51], v[72:73]
	v_lshlrev_b32_e32 v50, 16, v83
	v_and_b32_e32 v51, 0xffff0000, v83
	v_pk_add_f32 v[62:63], v[62:63], v[108:109]
	v_lshlrev_b32_e32 v60, 16, v81
	v_and_b32_e32 v61, 0xffff0000, v81
	v_pk_fma_f32 v[54:55], v[54:55], v[48:49], v[50:51]
	v_pk_fma_f32 v[56:57], v[62:63], v[56:57], v[60:61]
	v_pk_mul_f32 v[48:49], v[52:53], v[52:53]
	v_pk_mul_f32 v[50:51], v[54:55], v[54:55]
	v_pk_mul_f32 v[60:61], v[58:59], v[58:59]
	v_pk_mul_f32 v[62:63], v[56:57], v[56:57]
	v_add_f32_e32 v50, v50, v51
	v_add_f32_e32 v48, v48, v49
	v_add_f32_e32 v48, v48, v50
	v_add_f32_e32 v49, v62, v63
	v_add_f32_e32 v50, v60, v61
	v_add_f32_e32 v49, v50, v49
	v_add_f32_e32 v48, v49, v48
	ds_bpermute_b32 v49, v178, v48
	v_cvt_pk_bf16_f32 v50, v58, v59
	v_cvt_pk_bf16_f32 v51, v56, v57
	v_cvt_pk_bf16_f32 v52, v52, v53
	v_cvt_pk_bf16_f32 v53, v54, v55
	s_waitcnt lgkmcnt(0)
	v_add_f32_e32 v48, v48, v49
	ds_bpermute_b32 v49, v179, v48
	global_store_dwordx4 v[94:95], v[50:53], off sc0 sc1
	s_and_saveexec_b64 s[16:17], s[4:5]
	s_cbranch_execz .LBB0_276
	v_lshlrev_b64 v[50:51], 8, v[92:93]
	v_lshl_add_u64 v[50:51], s[14:15], 0, v[50:51]
	v_lshl_add_u64 v[50:51], s[52:53], 2, v[50:51]
	s_lshl_b32 s18, s37, 2
	v_lshl_add_u64 v[50:51], v[50:51], 0, s[18:19]
	s_waitcnt lgkmcnt(0)
	v_add_f32_e32 v48, v48, v49
	global_store_dword v[50:51], v48, off
; __device__ __forceinline__ unsigned pk2(float lo, float hi) { f32x2 v = {lo, hi}; bf16x2_t b = __builtin_convertvector(v, bf16x2_t); return __builtin_bit_cast(unsigned, b); }
; __device__ __forceinline__ float bflo(unsigned w) { return __uint_as_float(w << 16); }
; __device__ __forceinline__ float bfhi(unsigned w) { return __uint_as_float(w & 0xffff0000u); }
; __device__ __forceinline__ float fast_sigmoid(float g) { return __builtin_amdgcn_rcpf(1.0f + __expf(-g)); }
;     __device__ __forceinline__ void operator()(const f32x4 (&acc)[2][2][4][2], const Unit& u, int wr, int wc, int fr, int fq) const {
;     ...
;         for (int j = 0; j < 8; ++j) { const int ai = j >> 2, m = j & 3; const int row = row0 + ai * HALF + m * 16; const size_t off = (size_t)row * DM + col0; float ss = 0.f; f32x4 o[2];
;             if (j < 7) nxt = *(const u32x4*)(xb + (size_t)(row0 + ((j + 1) >> 2) * HALF + ((j + 1) & 3) * 16) * DM + col0);
; #pragma unroll
;             for (int n = 0; n < 2; ++n) {
;                 const f32x4 v = acc[ai][0][m][n] + (n ? bv1 : bv0), g = acc[ai][1][m][n] + (n ? bg1 : bg0);
;                 const unsigned w0 = n ? cur.z : cur.x, w1 = n ? cur.w : cur.y; o[n] = (f32x4){bflo(w0), bfhi(w0), bflo(w1), bfhi(w1)};
;                 o[n][0] += v[0] * fast_sigmoid(g[0]); o[n][1] += v[1] * fast_sigmoid(g[1]); o[n][2] += v[2] * fast_sigmoid(g[2]); o[n][3] += v[3] * fast_sigmoid(g[3]);
;                 ss += (o[n][0] * o[n][0] + o[n][1] * o[n][1]) + (o[n][2] * o[n][2] + o[n][3] * o[n][3]); }
;             { u32x4 w; w.x = pk2(o[0][0], o[0][1]); w.y = pk2(o[0][2], o[0][3]); w.z = pk2(o[1][0], o[1][1]); w.w = pk2(o[1][2], o[1][3]); *(u32x4*)(xb + off) = w; }
;             ss += __shfl_xor(ss, 16); ss += __shfl_xor(ss, 32); if (fq == 0) rsq[(size_t)row * 64 + u.pn * 4 + wc] = ss;
;             cur = nxt;
;             asm volatile("" ::: "memory"); }
.LBB0_276:
	s_or_b64 exec, exec, s[16:17]
	v_or_b32_e32 v52, 32, v92
	v_ashrrev_i32_e32 v53, 31, v52
	s_waitcnt lgkmcnt(0)
	v_lshlrev_b64 v[48:49], 12, v[52:53]
	v_lshl_add_u64 v[48:49], s[12:13], 0, v[48:49]
	v_lshl_add_u64 v[54:55], v[164:165], 1, v[48:49]
	global_load_dwordx4 v[48:51], v[54:55], off
	v_pk_add_f32 v[40:41], v[40:41], v[102:103]
	v_pk_add_f32 v[32:33], v[32:33], v[84:85]
	v_mul_f32_e32 v40, 0xbfb8aa3b, v40
	v_exp_f32_e32 v56, v40
	v_mul_f32_e32 v40, 0xbfb8aa3b, v41
	v_exp_f32_e32 v57, v40
	v_pk_add_f32 v[40:41], v[42:43], v[104:105]
	v_add_f32_e32 v42, 1.0, v56
	v_rcp_f32_e32 v42, v42
	v_add_f32_e32 v43, 1.0, v57
	v_rcp_f32_e32 v43, v43
	v_pk_add_f32 v[44:45], v[44:45], v[106:107]
	s_waitcnt vmcnt(2)
	v_lshlrev_b32_e32 v56, 16, v64
	v_and_b32_e32 v57, 0xffff0000, v64
	v_mul_f32_e32 v32, 0xbfb8aa3b, v32
	v_pk_fma_f32 v[42:43], v[44:45], v[42:43], v[56:57]
	v_exp_f32_e32 v56, v32
	v_mul_f32_e32 v32, 0xbfb8aa3b, v33
	v_exp_f32_e32 v57, v32
	v_pk_add_f32 v[32:33], v[34:35], v[86:87]
	v_mul_f32_e32 v40, 0xbfb8aa3b, v40
	v_mul_f32_e32 v32, 0xbfb8aa3b, v32
	v_mul_f32_e32 v33, 0xbfb8aa3b, v33
	v_mul_f32_e32 v41, 0xbfb8aa3b, v41
	v_exp_f32_e32 v32, v32
	v_exp_f32_e32 v33, v33
	v_exp_f32_e32 v40, v40
	v_exp_f32_e32 v41, v41
	v_add_f32_e32 v34, 1.0, v56
	v_add_f32_e32 v35, 1.0, v57
	v_rcp_f32_e32 v34, v34
	v_rcp_f32_e32 v35, v35
	v_add_f32_e32 v32, 1.0, v32
	v_add_f32_e32 v33, 1.0, v33
	v_add_f32_e32 v40, 1.0, v40
	v_add_f32_e32 v41, 1.0, v41
	v_rcp_f32_e32 v32, v32
	v_rcp_f32_e32 v33, v33
	v_rcp_f32_e32 v40, v40
	v_rcp_f32_e32 v41, v41
	v_pk_add_f32 v[36:37], v[36:37], v[88:89]
	v_lshlrev_b32_e32 v56, 16, v66
	v_and_b32_e32 v57, 0xffff0000, v66
	v_pk_add_f32 v[38:39], v[38:39], v[90:91]
	v_pk_fma_f32 v[36:37], v[36:37], v[34:35], v[56:57]
	v_lshlrev_b32_e32 v34, 16, v67
	v_and_b32_e32 v35, 0xffff0000, v67
	v_pk_add_f32 v[46:47], v[46:47], v[108:109]
	v_lshlrev_b32_e32 v44, 16, v65
	v_and_b32_e32 v45, 0xffff0000, v65
	v_pk_fma_f32 v[38:39], v[38:39], v[32:33], v[34:35]
	v_pk_fma_f32 v[40:41], v[46:47], v[40:41], v[44:45]
	v_pk_mul_f32 v[32:33], v[36:37], v[36:37]
	v_pk_mul_f32 v[34:35], v[38:39], v[38:39]
	v_pk_mul_f32 v[44:45], v[42:43], v[42:43]
	v_pk_mul_f32 v[46:47], v[40:41], v[40:41]
	v_add_f32_e32 v34, v34, v35
	v_add_f32_e32 v32, v32, v33
	v_add_f32_e32 v32, v32, v34
	v_add_f32_e32 v33, v46, v47
	v_add_f32_e32 v34, v44, v45
	v_add_f32_e32 v33, v34, v33
	v_add_f32_e32 v32, v33, v32
	ds_bpermute_b32 v33, v178, v32
	v_cvt_pk_bf16_f32 v34, v42, v43
	v_cvt_pk_bf16_f32 v35, v40, v41
	v_cvt_pk_bf16_f32 v36, v36, v37
	v_cvt_pk_bf16_f32 v37, v38, v39
	s_waitcnt lgkmcnt(0)
	v_add_f32_e32 v32, v32, v33
	ds_bpermute_b32 v33, v179, v32
	global_store_dwordx4 v[70:71], v[34:37], off sc0 sc1
	s_and_saveexec_b64 s[16:17], s[4:5]
	s_cbranch_execz .LBB0_278
	v_lshlrev_b64 v[34:35], 8, v[68:69]
	v_lshl_add_u64 v[34:35], s[14:15], 0, v[34:35]
	v_lshl_add_u64 v[34:35], s[52:53], 2, v[34:35]
	s_lshl_b32 s18, s37, 2
	v_lshl_add_u64 v[34:35], v[34:35], 0, s[18:19]
	s_waitcnt lgkmcnt(0)
	v_add_f32_e32 v32, v32, v33
	global_store_dword v[34:35], v32, off
; __device__ __forceinline__ unsigned pk2(float lo, float hi) { f32x2 v = {lo, hi}; bf16x2_t b = __builtin_convertvector(v, bf16x2_t); return __builtin_bit_cast(unsigned, b); }
; __device__ __forceinline__ float bflo(unsigned w) { return __uint_as_float(w << 16); }
; __device__ __forceinline__ float bfhi(unsigned w) { return __uint_as_float(w & 0xffff0000u); }
; __device__ __forceinline__ float fast_sigmoid(float g) { return __builtin_amdgcn_rcpf(1.0f + __expf(-g)); }
;     __device__ __forceinline__ void operator()(const f32x4 (&acc)[2][2][4][2], const Unit& u, int wr, int wc, int fr, int fq) const {
;     ...
;         for (int j = 0; j < 8; ++j) { const int ai = j >> 2, m = j & 3; const int row = row0 + ai * HALF + m * 16; const size_t off = (size_t)row * DM + col0; float ss = 0.f; f32x4 o[2];
;             if (j < 7) nxt = *(const u32x4*)(xb + (size_t)(row0 + ((j + 1) >> 2) * HALF + ((j + 1) & 3) * 16) * DM + col0);
; #pragma unroll
;             for (int n = 0; n < 2; ++n) {
;                 const f32x4 v = acc[ai][0][m][n] + (n ? bv1 : bv0), g = acc[ai][1][m][n] + (n ? bg1 : bg0);
;                 const unsigned w0 = n ? cur.z : cur.x, w1 = n ? cur.w : cur.y; o[n] = (f32x4){bflo(w0), bfhi(w0), bflo(w1), bfhi(w1)};
;                 o[n][0] += v[0] * fast_sigmoid(g[0]); o[n][1] += v[1] * fast_sigmoid(g[1]); o[n][2] += v[2] * fast_sigmoid(g[2]); o[n][3] += v[3] * fast_sigmoid(g[3]);
;                 ss += (o[n][0] * o[n][0] + o[n][1] * o[n][1]) + (o[n][2] * o[n][2] + o[n][3] * o[n][3]); }
;             { u32x4 w; w.x = pk2(o[0][0], o[0][1]); w.y = pk2(o[0][2], o[0][3]); w.z = pk2(o[1][0], o[1][1]); w.w = pk2(o[1][2], o[1][3]); *(u32x4*)(xb + off) = w; }
;             ss += __shfl_xor(ss, 16); ss += __shfl_xor(ss, 32); if (fq == 0) rsq[(size_t)row * 64 + u.pn * 4 + wc] = ss;
;             cur = nxt;
;             asm volatile("" ::: "memory"); }
.LBB0_278:
	s_or_b64 exec, exec, s[16:17]
	v_or_b32_e32 v36, 48, v92
	v_ashrrev_i32_e32 v37, 31, v36
	s_waitcnt lgkmcnt(0)
	v_lshlrev_b64 v[32:33], 12, v[36:37]
	v_lshl_add_u64 v[32:33], s[12:13], 0, v[32:33]
	v_lshl_add_u64 v[38:39], v[164:165], 1, v[32:33]
	global_load_dwordx4 v[32:35], v[38:39], off
	v_pk_add_f32 v[24:25], v[24:25], v[102:103]
	v_pk_add_f32 v[16:17], v[16:17], v[84:85]
	v_mul_f32_e32 v24, 0xbfb8aa3b, v24
	v_exp_f32_e32 v40, v24
	v_mul_f32_e32 v24, 0xbfb8aa3b, v25
	v_exp_f32_e32 v41, v24
	v_pk_add_f32 v[24:25], v[26:27], v[104:105]
	v_add_f32_e32 v26, 1.0, v40
	v_rcp_f32_e32 v26, v26
	v_add_f32_e32 v27, 1.0, v41
	v_rcp_f32_e32 v27, v27
	v_pk_add_f32 v[28:29], v[28:29], v[106:107]
	s_waitcnt vmcnt(2)
	v_lshlrev_b32_e32 v40, 16, v48
	v_and_b32_e32 v41, 0xffff0000, v48
	v_mul_f32_e32 v16, 0xbfb8aa3b, v16
	v_pk_fma_f32 v[26:27], v[28:29], v[26:27], v[40:41]
	v_exp_f32_e32 v40, v16
	v_mul_f32_e32 v16, 0xbfb8aa3b, v17
	v_exp_f32_e32 v41, v16
	v_pk_add_f32 v[16:17], v[18:19], v[86:87]
	v_mul_f32_e32 v24, 0xbfb8aa3b, v24
	v_mul_f32_e32 v16, 0xbfb8aa3b, v16
	v_mul_f32_e32 v17, 0xbfb8aa3b, v17
	v_mul_f32_e32 v25, 0xbfb8aa3b, v25
	v_exp_f32_e32 v16, v16
	v_exp_f32_e32 v17, v17
	v_exp_f32_e32 v24, v24
	v_exp_f32_e32 v25, v25
	v_add_f32_e32 v18, 1.0, v40
	v_add_f32_e32 v19, 1.0, v41
	v_rcp_f32_e32 v18, v18
	v_rcp_f32_e32 v19, v19
	v_add_f32_e32 v16, 1.0, v16
	v_add_f32_e32 v17, 1.0, v17
	v_add_f32_e32 v24, 1.0, v24
	v_add_f32_e32 v25, 1.0, v25
	v_rcp_f32_e32 v16, v16
	v_rcp_f32_e32 v17, v17
	v_rcp_f32_e32 v24, v24
	v_rcp_f32_e32 v25, v25
	v_pk_add_f32 v[20:21], v[20:21], v[88:89]
	v_lshlrev_b32_e32 v40, 16, v50
	v_and_b32_e32 v41, 0xffff0000, v50
	v_pk_add_f32 v[22:23], v[22:23], v[90:91]
	v_pk_fma_f32 v[20:21], v[20:21], v[18:19], v[40:41]
	v_lshlrev_b32_e32 v18, 16, v51
	v_and_b32_e32 v19, 0xffff0000, v51
	v_pk_add_f32 v[30:31], v[30:31], v[108:109]
	v_lshlrev_b32_e32 v28, 16, v49
	v_and_b32_e32 v29, 0xffff0000, v49
	v_pk_fma_f32 v[22:23], v[22:23], v[16:17], v[18:19]
	v_pk_fma_f32 v[24:25], v[30:31], v[24:25], v[28:29]
	v_pk_mul_f32 v[16:17], v[20:21], v[20:21]
	v_pk_mul_f32 v[18:19], v[22:23], v[22:23]
	v_pk_mul_f32 v[28:29], v[26:27], v[26:27]
	v_pk_mul_f32 v[30:31], v[24:25], v[24:25]
	v_add_f32_e32 v18, v18, v19
	v_add_f32_e32 v16, v16, v17
	v_add_f32_e32 v16, v16, v18
	v_add_f32_e32 v17, v30, v31
	v_add_f32_e32 v18, v28, v29
	v_add_f32_e32 v17, v18, v17
	v_add_f32_e32 v16, v17, v16
	ds_bpermute_b32 v17, v178, v16
	v_cvt_pk_bf16_f32 v18, v26, v27
	v_cvt_pk_bf16_f32 v19, v24, v25
	v_cvt_pk_bf16_f32 v20, v20, v21
	v_cvt_pk_bf16_f32 v21, v22, v23
	s_waitcnt lgkmcnt(0)
	v_add_f32_e32 v16, v16, v17
	ds_bpermute_b32 v17, v179, v16
	global_store_dwordx4 v[54:55], v[18:21], off sc0 sc1
	s_and_saveexec_b64 s[16:17], s[4:5]
	s_cbranch_execz .LBB0_280
	v_lshlrev_b64 v[18:19], 8, v[52:53]
	v_lshl_add_u64 v[18:19], s[14:15], 0, v[18:19]
	v_lshl_add_u64 v[18:19], s[52:53], 2, v[18:19]
	s_lshl_b32 s18, s37, 2
	v_lshl_add_u64 v[18:19], v[18:19], 0, s[18:19]
	s_waitcnt lgkmcnt(0)
	v_add_f32_e32 v16, v16, v17
	global_store_dword v[18:19], v16, off
.LBB0_280:
	s_or_b64 exec, exec, s[16:17]
	v_pk_add_f32 v[8:9], v[8:9], v[102:103]
	v_pk_add_f32 v[0:1], v[0:1], v[84:85]
	v_mul_f32_e32 v8, 0xbfb8aa3b, v8
	v_exp_f32_e32 v16, v8
	v_mul_f32_e32 v8, 0xbfb8aa3b, v9
	s_waitcnt lgkmcnt(0)
	v_exp_f32_e32 v17, v8
	v_pk_add_f32 v[8:9], v[10:11], v[104:105]
	v_add_f32_e32 v10, 1.0, v16
	v_rcp_f32_e32 v10, v10
	v_add_f32_e32 v11, 1.0, v17
	v_rcp_f32_e32 v11, v11
	v_pk_add_f32 v[12:13], v[12:13], v[106:107]
	s_waitcnt vmcnt(1)
	v_lshlrev_b32_e32 v16, 16, v32
	v_and_b32_e32 v17, 0xffff0000, v32
	v_mul_f32_e32 v0, 0xbfb8aa3b, v0
	v_pk_fma_f32 v[10:11], v[12:13], v[10:11], v[16:17]
	v_exp_f32_e32 v16, v0
	v_mul_f32_e32 v0, 0xbfb8aa3b, v1
	v_exp_f32_e32 v17, v0
	v_pk_add_f32 v[0:1], v[2:3], v[86:87]
	v_mul_f32_e32 v8, 0xbfb8aa3b, v8
	v_mul_f32_e32 v0, 0xbfb8aa3b, v0
	v_mul_f32_e32 v1, 0xbfb8aa3b, v1
	v_mul_f32_e32 v9, 0xbfb8aa3b, v9
	v_exp_f32_e32 v0, v0
	v_exp_f32_e32 v1, v1
	v_exp_f32_e32 v8, v8
	v_exp_f32_e32 v9, v9
	v_add_f32_e32 v2, 1.0, v16
	v_add_f32_e32 v3, 1.0, v17
	v_rcp_f32_e32 v2, v2
	v_rcp_f32_e32 v3, v3
	v_add_f32_e32 v0, 1.0, v0
	v_add_f32_e32 v1, 1.0, v1
	v_add_f32_e32 v8, 1.0, v8
	v_add_f32_e32 v9, 1.0, v9
	v_rcp_f32_e32 v0, v0
	v_rcp_f32_e32 v1, v1
	v_rcp_f32_e32 v8, v8
	v_rcp_f32_e32 v9, v9
	v_pk_add_f32 v[4:5], v[4:5], v[88:89]
	v_lshlrev_b32_e32 v16, 16, v34
	v_and_b32_e32 v17, 0xffff0000, v34
	v_pk_add_f32 v[6:7], v[6:7], v[90:91]
	v_pk_fma_f32 v[4:5], v[4:5], v[2:3], v[16:17]
	v_lshlrev_b32_e32 v2, 16, v35
	v_and_b32_e32 v3, 0xffff0000, v35
	v_pk_add_f32 v[14:15], v[14:15], v[108:109]
	v_lshlrev_b32_e32 v12, 16, v33
	v_and_b32_e32 v13, 0xffff0000, v33
	v_pk_fma_f32 v[6:7], v[6:7], v[0:1], v[2:3]
	v_pk_fma_f32 v[8:9], v[14:15], v[8:9], v[12:13]
	v_pk_mul_f32 v[0:1], v[4:5], v[4:5]
	v_pk_mul_f32 v[2:3], v[6:7], v[6:7]
	v_pk_mul_f32 v[12:13], v[10:11], v[10:11]
	v_pk_mul_f32 v[14:15], v[8:9], v[8:9]
	v_add_f32_e32 v2, v2, v3
	v_add_f32_e32 v0, v0, v1
	v_add_f32_e32 v0, v0, v2
	v_add_f32_e32 v1, v14, v15
	v_add_f32_e32 v2, v12, v13
	v_add_f32_e32 v1, v2, v1
	v_add_f32_e32 v0, v1, v0
	ds_bpermute_b32 v1, v178, v0
	v_cvt_pk_bf16_f32 v2, v10, v11
	v_cvt_pk_bf16_f32 v3, v8, v9
	v_cvt_pk_bf16_f32 v4, v4, v5
	s_waitcnt lgkmcnt(0)
	v_add_f32_e32 v0, v0, v1
	ds_bpermute_b32 v1, v179, v0
	v_cvt_pk_bf16_f32 v5, v6, v7
	global_store_dwordx4 v[38:39], v[2:5], off sc0 sc1
	s_and_saveexec_b64 s[16:17], s[4:5]
	s_cbranch_execz .LBB0_282
	v_lshlrev_b64 v[2:3], 8, v[36:37]
	v_lshl_add_u64 v[2:3], s[14:15], 0, v[2:3]
	v_lshl_add_u64 v[2:3], s[52:53], 2, v[2:3]
	s_lshl_b32 s18, s37, 2
	v_lshl_add_u64 v[2:3], v[2:3], 0, s[18:19]
	s_waitcnt lgkmcnt(0)
	v_add_f32_e32 v0, v0, v1
	global_store_dword v[2:3], v0, off

; __device__ __forceinline__ unsigned pk2(float lo, float hi) { f32x2 v = {lo, hi}; bf16x2_t b = __builtin_convertvector(v, bf16x2_t); return __builtin_bit_cast(unsigned, b); }
;     __device__ __forceinline__ void operator()(const f32x4 (&acc)[2][2][4][2], const Unit& u, int wr, int wc, int fr, int fq) const {
;     ...
; #pragma unroll
;         for (int ai = 0; ai < 2; ++ai)
; #pragma unroll
;             for (int m = 0; m < 4; ++m) { const int row = row0 + ai * HALF + m * 16; bf16_t* rowp = O + (size_t)row * ldc + col0;
;                 float rs = 1.0f; if (MODE == 1) rs = ct[wr * 64 + fr + ai * HALF + m * 16];
; #pragma unroll
;                 for (int bj = 0; bj < 2; ++bj) { f32x4 v0 = acc[ai][bj][m][0], v1 = acc[ai][bj][m][1];
;                     if (MODE == 1) { v0 = v0 * rs; v1 = v1 * rs; }
;                     if (MODE == 2) { v0 = v0 * cs[bj][0]; v1 = v1 * cs[bj][1]; }
;                     u32x4 w; w.x = pk2(v0[0], v0[1]); w.y = pk2(v0[2], v0[3]); w.z = pk2(v1[0], v1[1]); w.w = pk2(v1[2], v1[3]);
;                     *(u32x4*)(rowp + bj * HALF) = w; } }
.LBB0_370:
	ds_read2_b32 v[162:163], v157 offset1:16
	v_add_u32_e32 v160, s3, v153
	v_lshl_or_b32 v134, s44, 8, v158
	v_ashrrev_i32_e32 v161, 31, v160
	v_ashrrev_i32_e32 v135, 31, v134
	v_lshlrev_b64 v[164:165], 13, v[160:161]
	v_lshl_add_u64 v[164:165], s[14:15], 0, v[164:165]
	v_lshlrev_b64 v[166:167], 1, v[134:135]
	v_lshl_add_u64 v[134:135], v[164:165], 0, v[166:167]
	s_waitcnt lgkmcnt(0)
	v_pk_mul_f32 v[128:129], v[128:129], v[162:163] op_sel_hi:[1,0]
	v_pk_mul_f32 v[126:127], v[126:127], v[162:163] op_sel_hi:[1,0]
	v_pk_mul_f32 v[164:165], v[124:125], v[162:163] op_sel_hi:[1,0]
	v_pk_mul_f32 v[124:125], v[122:123], v[162:163] op_sel_hi:[1,0]
	v_cvt_pk_bf16_f32 v122, v126, v127
	v_cvt_pk_bf16_f32 v123, v128, v129
	v_cvt_pk_bf16_f32 v124, v124, v125
	v_cvt_pk_bf16_f32 v125, v164, v165
	global_store_dwordx4 v[134:135], v[122:125], off sc0 sc1
	v_pk_mul_f32 v[120:121], v[120:121], v[162:163] op_sel_hi:[1,0]
	v_pk_mul_f32 v[118:119], v[118:119], v[162:163] op_sel_hi:[1,0]
	v_pk_mul_f32 v[122:123], v[112:113], v[162:163] op_sel_hi:[1,0]
	v_pk_mul_f32 v[112:113], v[110:111], v[162:163] op_sel_hi:[1,0]
	v_cvt_pk_bf16_f32 v110, v118, v119
	v_cvt_pk_bf16_f32 v111, v120, v121
	v_cvt_pk_bf16_f32 v112, v112, v113
	v_cvt_pk_bf16_f32 v113, v122, v123
	global_store_dwordx4 v[134:135], v[110:113], off offset:256 sc0 sc1
	s_mov_b32 s3, 0x100000
	s_mov_b64 s[8:9], 0x100000
	v_or_b32_e32 v110, 16, v160
	v_ashrrev_i32_e32 v111, 31, v110
	v_lshlrev_b64 v[110:111], 13, v[110:111]
	v_mov_b32_e32 v112, v163
	v_lshl_add_u64 v[110:111], s[14:15], 0, v[110:111]
	v_pk_mul_f32 v[116:117], v[116:117], v[112:113] op_sel_hi:[1,0]
	v_pk_mul_f32 v[114:115], v[114:115], v[112:113] op_sel_hi:[1,0]
	v_pk_mul_f32 v[118:119], v[108:109], v[112:113] op_sel_hi:[1,0]
	v_pk_mul_f32 v[108:109], v[106:107], v[112:113] op_sel_hi:[1,0]
	v_lshl_add_u64 v[110:111], v[110:111], 0, v[166:167]
	v_cvt_pk_bf16_f32 v106, v114, v115
	v_cvt_pk_bf16_f32 v107, v116, v117
	v_cvt_pk_bf16_f32 v108, v108, v109
	v_cvt_pk_bf16_f32 v109, v118, v119
	global_store_dwordx4 v[110:111], v[106:109], off sc0 sc1
	v_pk_mul_f32 v[104:105], v[104:105], v[112:113] op_sel_hi:[1,0]
	v_pk_mul_f32 v[102:103], v[102:103], v[112:113] op_sel_hi:[1,0]
	v_pk_mul_f32 v[106:107], v[94:95], v[112:113] op_sel_hi:[1,0]
	v_pk_mul_f32 v[94:95], v[92:93], v[112:113] op_sel_hi:[1,0]
	v_cvt_pk_bf16_f32 v92, v102, v103
	v_cvt_pk_bf16_f32 v93, v104, v105
	v_cvt_pk_bf16_f32 v94, v94, v95
	v_cvt_pk_bf16_f32 v95, v106, v107
	global_store_dwordx4 v[110:111], v[92:95], off offset:256 sc0 sc1
	ds_read2_b32 v[94:95], v157 offset0:32 offset1:48
	s_waitcnt lgkmcnt(0)
	v_pk_mul_f32 v[100:101], v[100:101], v[94:95] op_sel_hi:[1,0]
	v_or_b32_e32 v92, 32, v160
	v_ashrrev_i32_e32 v93, 31, v92
	v_lshlrev_b64 v[92:93], 13, v[92:93]
	v_lshl_add_u64 v[92:93], s[14:15], 0, v[92:93]
	v_pk_mul_f32 v[98:99], v[98:99], v[94:95] op_sel_hi:[1,0]
	v_pk_mul_f32 v[102:103], v[90:91], v[94:95] op_sel_hi:[1,0]
	v_pk_mul_f32 v[90:91], v[88:89], v[94:95] op_sel_hi:[1,0]
	v_lshl_add_u64 v[92:93], v[92:93], 0, v[166:167]
	v_cvt_pk_bf16_f32 v88, v98, v99
	v_cvt_pk_bf16_f32 v89, v100, v101
	v_cvt_pk_bf16_f32 v90, v90, v91
	v_cvt_pk_bf16_f32 v91, v102, v103
	global_store_dwordx4 v[92:93], v[88:91], off sc0 sc1
	v_pk_mul_f32 v[86:87], v[86:87], v[94:95] op_sel_hi:[1,0]
	v_pk_mul_f32 v[84:85], v[84:85], v[94:95] op_sel_hi:[1,0]
	v_pk_mul_f32 v[88:89], v[78:79], v[94:95] op_sel_hi:[1,0]
	v_pk_mul_f32 v[78:79], v[76:77], v[94:95] op_sel_hi:[1,0]
	v_cvt_pk_bf16_f32 v76, v84, v85
	v_cvt_pk_bf16_f32 v77, v86, v87
	v_cvt_pk_bf16_f32 v78, v78, v79
	v_cvt_pk_bf16_f32 v79, v88, v89
	global_store_dwordx4 v[92:93], v[76:79], off offset:256 sc0 sc1
	s_nop 1
	v_or_b32_e32 v76, 48, v160
	v_ashrrev_i32_e32 v77, 31, v76
	v_lshlrev_b64 v[76:77], 13, v[76:77]
	v_mov_b32_e32 v78, v95
	v_lshl_add_u64 v[76:77], s[14:15], 0, v[76:77]
	v_pk_mul_f32 v[82:83], v[82:83], v[78:79] op_sel_hi:[1,0]
	v_pk_mul_f32 v[80:81], v[80:81], v[78:79] op_sel_hi:[1,0]
	v_pk_mul_f32 v[84:85], v[74:75], v[78:79] op_sel_hi:[1,0]
	v_pk_mul_f32 v[74:75], v[72:73], v[78:79] op_sel_hi:[1,0]
	v_lshl_add_u64 v[76:77], v[76:77], 0, v[166:167]
	v_cvt_pk_bf16_f32 v72, v80, v81
	v_cvt_pk_bf16_f32 v73, v82, v83
	v_cvt_pk_bf16_f32 v74, v74, v75
	v_cvt_pk_bf16_f32 v75, v84, v85
	v_pk_mul_f32 v[68:69], v[68:69], v[78:79] op_sel_hi:[1,0]
	global_store_dwordx4 v[76:77], v[72:75], off sc0 sc1
	v_pk_mul_f32 v[70:71], v[70:71], v[78:79] op_sel_hi:[1,0]
	s_nop 0
	v_pk_mul_f32 v[72:73], v[66:67], v[78:79] op_sel_hi:[1,0]
	v_pk_mul_f32 v[66:67], v[64:65], v[78:79] op_sel_hi:[1,0]
	v_cvt_pk_bf16_f32 v64, v68, v69
	ds_read2_b32 v[68:69], v157 offset0:128 offset1:144
	v_cvt_pk_bf16_f32 v65, v70, v71
	v_cvt_pk_bf16_f32 v66, v66, v67
	v_cvt_pk_bf16_f32 v67, v72, v73
	global_store_dwordx4 v[76:77], v[64:67], off offset:256 sc0 sc1
	s_waitcnt lgkmcnt(0)
; __device__ __forceinline__ unsigned pk2(float lo, float hi) { f32x2 v = {lo, hi}; bf16x2_t b = __builtin_convertvector(v, bf16x2_t); return __builtin_bit_cast(unsigned, b); }
; #define PG8_BAR __builtin_amdgcn_s_barrier()
;     __device__ __forceinline__ void operator()(const f32x4 (&acc)[2][2][4][2], const Unit& u, int wr, int wc, int fr, int fq) const {
;     ...
; #pragma unroll
;         for (int ai = 0; ai < 2; ++ai)
; #pragma unroll
;             for (int m = 0; m < 4; ++m) { const int row = row0 + ai * HALF + m * 16; bf16_t* rowp = O + (size_t)row * ldc + col0;
;                 float rs = 1.0f; if (MODE == 1) rs = ct[wr * 64 + fr + ai * HALF + m * 16];
; #pragma unroll
;                 for (int bj = 0; bj < 2; ++bj) { f32x4 v0 = acc[ai][bj][m][0], v1 = acc[ai][bj][m][1];
;                     if (MODE == 1) { v0 = v0 * rs; v1 = v1 * rs; }
;                     if (MODE == 2) { v0 = v0 * cs[bj][0]; v1 = v1 * cs[bj][1]; }
;                     u32x4 w; w.x = pk2(v0[0], v0[1]); w.y = pk2(v0[2], v0[3]); w.z = pk2(v1[0], v1[1]); w.w = pk2(v1[2], v1[3]);
;                     *(u32x4*)(rowp + bj * HALF) = w; } }
; template <int K, int LDA, int LDB, int KGRP, bool APERM, class Epi>
; __device__ __forceinline__ void gemm_phase(LAS unsigned char* lds, const Gemm g, const StaticOrder& S, const Epi& E, const int tid) {
;     ...
;         if (!has_next) break;
; #pragma unroll
;         for (int a = 0; a < 2; ++a)
; #pragma unroll
;             for (int b = 0; b < 2; ++b)
; #pragma unroll
;                 for (int m = 0; m < 4; ++m)
; #pragma unroll
;                     for (int n = 0; n < 2; ++n) acc[a][b][m][n] = (f32x4){0.f, 0.f, 0.f, 0.f};
;         cur = nxt; cA = nA; cB = nB; ++ui;
;         E.init_acc(acc, cur, wr, wc, fr, fq);
;         if (wr == 1) PG8_BAR;
	v_pk_mul_f32 v[60:61], v[60:61], v[68:69] op_sel_hi:[1,0]
	v_pk_mul_f32 v[62:63], v[62:63], v[68:69] op_sel_hi:[1,0]
	v_pk_mul_f32 v[66:67], v[58:59], v[68:69] op_sel_hi:[1,0]
	v_pk_mul_f32 v[58:59], v[56:57], v[68:69] op_sel_hi:[1,0]
	v_cvt_pk_bf16_f32 v56, v60, v61
	v_add_co_u32_e32 v60, vcc, s3, v134
	v_cvt_pk_bf16_f32 v57, v62, v63
	v_cvt_pk_bf16_f32 v58, v58, v59
	v_cvt_pk_bf16_f32 v59, v66, v67
	v_addc_co_u32_e32 v61, vcc, 0, v135, vcc
	global_store_dwordx4 v[60:61], v[56:59], off sc0 sc1
	v_pk_mul_f32 v[50:51], v[50:51], v[68:69] op_sel_hi:[1,0]
	v_pk_mul_f32 v[48:49], v[48:49], v[68:69] op_sel_hi:[1,0]
	v_pk_mul_f32 v[56:57], v[42:43], v[68:69] op_sel_hi:[1,0]
	v_pk_mul_f32 v[42:43], v[40:41], v[68:69] op_sel_hi:[1,0]
	v_lshl_add_u64 v[64:65], v[134:135], 0, s[8:9]
	v_cvt_pk_bf16_f32 v40, v48, v49
	v_cvt_pk_bf16_f32 v41, v50, v51
	v_cvt_pk_bf16_f32 v42, v42, v43
	v_cvt_pk_bf16_f32 v43, v56, v57
	v_mov_b32_e32 v50, v69
	global_store_dwordx4 v[64:65], v[40:43], off offset:256 sc0 sc1
	v_pk_mul_f32 v[44:45], v[44:45], v[50:51] op_sel_hi:[1,0]
	s_mov_b32 s3, 0x120000
	v_pk_mul_f32 v[42:43], v[54:55], v[50:51] op_sel_hi:[1,0]
	v_pk_mul_f32 v[40:41], v[52:53], v[50:51] op_sel_hi:[1,0]
	v_pk_mul_f32 v[46:47], v[46:47], v[50:51] op_sel_hi:[1,0]
	v_cvt_pk_bf16_f32 v40, v40, v41
	v_cvt_pk_bf16_f32 v41, v42, v43
	v_cvt_pk_bf16_f32 v42, v44, v45
	v_add_co_u32_e32 v44, vcc, s3, v134
	v_cvt_pk_bf16_f32 v43, v46, v47
	s_nop 0
	v_addc_co_u32_e32 v45, vcc, 0, v135, vcc
	v_pk_mul_f32 v[36:37], v[36:37], v[50:51] op_sel_hi:[1,0]
	global_store_dwordx4 v[44:45], v[40:43], off sc0 sc1
	s_mov_b64 s[8:9], 0x120000
	v_pk_mul_f32 v[38:39], v[38:39], v[50:51] op_sel_hi:[1,0]
	v_pk_mul_f32 v[40:41], v[30:31], v[50:51] op_sel_hi:[1,0]
	v_pk_mul_f32 v[30:31], v[28:29], v[50:51] op_sel_hi:[1,0]
	v_cvt_pk_bf16_f32 v28, v36, v37
	ds_read2_b32 v[36:37], v157 offset0:160 offset1:176
	v_lshl_add_u64 v[48:49], v[134:135], 0, s[8:9]
	v_cvt_pk_bf16_f32 v29, v38, v39
	v_cvt_pk_bf16_f32 v30, v30, v31
	v_cvt_pk_bf16_f32 v31, v40, v41
	global_store_dwordx4 v[48:49], v[28:31], off offset:256 sc0 sc1
	s_mov_b32 s3, 0x140000
	s_waitcnt lgkmcnt(0)
	v_pk_mul_f32 v[32:33], v[32:33], v[36:37] op_sel_hi:[1,0]
	v_pk_mul_f32 v[30:31], v[34:35], v[36:37] op_sel_hi:[1,0]
	v_pk_mul_f32 v[34:35], v[26:27], v[36:37] op_sel_hi:[1,0]
	v_pk_mul_f32 v[26:27], v[24:25], v[36:37] op_sel_hi:[1,0]
	v_cvt_pk_bf16_f32 v25, v30, v31
	v_add_co_u32_e32 v30, vcc, s3, v134
	v_cvt_pk_bf16_f32 v24, v32, v33
	v_cvt_pk_bf16_f32 v26, v26, v27
	v_cvt_pk_bf16_f32 v27, v34, v35
	v_addc_co_u32_e32 v31, vcc, 0, v135, vcc
	s_mov_b64 s[8:9], 0x140000
	global_store_dwordx4 v[30:31], v[24:27], off sc0 sc1
	v_pk_mul_f32 v[18:19], v[18:19], v[36:37] op_sel_hi:[1,0]
	v_pk_mul_f32 v[16:17], v[16:17], v[36:37] op_sel_hi:[1,0]
	v_pk_mul_f32 v[24:25], v[10:11], v[36:37] op_sel_hi:[1,0]
	v_pk_mul_f32 v[10:11], v[8:9], v[36:37] op_sel_hi:[1,0]
	v_lshl_add_u64 v[28:29], v[134:135], 0, s[8:9]
	v_cvt_pk_bf16_f32 v8, v16, v17
	v_cvt_pk_bf16_f32 v9, v18, v19
	v_cvt_pk_bf16_f32 v10, v10, v11
	v_cvt_pk_bf16_f32 v11, v24, v25
	v_mov_b32_e32 v18, v37
	global_store_dwordx4 v[28:29], v[8:11], off offset:256 sc0 sc1
	v_pk_mul_f32 v[12:13], v[12:13], v[18:19] op_sel_hi:[1,0]
	s_mov_b32 s3, 0x160000
	v_pk_mul_f32 v[10:11], v[22:23], v[18:19] op_sel_hi:[1,0]
	v_pk_mul_f32 v[8:9], v[20:21], v[18:19] op_sel_hi:[1,0]
	v_pk_mul_f32 v[14:15], v[14:15], v[18:19] op_sel_hi:[1,0]
	v_cvt_pk_bf16_f32 v8, v8, v9
	v_cvt_pk_bf16_f32 v9, v10, v11
	v_cvt_pk_bf16_f32 v10, v12, v13
	v_add_co_u32_e32 v12, vcc, s3, v134
	v_cvt_pk_bf16_f32 v11, v14, v15
	s_nop 0
	v_addc_co_u32_e32 v13, vcc, 0, v135, vcc
	s_mov_b64 s[8:9], 0x160000
	global_store_dwordx4 v[12:13], v[8:11], off sc0 sc1
	v_pk_mul_f32 v[6:7], v[6:7], v[18:19] op_sel_hi:[1,0]
	v_pk_mul_f32 v[4:5], v[4:5], v[18:19] op_sel_hi:[1,0]
	v_pk_mul_f32 v[8:9], v[2:3], v[18:19] op_sel_hi:[1,0]
	v_pk_mul_f32 v[2:3], v[0:1], v[18:19] op_sel_hi:[1,0]
	v_lshl_add_u64 v[16:17], v[134:135], 0, s[8:9]
	v_cvt_pk_bf16_f32 v0, v4, v5
	v_cvt_pk_bf16_f32 v1, v6, v7
	v_cvt_pk_bf16_f32 v2, v2, v3
	v_cvt_pk_bf16_f32 v3, v8, v9
	s_andn2_b64 vcc, exec, s[6:7]
	s_mov_b64 s[6:7], -1
	global_store_dwordx4 v[16:17], v[0:3], off offset:256 sc0 sc1
	s_cbranch_vccnz .LBB0_355
	s_cmp_lg_u32 s62, s10
	s_cselect_b64 s[54:55], -1, 0
	s_andn2_b64 vcc, exec, s[12:13]
	s_cbranch_vccnz .LBB0_354
	s_barrier
	s_branch .LBB0_354

; #define LAS __attribute__((address_space(3)))
; __device__ __forceinline__ unsigned pk2(float lo, float hi) { f32x2 v = {lo, hi}; bf16x2_t b = __builtin_convertvector(v, bf16x2_t); return __builtin_bit_cast(unsigned, b); }
;     __device__ __forceinline__ void operator()(const f32x4 (&acc)[2][2][4][2], const Unit& u, int wr, int wc, int fr, int fq) const {
;     ...
;         if (MODE == 2) {
; #pragma unroll
;             for (int bj = 0; bj < 2; ++bj)
; #pragma unroll
;                 for (int n = 0; n < 2; ++n) cs[bj][n] = *(const LAS f32x4*)(ct + wc * 32 + 8 * fq + bj * HALF + 4 * n);
;         }
; #pragma unroll
;         for (int ai = 0; ai < 2; ++ai)
; #pragma unroll
;             for (int m = 0; m < 4; ++m) { const int row = row0 + ai * HALF + m * 16; bf16_t* rowp = O + (size_t)row * ldc + col0;
;                 float rs = 1.0f; if (MODE == 1) rs = ct[wr * 64 + fr + ai * HALF + m * 16];
; #pragma unroll
;                 for (int bj = 0; bj < 2; ++bj) { f32x4 v0 = acc[ai][bj][m][0], v1 = acc[ai][bj][m][1];
;                     if (MODE == 1) { v0 = v0 * rs; v1 = v1 * rs; }
;                     if (MODE == 2) { v0 = v0 * cs[bj][0]; v1 = v1 * cs[bj][1]; }
;                     u32x4 w; w.x = pk2(v0[0], v0[1]); w.y = pk2(v0[2], v0[3]); w.z = pk2(v1[0], v1[1]); w.w = pk2(v1[2], v1[3]);
;                     *(u32x4*)(rowp + bj * HALF) = w; } }
.LBB0_398:
	v_lshl_add_u32 v166, s54, 8, v158
	v_or_b32_e32 v156, s3, v161
	ds_read_b128 v[142:145], v163
	ds_read_b128 v[138:141], v163 offset:16
	ds_read_b128 v[134:137], v163 offset:512
	ds_read_b128 v[130:133], v163 offset:528
	v_ashrrev_i32_e32 v167, 31, v166
	v_ashrrev_i32_e32 v157, 31, v156
	v_lshlrev_b64 v[168:169], 14, v[166:167]
	v_lshl_add_u64 v[168:169], s[12:13], 0, v[168:169]
	v_lshlrev_b64 v[170:171], 1, v[156:157]
	v_lshl_add_u64 v[156:157], v[168:169], 0, v[170:171]
	s_waitcnt lgkmcnt(0)
	v_pk_mul_f32 v[128:129], v[128:129], v[144:145]
	v_pk_mul_f32 v[126:127], v[126:127], v[142:143]
	v_pk_mul_f32 v[168:169], v[124:125], v[140:141]
	v_pk_mul_f32 v[124:125], v[122:123], v[138:139]
	v_cvt_pk_bf16_f32 v122, v126, v127
	v_cvt_pk_bf16_f32 v123, v128, v129
	v_cvt_pk_bf16_f32 v124, v124, v125
	v_cvt_pk_bf16_f32 v125, v168, v169
	global_store_dwordx4 v[156:157], v[122:125], off sc0 sc1
	v_pk_mul_f32 v[120:121], v[120:121], v[136:137]
	v_pk_mul_f32 v[118:119], v[118:119], v[134:135]
	v_pk_mul_f32 v[122:123], v[108:109], v[132:133]
	v_pk_mul_f32 v[108:109], v[106:107], v[130:131]
	v_cvt_pk_bf16_f32 v106, v118, v119
	v_cvt_pk_bf16_f32 v107, v120, v121
	v_cvt_pk_bf16_f32 v108, v108, v109
	v_cvt_pk_bf16_f32 v109, v122, v123
	global_store_dwordx4 v[156:157], v[106:109], off offset:256 sc0 sc1
	v_pk_mul_f32 v[112:113], v[112:113], v[140:141]
	v_pk_mul_f32 v[110:111], v[110:111], v[138:139]
	v_or_b32_e32 v106, 16, v166
	v_ashrrev_i32_e32 v107, 31, v106
	v_lshlrev_b64 v[106:107], 14, v[106:107]
	v_lshl_add_u64 v[106:107], s[12:13], 0, v[106:107]
	v_lshl_add_u64 v[118:119], v[106:107], 0, v[170:171]
	v_pk_mul_f32 v[108:109], v[116:117], v[144:145]
	v_pk_mul_f32 v[106:107], v[114:115], v[142:143]
	v_pk_mul_f32 v[100:101], v[100:101], v[136:137]
	v_cvt_pk_bf16_f32 v106, v106, v107
	v_cvt_pk_bf16_f32 v107, v108, v109
	v_cvt_pk_bf16_f32 v108, v110, v111
	v_cvt_pk_bf16_f32 v109, v112, v113
	global_store_dwordx4 v[118:119], v[106:109], off sc0 sc1
	v_pk_mul_f32 v[98:99], v[98:99], v[134:135]
	v_pk_mul_f32 v[94:95], v[94:95], v[140:141]
	v_pk_mul_f32 v[106:107], v[90:91], v[132:133]
	v_pk_mul_f32 v[90:91], v[88:89], v[130:131]
	v_cvt_pk_bf16_f32 v88, v98, v99
	v_cvt_pk_bf16_f32 v89, v100, v101
	v_cvt_pk_bf16_f32 v90, v90, v91
	v_cvt_pk_bf16_f32 v91, v106, v107
	global_store_dwordx4 v[118:119], v[88:91], off offset:256 sc0 sc1
	v_pk_mul_f32 v[92:93], v[92:93], v[138:139]
	v_pk_mul_f32 v[82:83], v[82:83], v[136:137]
	v_or_b32_e32 v88, 32, v166
	v_ashrrev_i32_e32 v89, 31, v88
	v_lshlrev_b64 v[88:89], 14, v[88:89]
	v_lshl_add_u64 v[88:89], s[12:13], 0, v[88:89]
	v_lshl_add_u64 v[98:99], v[88:89], 0, v[170:171]
	v_pk_mul_f32 v[90:91], v[104:105], v[144:145]
	v_pk_mul_f32 v[88:89], v[102:103], v[142:143]
	v_pk_mul_f32 v[80:81], v[80:81], v[134:135]
	v_cvt_pk_bf16_f32 v88, v88, v89
	v_cvt_pk_bf16_f32 v89, v90, v91
	v_cvt_pk_bf16_f32 v90, v92, v93
	v_cvt_pk_bf16_f32 v91, v94, v95
	global_store_dwordx4 v[98:99], v[88:91], off sc0 sc1
	v_pk_mul_f32 v[78:79], v[78:79], v[140:141]
	v_pk_mul_f32 v[76:77], v[76:77], v[138:139]
	v_pk_mul_f32 v[88:89], v[74:75], v[132:133]
	v_pk_mul_f32 v[74:75], v[72:73], v[130:131]
	v_cvt_pk_bf16_f32 v72, v80, v81
	v_cvt_pk_bf16_f32 v73, v82, v83
	v_cvt_pk_bf16_f32 v74, v74, v75
	v_cvt_pk_bf16_f32 v75, v88, v89
	global_store_dwordx4 v[98:99], v[72:75], off offset:256 sc0 sc1
	v_pk_mul_f32 v[70:71], v[70:71], v[136:137]
	v_pk_mul_f32 v[68:69], v[68:69], v[134:135]
	v_or_b32_e32 v72, 48, v166
	v_ashrrev_i32_e32 v73, 31, v72
	v_lshlrev_b64 v[72:73], 14, v[72:73]
	v_lshl_add_u64 v[72:73], s[12:13], 0, v[72:73]
	v_lshl_add_u64 v[80:81], v[72:73], 0, v[170:171]
	v_pk_mul_f32 v[74:75], v[86:87], v[144:145]
	v_pk_mul_f32 v[72:73], v[84:85], v[142:143]
	v_pk_mul_f32 v[60:61], v[60:61], v[142:143]
	v_cvt_pk_bf16_f32 v72, v72, v73
	v_cvt_pk_bf16_f32 v73, v74, v75
	v_cvt_pk_bf16_f32 v74, v76, v77
	v_cvt_pk_bf16_f32 v75, v78, v79
	global_store_dwordx4 v[80:81], v[72:75], off sc0 sc1
	s_mov_b32 s3, 0x200000
	v_pk_mul_f32 v[62:63], v[62:63], v[144:145]
	v_pk_mul_f32 v[72:73], v[66:67], v[132:133]
; #define LAS __attribute__((address_space(3)))
; __device__ __forceinline__ unsigned pk2(float lo, float hi) { f32x2 v = {lo, hi}; bf16x2_t b = __builtin_convertvector(v, bf16x2_t); return __builtin_bit_cast(unsigned, b); }
; #define PG8_BAR __builtin_amdgcn_s_barrier()
;     __device__ __forceinline__ void operator()(const f32x4 (&acc)[2][2][4][2], const Unit& u, int wr, int wc, int fr, int fq) const {
;     ...
;         if (MODE == 2) {
; #pragma unroll
;             for (int bj = 0; bj < 2; ++bj)
; #pragma unroll
;                 for (int n = 0; n < 2; ++n) cs[bj][n] = *(const LAS f32x4*)(ct + wc * 32 + 8 * fq + bj * HALF + 4 * n);
;         }
; #pragma unroll
;         for (int ai = 0; ai < 2; ++ai)
; #pragma unroll
;             for (int m = 0; m < 4; ++m) { const int row = row0 + ai * HALF + m * 16; bf16_t* rowp = O + (size_t)row * ldc + col0;
;                 float rs = 1.0f; if (MODE == 1) rs = ct[wr * 64 + fr + ai * HALF + m * 16];
; #pragma unroll
;                 for (int bj = 0; bj < 2; ++bj) { f32x4 v0 = acc[ai][bj][m][0], v1 = acc[ai][bj][m][1];
;                     if (MODE == 1) { v0 = v0 * rs; v1 = v1 * rs; }
;                     if (MODE == 2) { v0 = v0 * cs[bj][0]; v1 = v1 * cs[bj][1]; }
;                     u32x4 w; w.x = pk2(v0[0], v0[1]); w.y = pk2(v0[2], v0[3]); w.z = pk2(v1[0], v1[1]); w.w = pk2(v1[2], v1[3]);
;                     *(u32x4*)(rowp + bj * HALF) = w; } }
; template <int K, int LDA, int LDB, int KGRP, bool APERM, class Epi>
; __device__ __forceinline__ void gemm_phase(LAS unsigned char* lds, const Gemm g, const StaticOrder& S, const Epi& E, const int tid) {
;     ...
;         if (!has_next) break;
; #pragma unroll
;         for (int a = 0; a < 2; ++a)
; #pragma unroll
;             for (int b = 0; b < 2; ++b)
; #pragma unroll
;                 for (int m = 0; m < 4; ++m)
; #pragma unroll
;                     for (int n = 0; n < 2; ++n) acc[a][b][m][n] = (f32x4){0.f, 0.f, 0.f, 0.f};
;         cur = nxt; cA = nA; cB = nB; ++ui;
;         E.init_acc(acc, cur, wr, wc, fr, fq);
;         if (wr == 1) PG8_BAR;
	v_pk_mul_f32 v[66:67], v[64:65], v[130:131]
	v_cvt_pk_bf16_f32 v64, v68, v69
	v_cvt_pk_bf16_f32 v65, v70, v71
	v_cvt_pk_bf16_f32 v66, v66, v67
	v_cvt_pk_bf16_f32 v67, v72, v73
	global_store_dwordx4 v[80:81], v[64:67], off offset:256 sc0 sc1
	s_mov_b64 s[8:9], 0x200000
	v_pk_mul_f32 v[50:51], v[50:51], v[136:137]
	v_pk_mul_f32 v[66:67], v[58:59], v[140:141]
	v_pk_mul_f32 v[58:59], v[56:57], v[138:139]
	v_cvt_pk_bf16_f32 v56, v60, v61
	v_add_co_u32_e32 v60, vcc, s3, v156
	v_cvt_pk_bf16_f32 v57, v62, v63
	v_cvt_pk_bf16_f32 v58, v58, v59
	v_cvt_pk_bf16_f32 v59, v66, v67
	v_addc_co_u32_e32 v61, vcc, 0, v157, vcc
	global_store_dwordx4 v[60:61], v[56:59], off sc0 sc1
	v_pk_mul_f32 v[48:49], v[48:49], v[134:135]
	v_lshl_add_u64 v[64:65], v[156:157], 0, s[8:9]
	v_pk_mul_f32 v[56:57], v[42:43], v[132:133]
	v_pk_mul_f32 v[42:43], v[40:41], v[130:131]
	v_cvt_pk_bf16_f32 v40, v48, v49
	v_cvt_pk_bf16_f32 v41, v50, v51
	v_cvt_pk_bf16_f32 v42, v42, v43
	v_cvt_pk_bf16_f32 v43, v56, v57
	global_store_dwordx4 v[64:65], v[40:43], off offset:256 sc0 sc1
	v_pk_mul_f32 v[44:45], v[44:45], v[138:139]
	s_mov_b32 s3, 0x240000
	v_pk_mul_f32 v[42:43], v[54:55], v[144:145]
	v_pk_mul_f32 v[40:41], v[52:53], v[142:143]
	v_pk_mul_f32 v[46:47], v[46:47], v[140:141]
	v_cvt_pk_bf16_f32 v40, v40, v41
	v_cvt_pk_bf16_f32 v41, v42, v43
	v_cvt_pk_bf16_f32 v42, v44, v45
	v_add_co_u32_e32 v44, vcc, s3, v156
	v_cvt_pk_bf16_f32 v43, v46, v47
	s_nop 0
	v_addc_co_u32_e32 v45, vcc, 0, v157, vcc
	s_mov_b64 s[8:9], 0x240000
	global_store_dwordx4 v[44:45], v[40:43], off sc0 sc1
	v_pk_mul_f32 v[34:35], v[34:35], v[136:137]
	v_pk_mul_f32 v[32:33], v[32:33], v[134:135]
	v_pk_mul_f32 v[40:41], v[26:27], v[132:133]
	v_pk_mul_f32 v[26:27], v[24:25], v[130:131]
	v_lshl_add_u64 v[48:49], v[156:157], 0, s[8:9]
	v_cvt_pk_bf16_f32 v24, v32, v33
	v_cvt_pk_bf16_f32 v25, v34, v35
	v_cvt_pk_bf16_f32 v26, v26, v27
	v_cvt_pk_bf16_f32 v27, v40, v41
	global_store_dwordx4 v[48:49], v[24:27], off offset:256 sc0 sc1
	v_pk_mul_f32 v[28:29], v[28:29], v[138:139]
	s_mov_b32 s3, 0x280000
	v_pk_mul_f32 v[26:27], v[38:39], v[144:145]
	v_pk_mul_f32 v[24:25], v[36:37], v[142:143]
	v_pk_mul_f32 v[30:31], v[30:31], v[140:141]
	v_cvt_pk_bf16_f32 v24, v24, v25
	v_cvt_pk_bf16_f32 v25, v26, v27
	v_cvt_pk_bf16_f32 v26, v28, v29
	v_add_co_u32_e32 v28, vcc, s3, v156
	v_cvt_pk_bf16_f32 v27, v30, v31
	s_nop 0
	v_addc_co_u32_e32 v29, vcc, 0, v157, vcc
	s_mov_b64 s[8:9], 0x280000
	global_store_dwordx4 v[28:29], v[24:27], off sc0 sc1
	v_pk_mul_f32 v[18:19], v[18:19], v[136:137]
	v_pk_mul_f32 v[16:17], v[16:17], v[134:135]
	v_pk_mul_f32 v[24:25], v[10:11], v[132:133]
	v_pk_mul_f32 v[10:11], v[8:9], v[130:131]
	v_lshl_add_u64 v[32:33], v[156:157], 0, s[8:9]
	v_cvt_pk_bf16_f32 v8, v16, v17
	v_cvt_pk_bf16_f32 v9, v18, v19
	v_cvt_pk_bf16_f32 v10, v10, v11
	v_cvt_pk_bf16_f32 v11, v24, v25
	global_store_dwordx4 v[32:33], v[8:11], off offset:256 sc0 sc1
	v_pk_mul_f32 v[12:13], v[12:13], v[138:139]
	s_mov_b32 s3, 0x2c0000
	v_pk_mul_f32 v[10:11], v[22:23], v[144:145]
	v_pk_mul_f32 v[8:9], v[20:21], v[142:143]
	v_pk_mul_f32 v[14:15], v[14:15], v[140:141]
	v_cvt_pk_bf16_f32 v8, v8, v9
	v_cvt_pk_bf16_f32 v9, v10, v11
	v_cvt_pk_bf16_f32 v10, v12, v13
	v_add_co_u32_e32 v12, vcc, s3, v156
	v_cvt_pk_bf16_f32 v11, v14, v15
	s_nop 0
	v_addc_co_u32_e32 v13, vcc, 0, v157, vcc
	s_mov_b64 s[8:9], 0x2c0000
	global_store_dwordx4 v[12:13], v[8:11], off sc0 sc1
	v_pk_mul_f32 v[6:7], v[6:7], v[136:137]
	v_pk_mul_f32 v[4:5], v[4:5], v[134:135]
	v_pk_mul_f32 v[8:9], v[2:3], v[132:133]
	v_pk_mul_f32 v[2:3], v[0:1], v[130:131]
	v_lshl_add_u64 v[16:17], v[156:157], 0, s[8:9]
	v_cvt_pk_bf16_f32 v0, v4, v5
	v_cvt_pk_bf16_f32 v1, v6, v7
	v_cvt_pk_bf16_f32 v2, v2, v3
	v_cvt_pk_bf16_f32 v3, v8, v9
	s_andn2_b64 vcc, exec, s[6:7]
	s_mov_b64 s[6:7], -1
	global_store_dwordx4 v[16:17], v[0:3], off offset:256 sc0 sc1
	s_cbranch_vccnz .LBB0_383
	s_cmp_lg_u32 s52, s42
	s_cselect_b64 s[66:67], -1, 0
	s_andn2_b64 vcc, exec, s[10:11]
	s_cbranch_vccnz .LBB0_382
	s_barrier
	s_branch .LBB0_382

; __device__ __forceinline__ unsigned pk2(float lo, float hi) { f32x2 v = {lo, hi}; bf16x2_t b = __builtin_convertvector(v, bf16x2_t); return __builtin_bit_cast(unsigned, b); }
; __device__ __forceinline__ float bflo(unsigned w) { return __uint_as_float(w << 16); }
; __device__ __forceinline__ float bfhi(unsigned w) { return __uint_as_float(w & 0xffff0000u); }
;     __device__ __forceinline__ void operator()(const f32x4 (&acc)[2][2][4][2], const Unit& u, int wr, int wc, int fr, int fq) const {
;     ...
;         for (int j = 0; j < 8; ++j) { const int ai = j >> 2, m = j & 3; const int row = row0 + ai * HALF + m * 16; const size_t off = (size_t)row * DM + col0; float ss = 0.f;
;             if (MODE < 3 && j < 6) ldgrp(nx2, (size_t)(row0 + ((j + 2) >> 2) * HALF + ((j + 2) & 3) * 16) * DM + col0);
; #pragma unroll
;             for (int bj = 0; bj < 2; ++bj) { f32x4 o[2];
; #pragma unroll
;                 for (int n = 0; n < 2; ++n) { const int cc = bj * HALF + 4 * n;
;                     f32x4 v = acc[ai][bj][m][n];
;                     if (bias) { v = (v + *(const f32x4*)(bias + col0 + cc)) * *(const f32x4*)(scale + col0 + cc); }
;                     f32x4 b;
;                     if (MODE >= 3) b = (f32x4){0.f, 0.f, 0.f, 0.f};
;                     else if (MODE == 0) b = __builtin_bit_cast(f32x4, cur[bj][n]);
;                     else { const unsigned w0 = n ? cur[bj][0].z : cur[bj][0].x, w1 = n ? cur[bj][0].w : cur[bj][0].y; b = (f32x4){bflo(w0), bfhi(w0), bflo(w1), bfhi(w1)}; }
;                     o[n] = b + v;
;                     if (MODE == 2 || MODE == 4) *(f32x4*)(out + off + cc) = o[n];
;                     ss += (o[n][0] * o[n][0] + o[n][1] * o[n][1]) + (o[n][2] * o[n][2] + o[n][3] * o[n][3]); }
;                 if (MODE != 2 && MODE != 4) { u32x4 w; w.x = pk2(o[0][0], o[0][1]); w.y = pk2(o[0][2], o[0][3]); w.z = pk2(o[1][0], o[1][1]); w.w = pk2(o[1][2], o[1][3]); *(u32x4*)(xb + off + bj * HALF) = w; } }
;             if (MODE != 2 && MODE != 4 && rsq) { ss += __shfl_xor(ss, 16); ss += __shfl_xor(ss, 32); if (fq == 0) rsq[(size_t)row * 64 + u.pn * 4 + wc] = ss; }
; #pragma unroll
;             for (int bj = 0; bj < 2; ++bj)
; #pragma unroll
;                 for (int n = 0; n < 2; ++n) if (MODE < 3) { cur[bj][n] = nxt[bj][n]; nxt[bj][n] = nx2[bj][n]; }
;             asm volatile("" ::: "memory"); }
.LBB0_569:
	v_lshl_add_u32 v142, s68, 8, v148
	v_ashrrev_i32_e32 v143, 31, v142
	v_lshl_or_b32 v140, s8, 8, v150
	v_lshlrev_b64 v[146:147], 12, v[142:143]
	v_ashrrev_i32_e32 v141, 31, v140
	v_pk_add_f32 v[116:117], v[116:117], 0 op_sel_hi:[1,0]
	v_pk_add_f32 v[144:145], v[114:115], 0 op_sel_hi:[1,0]
	v_pk_add_f32 v[114:115], v[120:121], 0 op_sel_hi:[1,0]
	v_pk_add_f32 v[120:121], v[118:119], 0 op_sel_hi:[1,0]
	v_lshl_add_u64 v[118:119], s[10:11], 0, v[146:147]
	v_cvt_pk_bf16_f32 v152, v144, v145
	v_cvt_pk_bf16_f32 v153, v116, v117
	v_cvt_pk_bf16_f32 v154, v120, v121
	v_cvt_pk_bf16_f32 v155, v114, v115
	v_lshl_add_u64 v[156:157], v[140:141], 1, v[118:119]
	s_lshl_b32 s16, s8, 2
	global_store_dwordx4 v[156:157], v[152:155], off sc0 sc1
	v_pk_add_f32 v[124:125], v[124:125], 0 op_sel_hi:[1,0]
	v_pk_add_f32 v[146:147], v[122:123], 0 op_sel_hi:[1,0]
	v_pk_add_f32 v[118:119], v[128:129], 0 op_sel_hi:[1,0]
	v_pk_add_f32 v[122:123], v[126:127], 0 op_sel_hi:[1,0]
	v_cndmask_b32_e64 v152, 0, 1, s[60:61]
	s_ashr_i32 s17, s16, 31
	v_cvt_pk_bf16_f32 v126, v146, v147
	v_cvt_pk_bf16_f32 v127, v124, v125
	v_cvt_pk_bf16_f32 v128, v122, v123
	v_cvt_pk_bf16_f32 v129, v118, v119
	v_cmp_ne_u32_e64 s[8:9], 1, v152
	s_andn2_b64 vcc, exec, s[60:61]
	global_store_dwordx4 v[156:157], v[126:129], off offset:256 sc0 sc1
	s_cbranch_vccnz .LBB0_573
	s_nop 0
	v_mul_f32_e32 v126, v145, v145
	v_mul_f32_e32 v117, v117, v117
	v_fmac_f32_e32 v126, v144, v144
	v_fmac_f32_e32 v117, v116, v116
	v_add_f32_e32 v116, v126, v117
	v_mul_f32_e32 v117, v121, v121
	v_mul_f32_e32 v115, v115, v115
	v_fmac_f32_e32 v117, v120, v120
	v_fmac_f32_e32 v115, v114, v114
	v_add_f32_e32 v114, v117, v115
	v_add_f32_e32 v114, v116, v114
	v_mul_f32_e32 v115, v147, v147
	v_mul_f32_e32 v116, v125, v125
	v_fmac_f32_e32 v115, v146, v146
	v_fmac_f32_e32 v116, v124, v124
	v_add_f32_e32 v115, v115, v116
	v_add_f32_e32 v114, v114, v115
	v_mul_f32_e32 v115, v123, v123
	v_mul_f32_e32 v116, v119, v119
	v_fmac_f32_e32 v115, v122, v122
	v_fmac_f32_e32 v116, v118, v118
	v_add_f32_e32 v115, v115, v116
	v_and_b32_e32 v116, 64, v251
	v_add_f32_e32 v114, v114, v115
	v_xor_b32_e32 v115, 16, v251
	v_add_u32_e32 v116, 64, v116
	v_cmp_lt_i32_e32 vcc, v115, v116
	s_nop 1
	v_cndmask_b32_e32 v115, v251, v115, vcc
	v_lshlrev_b32_e32 v115, 2, v115
	ds_bpermute_b32 v115, v115, v114
	s_waitcnt lgkmcnt(0)
	v_add_f32_e32 v114, v114, v115
	v_xor_b32_e32 v115, 32, v251
	v_cmp_lt_i32_e32 vcc, v115, v116
	s_nop 1
	v_cndmask_b32_e32 v115, v251, v115, vcc
	v_lshlrev_b32_e32 v115, 2, v115
	ds_bpermute_b32 v115, v115, v114
	s_and_saveexec_b64 s[54:55], s[4:5]
	s_cbranch_execz .LBB0_572
	v_lshlrev_b64 v[116:117], 8, v[142:143]
	v_lshl_add_u64 v[116:117], s[14:15], 0, v[116:117]
	v_lshl_add_u64 v[116:117], s[16:17], 2, v[116:117]
	s_lshl_b32 s18, s27, 2
	v_lshl_add_u64 v[116:117], v[116:117], 0, s[18:19]
	s_waitcnt lgkmcnt(0)
	v_add_f32_e32 v114, v114, v115
	global_store_dword v[116:117], v114, off

; __device__ __forceinline__ unsigned pk2(float lo, float hi) { f32x2 v = {lo, hi}; bf16x2_t b = __builtin_convertvector(v, bf16x2_t); return __builtin_bit_cast(unsigned, b); }
; __device__ __forceinline__ float bflo(unsigned w) { return __uint_as_float(w << 16); }
; __device__ __forceinline__ float bfhi(unsigned w) { return __uint_as_float(w & 0xffff0000u); }
;     __device__ __forceinline__ void operator()(const f32x4 (&acc)[2][2][4][2], const Unit& u, int wr, int wc, int fr, int fq) const {
;     ...
;         for (int j = 0; j < 8; ++j) { const int ai = j >> 2, m = j & 3; const int row = row0 + ai * HALF + m * 16; const size_t off = (size_t)row * DM + col0; float ss = 0.f;
;             if (MODE < 3 && j < 6) ldgrp(nx2, (size_t)(row0 + ((j + 2) >> 2) * HALF + ((j + 2) & 3) * 16) * DM + col0);
; #pragma unroll
;             for (int bj = 0; bj < 2; ++bj) { f32x4 o[2];
; #pragma unroll
;                 for (int n = 0; n < 2; ++n) { const int cc = bj * HALF + 4 * n;
;                     f32x4 v = acc[ai][bj][m][n];
;                     if (bias) { v = (v + *(const f32x4*)(bias + col0 + cc)) * *(const f32x4*)(scale + col0 + cc); }
;                     f32x4 b;
;                     if (MODE >= 3) b = (f32x4){0.f, 0.f, 0.f, 0.f};
;                     else if (MODE == 0) b = __builtin_bit_cast(f32x4, cur[bj][n]);
;                     else { const unsigned w0 = n ? cur[bj][0].z : cur[bj][0].x, w1 = n ? cur[bj][0].w : cur[bj][0].y; b = (f32x4){bflo(w0), bfhi(w0), bflo(w1), bfhi(w1)}; }
;                     o[n] = b + v;
;                     if (MODE == 2 || MODE == 4) *(f32x4*)(out + off + cc) = o[n];
;                     ss += (o[n][0] * o[n][0] + o[n][1] * o[n][1]) + (o[n][2] * o[n][2] + o[n][3] * o[n][3]); }
;                 if (MODE != 2 && MODE != 4) { u32x4 w; w.x = pk2(o[0][0], o[0][1]); w.y = pk2(o[0][2], o[0][3]); w.z = pk2(o[1][0], o[1][1]); w.w = pk2(o[1][2], o[1][3]); *(u32x4*)(xb + off + bj * HALF) = w; } }
;             if (MODE != 2 && MODE != 4 && rsq) { ss += __shfl_xor(ss, 16); ss += __shfl_xor(ss, 32); if (fq == 0) rsq[(size_t)row * 64 + u.pn * 4 + wc] = ss; }
; #pragma unroll
;             for (int bj = 0; bj < 2; ++bj)
; #pragma unroll
;                 for (int n = 0; n < 2; ++n) if (MODE < 3) { cur[bj][n] = nxt[bj][n]; nxt[bj][n] = nx2[bj][n]; }
;             asm volatile("" ::: "memory"); }
.LBB0_573:
	v_or_b32_e32 v114, 16, v142
	s_waitcnt lgkmcnt(0)
	v_ashrrev_i32_e32 v115, 31, v114
	v_lshlrev_b64 v[122:123], 12, v[114:115]
	v_pk_add_f32 v[100:101], v[100:101], 0 op_sel_hi:[1,0]
	v_pk_add_f32 v[116:117], v[98:99], 0 op_sel_hi:[1,0]
	v_pk_add_f32 v[98:99], v[104:105], 0 op_sel_hi:[1,0]
	v_pk_add_f32 v[104:105], v[102:103], 0 op_sel_hi:[1,0]
	v_lshl_add_u64 v[102:103], s[10:11], 0, v[122:123]
	v_cvt_pk_bf16_f32 v118, v116, v117
	v_cvt_pk_bf16_f32 v119, v100, v101
	v_cvt_pk_bf16_f32 v120, v104, v105
	v_cvt_pk_bf16_f32 v121, v98, v99
	v_lshl_add_u64 v[122:123], v[140:141], 1, v[102:103]
	global_store_dwordx4 v[122:123], v[118:121], off sc0 sc1
	v_pk_add_f32 v[108:109], v[108:109], 0 op_sel_hi:[1,0]
	v_pk_add_f32 v[102:103], v[112:113], 0 op_sel_hi:[1,0]
	v_pk_add_f32 v[118:119], v[106:107], 0 op_sel_hi:[1,0]
	v_pk_add_f32 v[106:107], v[110:111], 0 op_sel_hi:[1,0]
	v_cvt_pk_bf16_f32 v110, v118, v119
	v_cvt_pk_bf16_f32 v111, v108, v109
	v_cvt_pk_bf16_f32 v112, v106, v107
	v_cvt_pk_bf16_f32 v113, v102, v103
	s_and_b64 vcc, exec, s[8:9]
	global_store_dwordx4 v[122:123], v[110:113], off offset:256 sc0 sc1
	s_cbranch_vccnz .LBB0_577
	s_nop 0
	v_mul_f32_e32 v110, v117, v117
	v_mul_f32_e32 v101, v101, v101
	v_fmac_f32_e32 v110, v116, v116
	v_fmac_f32_e32 v101, v100, v100
	v_add_f32_e32 v100, v110, v101
	v_mul_f32_e32 v101, v105, v105
	v_mul_f32_e32 v99, v99, v99
	v_fmac_f32_e32 v101, v104, v104
	v_fmac_f32_e32 v99, v98, v98
	v_add_f32_e32 v98, v101, v99
	v_add_f32_e32 v98, v100, v98
	v_mul_f32_e32 v99, v119, v119
	v_mul_f32_e32 v100, v109, v109
	v_fmac_f32_e32 v99, v118, v118
	v_fmac_f32_e32 v100, v108, v108
	v_add_f32_e32 v99, v99, v100
	v_add_f32_e32 v98, v98, v99
	v_mul_f32_e32 v99, v107, v107
	v_mul_f32_e32 v100, v103, v103
	v_fmac_f32_e32 v99, v106, v106
	v_fmac_f32_e32 v100, v102, v102
	v_add_f32_e32 v99, v99, v100
	v_and_b32_e32 v100, 64, v251
	v_add_f32_e32 v98, v98, v99
	v_xor_b32_e32 v99, 16, v251
	v_add_u32_e32 v100, 64, v100
	v_cmp_lt_i32_e32 vcc, v99, v100
	s_nop 1
	v_cndmask_b32_e32 v99, v251, v99, vcc
	v_lshlrev_b32_e32 v99, 2, v99
	ds_bpermute_b32 v99, v99, v98
	s_waitcnt lgkmcnt(0)
	v_add_f32_e32 v98, v98, v99
	v_xor_b32_e32 v99, 32, v251
	v_cmp_lt_i32_e32 vcc, v99, v100
	s_nop 1
	v_cndmask_b32_e32 v99, v251, v99, vcc
	v_lshlrev_b32_e32 v99, 2, v99
	ds_bpermute_b32 v99, v99, v98
	s_and_saveexec_b64 s[54:55], s[4:5]
	s_cbranch_execz .LBB0_576
	v_lshlrev_b64 v[100:101], 8, v[114:115]
	v_lshl_add_u64 v[100:101], s[14:15], 0, v[100:101]
	v_lshl_add_u64 v[100:101], s[16:17], 2, v[100:101]
	s_lshl_b32 s18, s27, 2
	v_lshl_add_u64 v[100:101], v[100:101], 0, s[18:19]
	s_waitcnt lgkmcnt(0)
	v_add_f32_e32 v98, v98, v99
	global_store_dword v[100:101], v98, off

; __device__ __forceinline__ unsigned pk2(float lo, float hi) { f32x2 v = {lo, hi}; bf16x2_t b = __builtin_convertvector(v, bf16x2_t); return __builtin_bit_cast(unsigned, b); }
; __device__ __forceinline__ float bflo(unsigned w) { return __uint_as_float(w << 16); }
; __device__ __forceinline__ float bfhi(unsigned w) { return __uint_as_float(w & 0xffff0000u); }
;     __device__ __forceinline__ void operator()(const f32x4 (&acc)[2][2][4][2], const Unit& u, int wr, int wc, int fr, int fq) const {
;     ...
;         for (int j = 0; j < 8; ++j) { const int ai = j >> 2, m = j & 3; const int row = row0 + ai * HALF + m * 16; const size_t off = (size_t)row * DM + col0; float ss = 0.f;
;             if (MODE < 3 && j < 6) ldgrp(nx2, (size_t)(row0 + ((j + 2) >> 2) * HALF + ((j + 2) & 3) * 16) * DM + col0);
; #pragma unroll
;             for (int bj = 0; bj < 2; ++bj) { f32x4 o[2];
; #pragma unroll
;                 for (int n = 0; n < 2; ++n) { const int cc = bj * HALF + 4 * n;
;                     f32x4 v = acc[ai][bj][m][n];
;                     if (bias) { v = (v + *(const f32x4*)(bias + col0 + cc)) * *(const f32x4*)(scale + col0 + cc); }
;                     f32x4 b;
;                     if (MODE >= 3) b = (f32x4){0.f, 0.f, 0.f, 0.f};
;                     else if (MODE == 0) b = __builtin_bit_cast(f32x4, cur[bj][n]);
;                     else { const unsigned w0 = n ? cur[bj][0].z : cur[bj][0].x, w1 = n ? cur[bj][0].w : cur[bj][0].y; b = (f32x4){bflo(w0), bfhi(w0), bflo(w1), bfhi(w1)}; }
;                     o[n] = b + v;
;                     if (MODE == 2 || MODE == 4) *(f32x4*)(out + off + cc) = o[n];
;                     ss += (o[n][0] * o[n][0] + o[n][1] * o[n][1]) + (o[n][2] * o[n][2] + o[n][3] * o[n][3]); }
;                 if (MODE != 2 && MODE != 4) { u32x4 w; w.x = pk2(o[0][0], o[0][1]); w.y = pk2(o[0][2], o[0][3]); w.z = pk2(o[1][0], o[1][1]); w.w = pk2(o[1][2], o[1][3]); *(u32x4*)(xb + off + bj * HALF) = w; } }
;             if (MODE != 2 && MODE != 4 && rsq) { ss += __shfl_xor(ss, 16); ss += __shfl_xor(ss, 32); if (fq == 0) rsq[(size_t)row * 64 + u.pn * 4 + wc] = ss; }
; #pragma unroll
;             for (int bj = 0; bj < 2; ++bj)
; #pragma unroll
;                 for (int n = 0; n < 2; ++n) if (MODE < 3) { cur[bj][n] = nxt[bj][n]; nxt[bj][n] = nx2[bj][n]; }
;             asm volatile("" ::: "memory"); }
.LBB0_577:
	v_or_b32_e32 v98, 32, v142
	s_waitcnt lgkmcnt(0)
	v_ashrrev_i32_e32 v99, 31, v98
	v_lshlrev_b64 v[106:107], 12, v[98:99]
	v_pk_add_f32 v[82:83], v[82:83], 0 op_sel_hi:[1,0]
	v_pk_add_f32 v[100:101], v[80:81], 0 op_sel_hi:[1,0]
	v_pk_add_f32 v[80:81], v[86:87], 0 op_sel_hi:[1,0]
	v_pk_add_f32 v[86:87], v[84:85], 0 op_sel_hi:[1,0]
	v_lshl_add_u64 v[84:85], s[10:11], 0, v[106:107]
	v_cvt_pk_bf16_f32 v102, v100, v101
	v_cvt_pk_bf16_f32 v103, v82, v83
	v_cvt_pk_bf16_f32 v104, v86, v87
	v_cvt_pk_bf16_f32 v105, v80, v81
	v_lshl_add_u64 v[106:107], v[140:141], 1, v[84:85]
	global_store_dwordx4 v[106:107], v[102:105], off sc0 sc1
	v_pk_add_f32 v[90:91], v[90:91], 0 op_sel_hi:[1,0]
	v_pk_add_f32 v[84:85], v[94:95], 0 op_sel_hi:[1,0]
	v_pk_add_f32 v[102:103], v[88:89], 0 op_sel_hi:[1,0]
	v_pk_add_f32 v[88:89], v[92:93], 0 op_sel_hi:[1,0]
	v_cvt_pk_bf16_f32 v92, v102, v103
	v_cvt_pk_bf16_f32 v93, v90, v91
	v_cvt_pk_bf16_f32 v94, v88, v89
	v_cvt_pk_bf16_f32 v95, v84, v85
	s_and_b64 vcc, exec, s[8:9]
	global_store_dwordx4 v[106:107], v[92:95], off offset:256 sc0 sc1
	s_cbranch_vccnz .LBB0_581
	s_nop 0
	v_mul_f32_e32 v92, v101, v101
	v_mul_f32_e32 v83, v83, v83
	v_fmac_f32_e32 v92, v100, v100
	v_fmac_f32_e32 v83, v82, v82
	v_add_f32_e32 v82, v92, v83
	v_mul_f32_e32 v83, v87, v87
	v_mul_f32_e32 v81, v81, v81
	v_fmac_f32_e32 v83, v86, v86
	v_fmac_f32_e32 v81, v80, v80
	v_add_f32_e32 v80, v83, v81
	v_add_f32_e32 v80, v82, v80
	v_mul_f32_e32 v81, v103, v103
	v_mul_f32_e32 v82, v91, v91
	v_fmac_f32_e32 v81, v102, v102
	v_fmac_f32_e32 v82, v90, v90
	v_add_f32_e32 v81, v81, v82
	v_add_f32_e32 v80, v80, v81
	v_mul_f32_e32 v81, v89, v89
	v_mul_f32_e32 v82, v85, v85
	v_fmac_f32_e32 v81, v88, v88
	v_fmac_f32_e32 v82, v84, v84
	v_add_f32_e32 v81, v81, v82
	v_and_b32_e32 v82, 64, v251
	v_add_f32_e32 v80, v80, v81
	v_xor_b32_e32 v81, 16, v251
	v_add_u32_e32 v82, 64, v82
	v_cmp_lt_i32_e32 vcc, v81, v82
	s_nop 1
	v_cndmask_b32_e32 v81, v251, v81, vcc
	v_lshlrev_b32_e32 v81, 2, v81
	ds_bpermute_b32 v81, v81, v80
	s_waitcnt lgkmcnt(0)
	v_add_f32_e32 v80, v80, v81
	v_xor_b32_e32 v81, 32, v251
	v_cmp_lt_i32_e32 vcc, v81, v82
	s_nop 1
	v_cndmask_b32_e32 v81, v251, v81, vcc
	v_lshlrev_b32_e32 v81, 2, v81
	ds_bpermute_b32 v81, v81, v80
	s_and_saveexec_b64 s[54:55], s[4:5]
	s_cbranch_execz .LBB0_580
	v_lshlrev_b64 v[82:83], 8, v[98:99]
	v_lshl_add_u64 v[82:83], s[14:15], 0, v[82:83]
	v_lshl_add_u64 v[82:83], s[16:17], 2, v[82:83]
	s_lshl_b32 s18, s27, 2
	v_lshl_add_u64 v[82:83], v[82:83], 0, s[18:19]
	s_waitcnt lgkmcnt(0)
	v_add_f32_e32 v80, v80, v81
	global_store_dword v[82:83], v80, off

; __device__ __forceinline__ unsigned pk2(float lo, float hi) { f32x2 v = {lo, hi}; bf16x2_t b = __builtin_convertvector(v, bf16x2_t); return __builtin_bit_cast(unsigned, b); }
; __device__ __forceinline__ float bflo(unsigned w) { return __uint_as_float(w << 16); }
; __device__ __forceinline__ float bfhi(unsigned w) { return __uint_as_float(w & 0xffff0000u); }
;     __device__ __forceinline__ void operator()(const f32x4 (&acc)[2][2][4][2], const Unit& u, int wr, int wc, int fr, int fq) const {
;     ...
;         for (int j = 0; j < 8; ++j) { const int ai = j >> 2, m = j & 3; const int row = row0 + ai * HALF + m * 16; const size_t off = (size_t)row * DM + col0; float ss = 0.f;
;             if (MODE < 3 && j < 6) ldgrp(nx2, (size_t)(row0 + ((j + 2) >> 2) * HALF + ((j + 2) & 3) * 16) * DM + col0);
; #pragma unroll
;             for (int bj = 0; bj < 2; ++bj) { f32x4 o[2];
; #pragma unroll
;                 for (int n = 0; n < 2; ++n) { const int cc = bj * HALF + 4 * n;
;                     f32x4 v = acc[ai][bj][m][n];
;                     if (bias) { v = (v + *(const f32x4*)(bias + col0 + cc)) * *(const f32x4*)(scale + col0 + cc); }
;                     f32x4 b;
;                     if (MODE >= 3) b = (f32x4){0.f, 0.f, 0.f, 0.f};
;                     else if (MODE == 0) b = __builtin_bit_cast(f32x4, cur[bj][n]);
;                     else { const unsigned w0 = n ? cur[bj][0].z : cur[bj][0].x, w1 = n ? cur[bj][0].w : cur[bj][0].y; b = (f32x4){bflo(w0), bfhi(w0), bflo(w1), bfhi(w1)}; }
;                     o[n] = b + v;
;                     if (MODE == 2 || MODE == 4) *(f32x4*)(out + off + cc) = o[n];
;                     ss += (o[n][0] * o[n][0] + o[n][1] * o[n][1]) + (o[n][2] * o[n][2] + o[n][3] * o[n][3]); }
;                 if (MODE != 2 && MODE != 4) { u32x4 w; w.x = pk2(o[0][0], o[0][1]); w.y = pk2(o[0][2], o[0][3]); w.z = pk2(o[1][0], o[1][1]); w.w = pk2(o[1][2], o[1][3]); *(u32x4*)(xb + off + bj * HALF) = w; } }
;             if (MODE != 2 && MODE != 4 && rsq) { ss += __shfl_xor(ss, 16); ss += __shfl_xor(ss, 32); if (fq == 0) rsq[(size_t)row * 64 + u.pn * 4 + wc] = ss; }
; #pragma unroll
;             for (int bj = 0; bj < 2; ++bj)
; #pragma unroll
;                 for (int n = 0; n < 2; ++n) if (MODE < 3) { cur[bj][n] = nxt[bj][n]; nxt[bj][n] = nx2[bj][n]; }
;             asm volatile("" ::: "memory"); }
.LBB0_581:
	v_or_b32_e32 v80, 48, v142
	s_waitcnt lgkmcnt(0)
	v_ashrrev_i32_e32 v81, 31, v80
	v_lshlrev_b64 v[88:89], 12, v[80:81]
	v_pk_add_f32 v[50:51], v[50:51], 0 op_sel_hi:[1,0]
	v_pk_add_f32 v[82:83], v[48:49], 0 op_sel_hi:[1,0]
	v_pk_add_f32 v[48:49], v[54:55], 0 op_sel_hi:[1,0]
	v_pk_add_f32 v[54:55], v[52:53], 0 op_sel_hi:[1,0]
	v_lshl_add_u64 v[52:53], s[10:11], 0, v[88:89]
	v_cvt_pk_bf16_f32 v84, v82, v83
	v_cvt_pk_bf16_f32 v85, v50, v51
	v_cvt_pk_bf16_f32 v86, v54, v55
	v_cvt_pk_bf16_f32 v87, v48, v49
	v_lshl_add_u64 v[88:89], v[140:141], 1, v[52:53]
	global_store_dwordx4 v[88:89], v[84:87], off sc0 sc1
	v_pk_add_f32 v[70:71], v[70:71], 0 op_sel_hi:[1,0]
	v_pk_add_f32 v[52:53], v[78:79], 0 op_sel_hi:[1,0]
	v_pk_add_f32 v[84:85], v[68:69], 0 op_sel_hi:[1,0]
	v_pk_add_f32 v[68:69], v[76:77], 0 op_sel_hi:[1,0]
	v_cvt_pk_bf16_f32 v76, v84, v85
	v_cvt_pk_bf16_f32 v77, v70, v71
	v_cvt_pk_bf16_f32 v78, v68, v69
	v_cvt_pk_bf16_f32 v79, v52, v53
	s_and_b64 vcc, exec, s[8:9]
	global_store_dwordx4 v[88:89], v[76:79], off offset:256 sc0 sc1
	s_cbranch_vccnz .LBB0_585
	s_nop 0
	v_mul_f32_e32 v76, v83, v83
	v_mul_f32_e32 v51, v51, v51
	v_fmac_f32_e32 v76, v82, v82
	v_fmac_f32_e32 v51, v50, v50
	v_add_f32_e32 v50, v76, v51
	v_mul_f32_e32 v51, v55, v55
	v_mul_f32_e32 v49, v49, v49
	v_fmac_f32_e32 v51, v54, v54
	v_fmac_f32_e32 v49, v48, v48
	v_add_f32_e32 v48, v51, v49
	v_add_f32_e32 v48, v50, v48
	v_mul_f32_e32 v49, v85, v85
	v_mul_f32_e32 v50, v71, v71
	v_fmac_f32_e32 v49, v84, v84
	v_fmac_f32_e32 v50, v70, v70
	v_add_f32_e32 v49, v49, v50
	v_add_f32_e32 v48, v48, v49
	v_mul_f32_e32 v49, v69, v69
	v_mul_f32_e32 v50, v53, v53
	v_fmac_f32_e32 v49, v68, v68
	v_fmac_f32_e32 v50, v52, v52
	v_add_f32_e32 v49, v49, v50
	v_and_b32_e32 v50, 64, v251
	v_add_f32_e32 v48, v48, v49
	v_xor_b32_e32 v49, 16, v251
	v_add_u32_e32 v50, 64, v50
	v_cmp_lt_i32_e32 vcc, v49, v50
	s_nop 1
	v_cndmask_b32_e32 v49, v251, v49, vcc
	v_lshlrev_b32_e32 v49, 2, v49
	ds_bpermute_b32 v49, v49, v48
	s_waitcnt lgkmcnt(0)
	v_add_f32_e32 v48, v48, v49
	v_xor_b32_e32 v49, 32, v251
	v_cmp_lt_i32_e32 vcc, v49, v50
	s_nop 1
	v_cndmask_b32_e32 v49, v251, v49, vcc
	v_lshlrev_b32_e32 v49, 2, v49
	ds_bpermute_b32 v49, v49, v48
	s_and_saveexec_b64 s[54:55], s[4:5]
	s_cbranch_execz .LBB0_584
	v_lshlrev_b64 v[50:51], 8, v[80:81]
	v_lshl_add_u64 v[50:51], s[14:15], 0, v[50:51]
	v_lshl_add_u64 v[50:51], s[16:17], 2, v[50:51]
	s_lshl_b32 s18, s27, 2
	v_lshl_add_u64 v[50:51], v[50:51], 0, s[18:19]
	s_waitcnt lgkmcnt(0)
	v_add_f32_e32 v48, v48, v49
	global_store_dword v[50:51], v48, off

; __device__ __forceinline__ unsigned pk2(float lo, float hi) { f32x2 v = {lo, hi}; bf16x2_t b = __builtin_convertvector(v, bf16x2_t); return __builtin_bit_cast(unsigned, b); }
; __device__ __forceinline__ float bflo(unsigned w) { return __uint_as_float(w << 16); }
; __device__ __forceinline__ float bfhi(unsigned w) { return __uint_as_float(w & 0xffff0000u); }
;     __device__ __forceinline__ void operator()(const f32x4 (&acc)[2][2][4][2], const Unit& u, int wr, int wc, int fr, int fq) const {
;     ...
;         for (int j = 0; j < 8; ++j) { const int ai = j >> 2, m = j & 3; const int row = row0 + ai * HALF + m * 16; const size_t off = (size_t)row * DM + col0; float ss = 0.f;
;             if (MODE < 3 && j < 6) ldgrp(nx2, (size_t)(row0 + ((j + 2) >> 2) * HALF + ((j + 2) & 3) * 16) * DM + col0);
; #pragma unroll
;             for (int bj = 0; bj < 2; ++bj) { f32x4 o[2];
; #pragma unroll
;                 for (int n = 0; n < 2; ++n) { const int cc = bj * HALF + 4 * n;
;                     f32x4 v = acc[ai][bj][m][n];
;                     if (bias) { v = (v + *(const f32x4*)(bias + col0 + cc)) * *(const f32x4*)(scale + col0 + cc); }
;                     f32x4 b;
;                     if (MODE >= 3) b = (f32x4){0.f, 0.f, 0.f, 0.f};
;                     else if (MODE == 0) b = __builtin_bit_cast(f32x4, cur[bj][n]);
;                     else { const unsigned w0 = n ? cur[bj][0].z : cur[bj][0].x, w1 = n ? cur[bj][0].w : cur[bj][0].y; b = (f32x4){bflo(w0), bfhi(w0), bflo(w1), bfhi(w1)}; }
;                     o[n] = b + v;
;                     if (MODE == 2 || MODE == 4) *(f32x4*)(out + off + cc) = o[n];
;                     ss += (o[n][0] * o[n][0] + o[n][1] * o[n][1]) + (o[n][2] * o[n][2] + o[n][3] * o[n][3]); }
;                 if (MODE != 2 && MODE != 4) { u32x4 w; w.x = pk2(o[0][0], o[0][1]); w.y = pk2(o[0][2], o[0][3]); w.z = pk2(o[1][0], o[1][1]); w.w = pk2(o[1][2], o[1][3]); *(u32x4*)(xb + off + bj * HALF) = w; } }
;             if (MODE != 2 && MODE != 4 && rsq) { ss += __shfl_xor(ss, 16); ss += __shfl_xor(ss, 32); if (fq == 0) rsq[(size_t)row * 64 + u.pn * 4 + wc] = ss; }
; #pragma unroll
;             for (int bj = 0; bj < 2; ++bj)
; #pragma unroll
;                 for (int n = 0; n < 2; ++n) if (MODE < 3) { cur[bj][n] = nxt[bj][n]; nxt[bj][n] = nx2[bj][n]; }
;             asm volatile("" ::: "memory"); }
.LBB0_585:
	v_add_u32_e32 v48, 0x80, v142
	s_waitcnt lgkmcnt(0)
	v_ashrrev_i32_e32 v49, 31, v48
	v_lshlrev_b64 v[68:69], 12, v[48:49]
	v_pk_add_f32 v[38:39], v[38:39], 0 op_sel_hi:[1,0]
	v_pk_add_f32 v[50:51], v[36:37], 0 op_sel_hi:[1,0]
	v_pk_add_f32 v[36:37], v[46:47], 0 op_sel_hi:[1,0]
	v_pk_add_f32 v[46:47], v[44:45], 0 op_sel_hi:[1,0]
	v_lshl_add_u64 v[44:45], s[10:11], 0, v[68:69]
	v_cvt_pk_bf16_f32 v52, v50, v51
	v_cvt_pk_bf16_f32 v53, v38, v39
	v_cvt_pk_bf16_f32 v54, v46, v47
	v_cvt_pk_bf16_f32 v55, v36, v37
	v_lshl_add_u64 v[68:69], v[140:141], 1, v[44:45]
	global_store_dwordx4 v[68:69], v[52:55], off sc0 sc1
	v_pk_add_f32 v[56:57], v[56:57], 0 op_sel_hi:[1,0]
	v_pk_add_f32 v[44:45], v[62:63], 0 op_sel_hi:[1,0]
	v_pk_add_f32 v[52:53], v[58:59], 0 op_sel_hi:[1,0]
	v_pk_add_f32 v[54:55], v[60:61], 0 op_sel_hi:[1,0]
	v_cvt_pk_bf16_f32 v58, v56, v57
	v_cvt_pk_bf16_f32 v59, v52, v53
	v_cvt_pk_bf16_f32 v60, v54, v55
	v_cvt_pk_bf16_f32 v61, v44, v45
	s_and_b64 vcc, exec, s[8:9]
	global_store_dwordx4 v[68:69], v[58:61], off offset:256 sc0 sc1
	s_cbranch_vccnz .LBB0_589
	v_mul_f32_e32 v51, v51, v51
	v_mul_f32_e32 v39, v39, v39
	v_fmac_f32_e32 v51, v50, v50
	v_fmac_f32_e32 v39, v38, v38
	v_add_f32_e32 v38, v51, v39
	v_mul_f32_e32 v39, v47, v47
	v_mul_f32_e32 v37, v37, v37
	v_fmac_f32_e32 v39, v46, v46
	v_fmac_f32_e32 v37, v36, v36
	v_add_f32_e32 v36, v39, v37
	v_add_f32_e32 v36, v38, v36
	v_mul_f32_e32 v37, v57, v57
	v_mul_f32_e32 v38, v53, v53
	v_fmac_f32_e32 v37, v56, v56
	v_fmac_f32_e32 v38, v52, v52
	v_add_f32_e32 v37, v37, v38
	v_add_f32_e32 v36, v36, v37
	v_mul_f32_e32 v37, v55, v55
	v_mul_f32_e32 v38, v45, v45
	v_fmac_f32_e32 v37, v54, v54
	v_fmac_f32_e32 v38, v44, v44
	v_add_f32_e32 v37, v37, v38
	v_and_b32_e32 v38, 64, v251
	v_add_f32_e32 v36, v36, v37
	v_xor_b32_e32 v37, 16, v251
	v_add_u32_e32 v38, 64, v38
	v_cmp_lt_i32_e32 vcc, v37, v38
	s_nop 1
	v_cndmask_b32_e32 v37, v251, v37, vcc
	v_lshlrev_b32_e32 v37, 2, v37
	ds_bpermute_b32 v37, v37, v36
	s_waitcnt lgkmcnt(0)
	v_add_f32_e32 v36, v36, v37
	v_xor_b32_e32 v37, 32, v251
	v_cmp_lt_i32_e32 vcc, v37, v38
	s_nop 1
	v_cndmask_b32_e32 v37, v251, v37, vcc
	v_lshlrev_b32_e32 v37, 2, v37
	ds_bpermute_b32 v37, v37, v36
	s_and_saveexec_b64 s[54:55], s[4:5]
	s_cbranch_execz .LBB0_588
	v_lshlrev_b64 v[38:39], 8, v[48:49]
	v_lshl_add_u64 v[38:39], s[14:15], 0, v[38:39]
	v_lshl_add_u64 v[38:39], s[16:17], 2, v[38:39]
	s_lshl_b32 s18, s27, 2
	v_lshl_add_u64 v[38:39], v[38:39], 0, s[18:19]
	s_waitcnt lgkmcnt(0)
	v_add_f32_e32 v36, v36, v37
	global_store_dword v[38:39], v36, off

; __device__ __forceinline__ unsigned pk2(float lo, float hi) { f32x2 v = {lo, hi}; bf16x2_t b = __builtin_convertvector(v, bf16x2_t); return __builtin_bit_cast(unsigned, b); }
; __device__ __forceinline__ float bflo(unsigned w) { return __uint_as_float(w << 16); }
; __device__ __forceinline__ float bfhi(unsigned w) { return __uint_as_float(w & 0xffff0000u); }
;     __device__ __forceinline__ void operator()(const f32x4 (&acc)[2][2][4][2], const Unit& u, int wr, int wc, int fr, int fq) const {
;     ...
;         for (int j = 0; j < 8; ++j) { const int ai = j >> 2, m = j & 3; const int row = row0 + ai * HALF + m * 16; const size_t off = (size_t)row * DM + col0; float ss = 0.f;
;             if (MODE < 3 && j < 6) ldgrp(nx2, (size_t)(row0 + ((j + 2) >> 2) * HALF + ((j + 2) & 3) * 16) * DM + col0);
; #pragma unroll
;             for (int bj = 0; bj < 2; ++bj) { f32x4 o[2];
; #pragma unroll
;                 for (int n = 0; n < 2; ++n) { const int cc = bj * HALF + 4 * n;
;                     f32x4 v = acc[ai][bj][m][n];
;                     if (bias) { v = (v + *(const f32x4*)(bias + col0 + cc)) * *(const f32x4*)(scale + col0 + cc); }
;                     f32x4 b;
;                     if (MODE >= 3) b = (f32x4){0.f, 0.f, 0.f, 0.f};
;                     else if (MODE == 0) b = __builtin_bit_cast(f32x4, cur[bj][n]);
;                     else { const unsigned w0 = n ? cur[bj][0].z : cur[bj][0].x, w1 = n ? cur[bj][0].w : cur[bj][0].y; b = (f32x4){bflo(w0), bfhi(w0), bflo(w1), bfhi(w1)}; }
;                     o[n] = b + v;
;                     if (MODE == 2 || MODE == 4) *(f32x4*)(out + off + cc) = o[n];
;                     ss += (o[n][0] * o[n][0] + o[n][1] * o[n][1]) + (o[n][2] * o[n][2] + o[n][3] * o[n][3]); }
;                 if (MODE != 2 && MODE != 4) { u32x4 w; w.x = pk2(o[0][0], o[0][1]); w.y = pk2(o[0][2], o[0][3]); w.z = pk2(o[1][0], o[1][1]); w.w = pk2(o[1][2], o[1][3]); *(u32x4*)(xb + off + bj * HALF) = w; } }
;             if (MODE != 2 && MODE != 4 && rsq) { ss += __shfl_xor(ss, 16); ss += __shfl_xor(ss, 32); if (fq == 0) rsq[(size_t)row * 64 + u.pn * 4 + wc] = ss; }
; #pragma unroll
;             for (int bj = 0; bj < 2; ++bj)
; #pragma unroll
;                 for (int n = 0; n < 2; ++n) if (MODE < 3) { cur[bj][n] = nxt[bj][n]; nxt[bj][n] = nx2[bj][n]; }
;             asm volatile("" ::: "memory"); }
.LBB0_589:
	v_or_b32_e32 v36, 16, v48
	s_waitcnt lgkmcnt(0)
	v_ashrrev_i32_e32 v37, 31, v36
	v_lshlrev_b64 v[50:51], 12, v[36:37]
	v_pk_add_f32 v[14:15], v[14:15], 0 op_sel_hi:[1,0]
	v_pk_add_f32 v[38:39], v[12:13], 0 op_sel_hi:[1,0]
	v_pk_add_f32 v[12:13], v[22:23], 0 op_sel_hi:[1,0]
	v_pk_add_f32 v[22:23], v[20:21], 0 op_sel_hi:[1,0]
	v_lshl_add_u64 v[20:21], s[10:11], 0, v[50:51]
	v_cvt_pk_bf16_f32 v44, v38, v39
	v_cvt_pk_bf16_f32 v45, v14, v15
	v_cvt_pk_bf16_f32 v46, v22, v23
	v_cvt_pk_bf16_f32 v47, v12, v13
	v_lshl_add_u64 v[56:57], v[140:141], 1, v[20:21]
	global_store_dwordx4 v[56:57], v[44:47], off sc0 sc1
	v_pk_add_f32 v[50:51], v[64:65], 0 op_sel_hi:[1,0]
	v_pk_add_f32 v[20:21], v[74:75], 0 op_sel_hi:[1,0]
	v_pk_add_f32 v[44:45], v[66:67], 0 op_sel_hi:[1,0]
	v_pk_add_f32 v[46:47], v[72:73], 0 op_sel_hi:[1,0]
	v_cvt_pk_bf16_f32 v52, v50, v51
	v_cvt_pk_bf16_f32 v53, v44, v45
	v_cvt_pk_bf16_f32 v54, v46, v47
	v_cvt_pk_bf16_f32 v55, v20, v21
	s_and_b64 vcc, exec, s[8:9]
	global_store_dwordx4 v[56:57], v[52:55], off offset:256 sc0 sc1
	s_cbranch_vccnz .LBB0_593
	v_mul_f32_e32 v39, v39, v39
	v_mul_f32_e32 v15, v15, v15
	v_fmac_f32_e32 v39, v38, v38
	v_fmac_f32_e32 v15, v14, v14
	v_add_f32_e32 v14, v39, v15
	v_mul_f32_e32 v15, v23, v23
	v_mul_f32_e32 v13, v13, v13
	v_fmac_f32_e32 v15, v22, v22
	v_fmac_f32_e32 v13, v12, v12
	v_add_f32_e32 v12, v15, v13
	v_add_f32_e32 v12, v14, v12
	v_mul_f32_e32 v13, v51, v51
	v_mul_f32_e32 v14, v45, v45
	v_fmac_f32_e32 v13, v50, v50
	v_fmac_f32_e32 v14, v44, v44
	v_add_f32_e32 v13, v13, v14
	v_add_f32_e32 v12, v12, v13
	v_mul_f32_e32 v13, v47, v47
	v_mul_f32_e32 v14, v21, v21
	v_fmac_f32_e32 v13, v46, v46
	v_fmac_f32_e32 v14, v20, v20
	v_add_f32_e32 v13, v13, v14
	v_and_b32_e32 v14, 64, v251
	v_add_f32_e32 v12, v12, v13
	v_xor_b32_e32 v13, 16, v251
	v_add_u32_e32 v14, 64, v14
	v_cmp_lt_i32_e32 vcc, v13, v14
	s_nop 1
	v_cndmask_b32_e32 v13, v251, v13, vcc
	v_lshlrev_b32_e32 v13, 2, v13
	ds_bpermute_b32 v13, v13, v12
	s_waitcnt lgkmcnt(0)
	v_add_f32_e32 v12, v12, v13
	v_xor_b32_e32 v13, 32, v251
	v_cmp_lt_i32_e32 vcc, v13, v14
	s_nop 1
	v_cndmask_b32_e32 v13, v251, v13, vcc
	v_lshlrev_b32_e32 v13, 2, v13
	ds_bpermute_b32 v13, v13, v12
	s_and_saveexec_b64 s[54:55], s[4:5]
	s_cbranch_execz .LBB0_592
	v_lshlrev_b64 v[14:15], 8, v[36:37]
	v_lshl_add_u64 v[14:15], s[14:15], 0, v[14:15]
	v_lshl_add_u64 v[14:15], s[16:17], 2, v[14:15]
	s_lshl_b32 s18, s27, 2
	v_lshl_add_u64 v[14:15], v[14:15], 0, s[18:19]
	s_waitcnt lgkmcnt(0)
	v_add_f32_e32 v12, v12, v13
	global_store_dword v[14:15], v12, off

; __device__ __forceinline__ unsigned pk2(float lo, float hi) { f32x2 v = {lo, hi}; bf16x2_t b = __builtin_convertvector(v, bf16x2_t); return __builtin_bit_cast(unsigned, b); }
; __device__ __forceinline__ float bflo(unsigned w) { return __uint_as_float(w << 16); }
; __device__ __forceinline__ float bfhi(unsigned w) { return __uint_as_float(w & 0xffff0000u); }
;     __device__ __forceinline__ void operator()(const f32x4 (&acc)[2][2][4][2], const Unit& u, int wr, int wc, int fr, int fq) const {
;     ...
;         for (int j = 0; j < 8; ++j) { const int ai = j >> 2, m = j & 3; const int row = row0 + ai * HALF + m * 16; const size_t off = (size_t)row * DM + col0; float ss = 0.f;
;             if (MODE < 3 && j < 6) ldgrp(nx2, (size_t)(row0 + ((j + 2) >> 2) * HALF + ((j + 2) & 3) * 16) * DM + col0);
; #pragma unroll
;             for (int bj = 0; bj < 2; ++bj) { f32x4 o[2];
; #pragma unroll
;                 for (int n = 0; n < 2; ++n) { const int cc = bj * HALF + 4 * n;
;                     f32x4 v = acc[ai][bj][m][n];
;                     if (bias) { v = (v + *(const f32x4*)(bias + col0 + cc)) * *(const f32x4*)(scale + col0 + cc); }
;                     f32x4 b;
;                     if (MODE >= 3) b = (f32x4){0.f, 0.f, 0.f, 0.f};
;                     else if (MODE == 0) b = __builtin_bit_cast(f32x4, cur[bj][n]);
;                     else { const unsigned w0 = n ? cur[bj][0].z : cur[bj][0].x, w1 = n ? cur[bj][0].w : cur[bj][0].y; b = (f32x4){bflo(w0), bfhi(w0), bflo(w1), bfhi(w1)}; }
;                     o[n] = b + v;
;                     if (MODE == 2 || MODE == 4) *(f32x4*)(out + off + cc) = o[n];
;                     ss += (o[n][0] * o[n][0] + o[n][1] * o[n][1]) + (o[n][2] * o[n][2] + o[n][3] * o[n][3]); }
;                 if (MODE != 2 && MODE != 4) { u32x4 w; w.x = pk2(o[0][0], o[0][1]); w.y = pk2(o[0][2], o[0][3]); w.z = pk2(o[1][0], o[1][1]); w.w = pk2(o[1][2], o[1][3]); *(u32x4*)(xb + off + bj * HALF) = w; } }
;             if (MODE != 2 && MODE != 4 && rsq) { ss += __shfl_xor(ss, 16); ss += __shfl_xor(ss, 32); if (fq == 0) rsq[(size_t)row * 64 + u.pn * 4 + wc] = ss; }
; #pragma unroll
;             for (int bj = 0; bj < 2; ++bj)
; #pragma unroll
;                 for (int n = 0; n < 2; ++n) if (MODE < 3) { cur[bj][n] = nxt[bj][n]; nxt[bj][n] = nx2[bj][n]; }
;             asm volatile("" ::: "memory"); }
.LBB0_593:
	v_or_b32_e32 v12, 32, v48
	s_waitcnt lgkmcnt(0)
	v_ashrrev_i32_e32 v13, 31, v12
	v_lshlrev_b64 v[22:23], 12, v[12:13]
	v_pk_add_f32 v[20:21], v[26:27], 0 op_sel_hi:[1,0]
	v_pk_add_f32 v[26:27], v[24:25], 0 op_sel_hi:[1,0]
	v_pk_add_f32 v[14:15], v[30:31], 0 op_sel_hi:[1,0]
	v_pk_add_f32 v[24:25], v[28:29], 0 op_sel_hi:[1,0]
	v_lshl_add_u64 v[22:23], s[10:11], 0, v[22:23]
	v_cvt_pk_bf16_f32 v28, v26, v27
	v_cvt_pk_bf16_f32 v29, v20, v21
	v_cvt_pk_bf16_f32 v30, v24, v25
	v_cvt_pk_bf16_f32 v31, v14, v15
	v_lshl_add_u64 v[38:39], v[140:141], 1, v[22:23]
	global_store_dwordx4 v[38:39], v[28:31], off sc0 sc1
	v_pk_add_f32 v[32:33], v[32:33], 0 op_sel_hi:[1,0]
	v_pk_add_f32 v[22:23], v[42:43], 0 op_sel_hi:[1,0]
	v_pk_add_f32 v[28:29], v[34:35], 0 op_sel_hi:[1,0]
	v_pk_add_f32 v[30:31], v[40:41], 0 op_sel_hi:[1,0]
	v_cvt_pk_bf16_f32 v34, v32, v33
	v_cvt_pk_bf16_f32 v35, v28, v29
	v_cvt_pk_bf16_f32 v36, v30, v31
	v_cvt_pk_bf16_f32 v37, v22, v23
	s_and_b64 vcc, exec, s[8:9]
	global_store_dwordx4 v[38:39], v[34:37], off offset:256 sc0 sc1
	s_cbranch_vccnz .LBB0_597
	v_mul_f32_e32 v27, v27, v27
	v_mul_f32_e32 v21, v21, v21
	v_fmac_f32_e32 v27, v26, v26
	v_fmac_f32_e32 v21, v20, v20
	v_add_f32_e32 v20, v27, v21
	v_mul_f32_e32 v21, v25, v25
	v_mul_f32_e32 v15, v15, v15
	v_fmac_f32_e32 v21, v24, v24
	v_fmac_f32_e32 v15, v14, v14
	v_add_f32_e32 v14, v21, v15
	v_add_f32_e32 v14, v20, v14
	v_mul_f32_e32 v15, v33, v33
	v_mul_f32_e32 v20, v29, v29
	v_fmac_f32_e32 v15, v32, v32
	v_fmac_f32_e32 v20, v28, v28
	v_add_f32_e32 v15, v15, v20
	v_add_f32_e32 v14, v14, v15
	v_mul_f32_e32 v15, v31, v31
	v_mul_f32_e32 v20, v23, v23
	v_fmac_f32_e32 v15, v30, v30
	v_fmac_f32_e32 v20, v22, v22
	v_add_f32_e32 v15, v15, v20
	v_and_b32_e32 v20, 64, v251
	v_add_f32_e32 v14, v14, v15
	v_xor_b32_e32 v15, 16, v251
	v_add_u32_e32 v20, 64, v20
	v_cmp_lt_i32_e32 vcc, v15, v20
	s_nop 1
	v_cndmask_b32_e32 v15, v251, v15, vcc
	v_lshlrev_b32_e32 v15, 2, v15
	ds_bpermute_b32 v15, v15, v14
	s_waitcnt lgkmcnt(0)
	v_add_f32_e32 v14, v14, v15
	v_xor_b32_e32 v15, 32, v251
	v_cmp_lt_i32_e32 vcc, v15, v20
	s_nop 1
	v_cndmask_b32_e32 v15, v251, v15, vcc
	v_lshlrev_b32_e32 v15, 2, v15
	ds_bpermute_b32 v15, v15, v14
	s_and_saveexec_b64 s[54:55], s[4:5]
	s_cbranch_execz .LBB0_596
	v_lshlrev_b64 v[12:13], 8, v[12:13]
	v_lshl_add_u64 v[12:13], s[14:15], 0, v[12:13]
	v_lshl_add_u64 v[12:13], s[16:17], 2, v[12:13]
	s_lshl_b32 s18, s27, 2
	v_lshl_add_u64 v[12:13], v[12:13], 0, s[18:19]
	s_waitcnt lgkmcnt(0)
	v_add_f32_e32 v14, v14, v15
	global_store_dword v[12:13], v14, off

; __device__ __forceinline__ unsigned pk2(float lo, float hi) { f32x2 v = {lo, hi}; bf16x2_t b = __builtin_convertvector(v, bf16x2_t); return __builtin_bit_cast(unsigned, b); }
; __device__ __forceinline__ float bflo(unsigned w) { return __uint_as_float(w << 16); }
; __device__ __forceinline__ float bfhi(unsigned w) { return __uint_as_float(w & 0xffff0000u); }
;     __device__ __forceinline__ void operator()(const f32x4 (&acc)[2][2][4][2], const Unit& u, int wr, int wc, int fr, int fq) const {
;     ...
;         for (int j = 0; j < 8; ++j) { const int ai = j >> 2, m = j & 3; const int row = row0 + ai * HALF + m * 16; const size_t off = (size_t)row * DM + col0; float ss = 0.f;
;             if (MODE < 3 && j < 6) ldgrp(nx2, (size_t)(row0 + ((j + 2) >> 2) * HALF + ((j + 2) & 3) * 16) * DM + col0);
; #pragma unroll
;             for (int bj = 0; bj < 2; ++bj) { f32x4 o[2];
; #pragma unroll
;                 for (int n = 0; n < 2; ++n) { const int cc = bj * HALF + 4 * n;
;                     f32x4 v = acc[ai][bj][m][n];
;                     if (bias) { v = (v + *(const f32x4*)(bias + col0 + cc)) * *(const f32x4*)(scale + col0 + cc); }
;                     f32x4 b;
;                     if (MODE >= 3) b = (f32x4){0.f, 0.f, 0.f, 0.f};
;                     else if (MODE == 0) b = __builtin_bit_cast(f32x4, cur[bj][n]);
;                     else { const unsigned w0 = n ? cur[bj][0].z : cur[bj][0].x, w1 = n ? cur[bj][0].w : cur[bj][0].y; b = (f32x4){bflo(w0), bfhi(w0), bflo(w1), bfhi(w1)}; }
;                     o[n] = b + v;
;                     if (MODE == 2 || MODE == 4) *(f32x4*)(out + off + cc) = o[n];
;                     ss += (o[n][0] * o[n][0] + o[n][1] * o[n][1]) + (o[n][2] * o[n][2] + o[n][3] * o[n][3]); }
;                 if (MODE != 2 && MODE != 4) { u32x4 w; w.x = pk2(o[0][0], o[0][1]); w.y = pk2(o[0][2], o[0][3]); w.z = pk2(o[1][0], o[1][1]); w.w = pk2(o[1][2], o[1][3]); *(u32x4*)(xb + off + bj * HALF) = w; } }
;             if (MODE != 2 && MODE != 4 && rsq) { ss += __shfl_xor(ss, 16); ss += __shfl_xor(ss, 32); if (fq == 0) rsq[(size_t)row * 64 + u.pn * 4 + wc] = ss; }
; #pragma unroll
;             for (int bj = 0; bj < 2; ++bj)
; #pragma unroll
;                 for (int n = 0; n < 2; ++n) if (MODE < 3) { cur[bj][n] = nxt[bj][n]; nxt[bj][n] = nx2[bj][n]; }
;             asm volatile("" ::: "memory"); }
.LBB0_597:
	v_or_b32_e32 v12, 48, v48
	v_ashrrev_i32_e32 v13, 31, v12
	v_lshlrev_b64 v[24:25], 12, v[12:13]
	v_pk_add_f32 v[2:3], v[2:3], 0 op_sel_hi:[1,0]
	s_waitcnt lgkmcnt(0)
	v_pk_add_f32 v[14:15], v[0:1], 0 op_sel_hi:[1,0]
	v_pk_add_f32 v[0:1], v[6:7], 0 op_sel_hi:[1,0]
	v_pk_add_f32 v[6:7], v[4:5], 0 op_sel_hi:[1,0]
	v_lshl_add_u64 v[4:5], s[10:11], 0, v[24:25]
	v_cvt_pk_bf16_f32 v20, v14, v15
	v_cvt_pk_bf16_f32 v21, v2, v3
	v_cvt_pk_bf16_f32 v22, v6, v7
	v_cvt_pk_bf16_f32 v23, v0, v1
	v_lshl_add_u64 v[24:25], v[140:141], 1, v[4:5]
	global_store_dwordx4 v[24:25], v[20:23], off sc0 sc1
	v_pk_add_f32 v[10:11], v[10:11], 0 op_sel_hi:[1,0]
	v_pk_add_f32 v[4:5], v[18:19], 0 op_sel_hi:[1,0]
	v_pk_add_f32 v[20:21], v[8:9], 0 op_sel_hi:[1,0]
	v_pk_add_f32 v[8:9], v[16:17], 0 op_sel_hi:[1,0]
	v_cvt_pk_bf16_f32 v16, v20, v21
	v_cvt_pk_bf16_f32 v17, v10, v11
	v_cvt_pk_bf16_f32 v18, v8, v9
	v_cvt_pk_bf16_f32 v19, v4, v5
	s_and_b64 vcc, exec, s[8:9]
	global_store_dwordx4 v[24:25], v[16:19], off offset:256 sc0 sc1
	s_cbranch_vccnz .LBB0_601
	v_mul_f32_e32 v15, v15, v15
	v_mul_f32_e32 v3, v3, v3
	v_fmac_f32_e32 v15, v14, v14
	v_fmac_f32_e32 v3, v2, v2
	v_add_f32_e32 v2, v15, v3
	v_mul_f32_e32 v3, v7, v7
	v_mul_f32_e32 v1, v1, v1
	v_fmac_f32_e32 v3, v6, v6
	v_fmac_f32_e32 v1, v0, v0
	v_add_f32_e32 v0, v3, v1
	v_add_f32_e32 v0, v2, v0
	v_mul_f32_e32 v1, v21, v21
	v_mul_f32_e32 v2, v11, v11
	v_fmac_f32_e32 v1, v20, v20
	v_fmac_f32_e32 v2, v10, v10
	v_add_f32_e32 v1, v1, v2
	v_add_f32_e32 v0, v0, v1
	v_mul_f32_e32 v1, v9, v9
	v_mul_f32_e32 v2, v5, v5
	v_fmac_f32_e32 v1, v8, v8
	v_fmac_f32_e32 v2, v4, v4
	v_add_f32_e32 v1, v1, v2
	v_and_b32_e32 v2, 64, v251
	v_add_f32_e32 v0, v0, v1
	v_xor_b32_e32 v1, 16, v251
	v_add_u32_e32 v2, 64, v2
	v_cmp_lt_i32_e32 vcc, v1, v2
	s_nop 1
	v_cndmask_b32_e32 v1, v251, v1, vcc
	v_lshlrev_b32_e32 v1, 2, v1
	ds_bpermute_b32 v1, v1, v0
	s_waitcnt lgkmcnt(0)
	v_add_f32_e32 v0, v0, v1
	v_xor_b32_e32 v1, 32, v251
	v_cmp_lt_i32_e32 vcc, v1, v2
	s_nop 1
	v_cndmask_b32_e32 v1, v251, v1, vcc
	v_lshlrev_b32_e32 v1, 2, v1
	ds_bpermute_b32 v1, v1, v0
	s_and_saveexec_b64 s[8:9], s[4:5]
	s_cbranch_execz .LBB0_600
	v_lshlrev_b64 v[2:3], 8, v[12:13]
	v_lshl_add_u64 v[2:3], s[14:15], 0, v[2:3]
	v_lshl_add_u64 v[2:3], s[16:17], 2, v[2:3]
	s_lshl_b32 s18, s27, 2
	v_lshl_add_u64 v[2:3], v[2:3], 0, s[18:19]
	s_waitcnt lgkmcnt(0)
	v_add_f32_e32 v0, v0, v1
	global_store_dword v[2:3], v0, off

; __device__ __forceinline__ unsigned pk2(float lo, float hi) { f32x2 v = {lo, hi}; bf16x2_t b = __builtin_convertvector(v, bf16x2_t); return __builtin_bit_cast(unsigned, b); }
; __device__ __forceinline__ float bflo(unsigned w) { return __uint_as_float(w << 16); }
; __device__ __forceinline__ float bfhi(unsigned w) { return __uint_as_float(w & 0xffff0000u); }
;     __device__ __forceinline__ void operator()(const f32x4 (&acc)[2][2][4][2], const Unit& u, int wr, int wc, int fr, int fq) const {
;     ...
;         for (int j = 0; j < 8; ++j) { const int ai = j >> 2, m = j & 3; const int row = row0 + ai * HALF + m * 16; const size_t off = (size_t)row * DM + col0; float ss = 0.f;
;             if (MODE < 3 && j < 6) ldgrp(nx2, (size_t)(row0 + ((j + 2) >> 2) * HALF + ((j + 2) & 3) * 16) * DM + col0);
; #pragma unroll
;             for (int bj = 0; bj < 2; ++bj) { f32x4 o[2];
; #pragma unroll
;                 for (int n = 0; n < 2; ++n) { const int cc = bj * HALF + 4 * n;
;                     f32x4 v = acc[ai][bj][m][n];
;                     if (bias) { v = (v + *(const f32x4*)(bias + col0 + cc)) * *(const f32x4*)(scale + col0 + cc); }
;                     f32x4 b;
;                     if (MODE >= 3) b = (f32x4){0.f, 0.f, 0.f, 0.f};
;                     else if (MODE == 0) b = __builtin_bit_cast(f32x4, cur[bj][n]);
;                     else { const unsigned w0 = n ? cur[bj][0].z : cur[bj][0].x, w1 = n ? cur[bj][0].w : cur[bj][0].y; b = (f32x4){bflo(w0), bfhi(w0), bflo(w1), bfhi(w1)}; }
;                     o[n] = b + v;
;                     if (MODE == 2 || MODE == 4) *(f32x4*)(out + off + cc) = o[n];
;                     ss += (o[n][0] * o[n][0] + o[n][1] * o[n][1]) + (o[n][2] * o[n][2] + o[n][3] * o[n][3]); }
;                 if (MODE != 2 && MODE != 4) { u32x4 w; w.x = pk2(o[0][0], o[0][1]); w.y = pk2(o[0][2], o[0][3]); w.z = pk2(o[1][0], o[1][1]); w.w = pk2(o[1][2], o[1][3]); *(u32x4*)(xb + off + bj * HALF) = w; } }
.LBB0_774:
	s_waitcnt vmcnt(0)
	v_lshlrev_b32_e32 v190, 16, v150
	v_and_b32_e32 v191, 0xffff0000, v150
	v_lshlrev_b32_e32 v150, 16, v151
	v_and_b32_e32 v151, 0xffff0000, v151
	v_pk_add_f32 v[132:133], v[132:133], v[150:151]
	v_lshlrev_b32_e32 v150, 16, v152
	v_and_b32_e32 v151, 0xffff0000, v152
	v_lshlrev_b32_e32 v152, 16, v153
	v_and_b32_e32 v153, 0xffff0000, v153
	v_pk_add_f32 v[130:131], v[130:131], v[190:191]
	v_pk_add_f32 v[128:129], v[128:129], v[152:153]
	v_pk_add_f32 v[126:127], v[126:127], v[150:151]
	v_cvt_pk_bf16_f32 v150, v130, v131
	v_cvt_pk_bf16_f32 v151, v132, v133
	v_cvt_pk_bf16_f32 v152, v126, v127
	v_cvt_pk_bf16_f32 v153, v128, v129
	s_and_b64 vcc, exec, s[8:9]
	global_store_dwordx4 v[182:183], v[150:153], off sc0 sc1
	s_cbranch_vccnz .LBB0_776
	global_load_dwordx4 v[150:153], v[166:167], off offset:512
	s_waitcnt vmcnt(0)
	v_pk_add_f32 v[152:153], v[120:121], v[152:153]
	v_pk_add_f32 v[150:151], v[118:119], v[150:151]
	global_load_dwordx4 v[118:121], v[164:165], off offset:512
	s_waitcnt vmcnt(0)
	v_pk_mul_f32 v[120:121], v[152:153], v[120:121]
	v_pk_mul_f32 v[118:119], v[150:151], v[118:119]

; __device__ __forceinline__ unsigned pk2(float lo, float hi) { f32x2 v = {lo, hi}; bf16x2_t b = __builtin_convertvector(v, bf16x2_t); return __builtin_bit_cast(unsigned, b); }
; __device__ __forceinline__ float bflo(unsigned w) { return __uint_as_float(w << 16); }
; __device__ __forceinline__ float bfhi(unsigned w) { return __uint_as_float(w & 0xffff0000u); }
;     __device__ __forceinline__ void operator()(const f32x4 (&acc)[2][2][4][2], const Unit& u, int wr, int wc, int fr, int fq) const {
;     ...
;         for (int j = 0; j < 8; ++j) { const int ai = j >> 2, m = j & 3; const int row = row0 + ai * HALF + m * 16; const size_t off = (size_t)row * DM + col0; float ss = 0.f;
;             if (MODE < 3 && j < 6) ldgrp(nx2, (size_t)(row0 + ((j + 2) >> 2) * HALF + ((j + 2) & 3) * 16) * DM + col0);
; #pragma unroll
;             for (int bj = 0; bj < 2; ++bj) { f32x4 o[2];
; #pragma unroll
;                 for (int n = 0; n < 2; ++n) { const int cc = bj * HALF + 4 * n;
;                     f32x4 v = acc[ai][bj][m][n];
;                     if (bias) { v = (v + *(const f32x4*)(bias + col0 + cc)) * *(const f32x4*)(scale + col0 + cc); }
;                     f32x4 b;
;                     if (MODE >= 3) b = (f32x4){0.f, 0.f, 0.f, 0.f};
;                     else if (MODE == 0) b = __builtin_bit_cast(f32x4, cur[bj][n]);
;                     else { const unsigned w0 = n ? cur[bj][0].z : cur[bj][0].x, w1 = n ? cur[bj][0].w : cur[bj][0].y; b = (f32x4){bflo(w0), bfhi(w0), bflo(w1), bfhi(w1)}; }
;                     o[n] = b + v;
;                     if (MODE == 2 || MODE == 4) *(f32x4*)(out + off + cc) = o[n];
;                     ss += (o[n][0] * o[n][0] + o[n][1] * o[n][1]) + (o[n][2] * o[n][2] + o[n][3] * o[n][3]); }
;                 if (MODE != 2 && MODE != 4) { u32x4 w; w.x = pk2(o[0][0], o[0][1]); w.y = pk2(o[0][2], o[0][3]); w.z = pk2(o[1][0], o[1][1]); w.w = pk2(o[1][2], o[1][3]); *(u32x4*)(xb + off + bj * HALF) = w; } }
;             if (MODE != 2 && MODE != 4 && rsq) { ss += __shfl_xor(ss, 16); ss += __shfl_xor(ss, 32); if (fq == 0) rsq[(size_t)row * 64 + u.pn * 4 + wc] = ss; }
.LBB0_778:
	v_lshlrev_b32_e32 v150, 16, v146
	v_and_b32_e32 v151, 0xffff0000, v146
	v_lshlrev_b32_e32 v146, 16, v147
	v_and_b32_e32 v147, 0xffff0000, v147
	v_pk_add_f32 v[120:121], v[120:121], v[146:147]
	v_lshlrev_b32_e32 v146, 16, v148
	v_and_b32_e32 v147, 0xffff0000, v148
	v_lshlrev_b32_e32 v148, 16, v149
	v_and_b32_e32 v149, 0xffff0000, v149
	v_pk_add_f32 v[118:119], v[118:119], v[150:151]
	s_lshl_b32 s78, s10, 2
	v_pk_add_f32 v[116:117], v[116:117], v[148:149]
	v_pk_add_f32 v[114:115], v[114:115], v[146:147]
	v_cndmask_b32_e64 v150, 0, 1, s[68:69]
	s_ashr_i32 s79, s78, 31
	v_cvt_pk_bf16_f32 v146, v118, v119
	v_cvt_pk_bf16_f32 v147, v120, v121
	v_cvt_pk_bf16_f32 v148, v114, v115
	v_cvt_pk_bf16_f32 v149, v116, v117
	v_cmp_ne_u32_e64 s[10:11], 1, v150
	s_andn2_b64 vcc, exec, s[68:69]
	global_store_dwordx4 v[182:183], v[146:149], off offset:256 sc0 sc1
	s_cbranch_vccnz .LBB0_782
	v_mul_f32_e32 v131, v131, v131
	v_mul_f32_e32 v127, v127, v127
	v_mul_f32_e32 v115, v115, v115
	v_fmac_f32_e32 v131, v130, v130
	v_mul_f32_e32 v130, v133, v133
	v_fmac_f32_e32 v127, v126, v126
	v_mul_f32_e32 v126, v129, v129
	v_mul_f32_e32 v119, v119, v119
	v_fmac_f32_e32 v115, v114, v114
	v_mul_f32_e32 v114, v117, v117
	v_fmac_f32_e32 v130, v132, v132
	v_fmac_f32_e32 v126, v128, v128
	v_fmac_f32_e32 v119, v118, v118
	v_mul_f32_e32 v118, v121, v121
	v_fmac_f32_e32 v114, v116, v116
	v_and_b32_e32 v116, 64, v251
	v_add_f32_e32 v130, v131, v130
	v_add_f32_e32 v126, v127, v126
	v_fmac_f32_e32 v118, v120, v120
	v_add_f32_e32 v114, v115, v114
	v_xor_b32_e32 v115, 16, v251
	v_add_u32_e32 v116, 64, v116
	v_add_f32_e32 v126, v130, v126
	v_add_f32_e32 v118, v119, v118
	v_cmp_lt_i32_e32 vcc, v115, v116
	v_add_f32_e32 v118, v126, v118
	v_add_f32_e32 v114, v118, v114
	v_cndmask_b32_e32 v115, v251, v115, vcc
	v_lshlrev_b32_e32 v115, 2, v115
	ds_bpermute_b32 v115, v115, v114
	s_waitcnt lgkmcnt(0)
	v_add_f32_e32 v114, v114, v115
	v_xor_b32_e32 v115, 32, v251
	v_cmp_lt_i32_e32 vcc, v115, v116
	s_nop 1
	v_cndmask_b32_e32 v115, v251, v115, vcc
	v_lshlrev_b32_e32 v115, 2, v115
	ds_bpermute_b32 v115, v115, v114
	s_and_saveexec_b64 s[16:17], s[4:5]
	s_cbranch_execz .LBB0_781
	v_lshlrev_b64 v[116:117], 8, v[176:177]
	v_lshl_add_u64 v[116:117], s[62:63], 0, v[116:117]
	v_lshl_add_u64 v[116:117], s[78:79], 2, v[116:117]
	s_lshl_b32 s18, s28, 2
	v_lshl_add_u64 v[116:117], v[116:117], 0, s[18:19]
	s_waitcnt lgkmcnt(0)
	v_add_f32_e32 v114, v114, v115
	global_store_dword v[116:117], v114, off

; __device__ __forceinline__ unsigned pk2(float lo, float hi) { f32x2 v = {lo, hi}; bf16x2_t b = __builtin_convertvector(v, bf16x2_t); return __builtin_bit_cast(unsigned, b); }
; __device__ __forceinline__ float bflo(unsigned w) { return __uint_as_float(w << 16); }
; __device__ __forceinline__ float bfhi(unsigned w) { return __uint_as_float(w & 0xffff0000u); }
;     __device__ __forceinline__ void operator()(const f32x4 (&acc)[2][2][4][2], const Unit& u, int wr, int wc, int fr, int fq) const {
;     ...
;         for (int j = 0; j < 8; ++j) { const int ai = j >> 2, m = j & 3; const int row = row0 + ai * HALF + m * 16; const size_t off = (size_t)row * DM + col0; float ss = 0.f;
;             if (MODE < 3 && j < 6) ldgrp(nx2, (size_t)(row0 + ((j + 2) >> 2) * HALF + ((j + 2) & 3) * 16) * DM + col0);
; #pragma unroll
;             for (int bj = 0; bj < 2; ++bj) { f32x4 o[2];
; #pragma unroll
;                 for (int n = 0; n < 2; ++n) { const int cc = bj * HALF + 4 * n;
;                     f32x4 v = acc[ai][bj][m][n];
;                     if (bias) { v = (v + *(const f32x4*)(bias + col0 + cc)) * *(const f32x4*)(scale + col0 + cc); }
;                     f32x4 b;
;                     if (MODE >= 3) b = (f32x4){0.f, 0.f, 0.f, 0.f};
;                     else if (MODE == 0) b = __builtin_bit_cast(f32x4, cur[bj][n]);
;                     else { const unsigned w0 = n ? cur[bj][0].z : cur[bj][0].x, w1 = n ? cur[bj][0].w : cur[bj][0].y; b = (f32x4){bflo(w0), bfhi(w0), bflo(w1), bfhi(w1)}; }
;                     o[n] = b + v;
;                     if (MODE == 2 || MODE == 4) *(f32x4*)(out + off + cc) = o[n];
;                     ss += (o[n][0] * o[n][0] + o[n][1] * o[n][1]) + (o[n][2] * o[n][2] + o[n][3] * o[n][3]); }
;                 if (MODE != 2 && MODE != 4) { u32x4 w; w.x = pk2(o[0][0], o[0][1]); w.y = pk2(o[0][2], o[0][3]); w.z = pk2(o[1][0], o[1][1]); w.w = pk2(o[1][2], o[1][3]); *(u32x4*)(xb + off + bj * HALF) = w; } }
.LBB0_786:
	v_lshlrev_b32_e32 v130, 16, v142
	v_and_b32_e32 v131, 0xffff0000, v142
	v_lshlrev_b32_e32 v132, 16, v143
	v_and_b32_e32 v133, 0xffff0000, v143
	v_pk_add_f32 v[112:113], v[112:113], v[132:133]
	v_pk_add_f32 v[110:111], v[110:111], v[130:131]
	v_lshlrev_b32_e32 v130, 16, v144
	v_and_b32_e32 v131, 0xffff0000, v144
	v_lshlrev_b32_e32 v132, 16, v145
	v_and_b32_e32 v133, 0xffff0000, v145
	v_pk_add_f32 v[108:109], v[108:109], v[132:133]
	v_pk_add_f32 v[106:107], v[106:107], v[130:131]
	v_cvt_pk_bf16_f32 v130, v110, v111
	v_cvt_pk_bf16_f32 v131, v112, v113
	v_cvt_pk_bf16_f32 v132, v106, v107
	v_cvt_pk_bf16_f32 v133, v108, v109
	s_and_b64 vcc, exec, s[8:9]
	global_store_dwordx4 v[180:181], v[130:133], off sc0 sc1
	s_cbranch_vccnz .LBB0_788
	global_load_dwordx4 v[130:133], v[166:167], off offset:512
	s_waitcnt vmcnt(0)
	v_pk_add_f32 v[132:133], v[104:105], v[132:133]
	v_pk_add_f32 v[130:131], v[102:103], v[130:131]
	global_load_dwordx4 v[102:105], v[164:165], off offset:512
	s_waitcnt vmcnt(0)
	v_pk_mul_f32 v[104:105], v[132:133], v[104:105]
	v_pk_mul_f32 v[102:103], v[130:131], v[102:103]

; __device__ __forceinline__ unsigned pk2(float lo, float hi) { f32x2 v = {lo, hi}; bf16x2_t b = __builtin_convertvector(v, bf16x2_t); return __builtin_bit_cast(unsigned, b); }
; __device__ __forceinline__ float bflo(unsigned w) { return __uint_as_float(w << 16); }
; __device__ __forceinline__ float bfhi(unsigned w) { return __uint_as_float(w & 0xffff0000u); }
;     __device__ __forceinline__ void operator()(const f32x4 (&acc)[2][2][4][2], const Unit& u, int wr, int wc, int fr, int fq) const {
;     ...
;         for (int j = 0; j < 8; ++j) { const int ai = j >> 2, m = j & 3; const int row = row0 + ai * HALF + m * 16; const size_t off = (size_t)row * DM + col0; float ss = 0.f;
;             if (MODE < 3 && j < 6) ldgrp(nx2, (size_t)(row0 + ((j + 2) >> 2) * HALF + ((j + 2) & 3) * 16) * DM + col0);
; #pragma unroll
;             for (int bj = 0; bj < 2; ++bj) { f32x4 o[2];
; #pragma unroll
;                 for (int n = 0; n < 2; ++n) { const int cc = bj * HALF + 4 * n;
;                     f32x4 v = acc[ai][bj][m][n];
;                     if (bias) { v = (v + *(const f32x4*)(bias + col0 + cc)) * *(const f32x4*)(scale + col0 + cc); }
;                     f32x4 b;
;                     if (MODE >= 3) b = (f32x4){0.f, 0.f, 0.f, 0.f};
;                     else if (MODE == 0) b = __builtin_bit_cast(f32x4, cur[bj][n]);
;                     else { const unsigned w0 = n ? cur[bj][0].z : cur[bj][0].x, w1 = n ? cur[bj][0].w : cur[bj][0].y; b = (f32x4){bflo(w0), bfhi(w0), bflo(w1), bfhi(w1)}; }
;                     o[n] = b + v;
;                     if (MODE == 2 || MODE == 4) *(f32x4*)(out + off + cc) = o[n];
;                     ss += (o[n][0] * o[n][0] + o[n][1] * o[n][1]) + (o[n][2] * o[n][2] + o[n][3] * o[n][3]); }
;                 if (MODE != 2 && MODE != 4) { u32x4 w; w.x = pk2(o[0][0], o[0][1]); w.y = pk2(o[0][2], o[0][3]); w.z = pk2(o[1][0], o[1][1]); w.w = pk2(o[1][2], o[1][3]); *(u32x4*)(xb + off + bj * HALF) = w; } }
;             if (MODE != 2 && MODE != 4 && rsq) { ss += __shfl_xor(ss, 16); ss += __shfl_xor(ss, 32); if (fq == 0) rsq[(size_t)row * 64 + u.pn * 4 + wc] = ss; }
.LBB0_790:
	v_lshlrev_b32_e32 v130, 16, v138
	v_and_b32_e32 v131, 0xffff0000, v138
	v_lshlrev_b32_e32 v132, 16, v139
	v_and_b32_e32 v133, 0xffff0000, v139
	v_pk_add_f32 v[104:105], v[104:105], v[132:133]
	v_pk_add_f32 v[102:103], v[102:103], v[130:131]
	v_lshlrev_b32_e32 v130, 16, v140
	v_and_b32_e32 v131, 0xffff0000, v140
	v_lshlrev_b32_e32 v132, 16, v141
	v_and_b32_e32 v133, 0xffff0000, v141
	v_pk_add_f32 v[100:101], v[100:101], v[132:133]
	v_pk_add_f32 v[98:99], v[98:99], v[130:131]
	v_cvt_pk_bf16_f32 v130, v102, v103
	v_cvt_pk_bf16_f32 v131, v104, v105
	v_cvt_pk_bf16_f32 v132, v98, v99
	v_cvt_pk_bf16_f32 v133, v100, v101
	s_and_b64 vcc, exec, s[10:11]
	global_store_dwordx4 v[180:181], v[130:133], off offset:256 sc0 sc1
	s_cbranch_vccnz .LBB0_794
	v_mul_f32_e32 v111, v111, v111
	v_mul_f32_e32 v107, v107, v107
	v_mul_f32_e32 v99, v99, v99
	v_fmac_f32_e32 v111, v110, v110
	v_mul_f32_e32 v110, v113, v113
	v_fmac_f32_e32 v107, v106, v106
	v_mul_f32_e32 v106, v109, v109
	v_mul_f32_e32 v103, v103, v103
	v_fmac_f32_e32 v99, v98, v98
	v_mul_f32_e32 v98, v101, v101
	v_fmac_f32_e32 v110, v112, v112
	v_fmac_f32_e32 v106, v108, v108
	v_fmac_f32_e32 v103, v102, v102
	v_mul_f32_e32 v102, v105, v105
	v_fmac_f32_e32 v98, v100, v100
	v_and_b32_e32 v100, 64, v251
	v_add_f32_e32 v110, v111, v110
	v_add_f32_e32 v106, v107, v106
	v_fmac_f32_e32 v102, v104, v104
	v_add_f32_e32 v98, v99, v98
	v_xor_b32_e32 v99, 16, v251
	v_add_u32_e32 v100, 64, v100
	v_add_f32_e32 v106, v110, v106
	v_add_f32_e32 v102, v103, v102
	v_cmp_lt_i32_e32 vcc, v99, v100
	v_add_f32_e32 v102, v106, v102
	v_add_f32_e32 v98, v102, v98
	v_cndmask_b32_e32 v99, v251, v99, vcc
	v_lshlrev_b32_e32 v99, 2, v99
	ds_bpermute_b32 v99, v99, v98
	s_waitcnt lgkmcnt(0)
	v_add_f32_e32 v98, v98, v99
	v_xor_b32_e32 v99, 32, v251
	v_cmp_lt_i32_e32 vcc, v99, v100
	s_nop 1
	v_cndmask_b32_e32 v99, v251, v99, vcc
	v_lshlrev_b32_e32 v99, 2, v99
	ds_bpermute_b32 v99, v99, v98
	s_and_saveexec_b64 s[16:17], s[4:5]
	s_cbranch_execz .LBB0_793
	v_lshlrev_b64 v[100:101], 8, v[178:179]
	v_lshl_add_u64 v[100:101], s[62:63], 0, v[100:101]
	v_lshl_add_u64 v[100:101], s[78:79], 2, v[100:101]
	s_lshl_b32 s18, s28, 2
	v_lshl_add_u64 v[100:101], v[100:101], 0, s[18:19]
	s_waitcnt lgkmcnt(0)
	v_add_f32_e32 v98, v98, v99
	global_store_dword v[100:101], v98, off

; __device__ __forceinline__ unsigned pk2(float lo, float hi) { f32x2 v = {lo, hi}; bf16x2_t b = __builtin_convertvector(v, bf16x2_t); return __builtin_bit_cast(unsigned, b); }
; __device__ __forceinline__ float bflo(unsigned w) { return __uint_as_float(w << 16); }
; __device__ __forceinline__ float bfhi(unsigned w) { return __uint_as_float(w & 0xffff0000u); }
;     __device__ __forceinline__ void operator()(const f32x4 (&acc)[2][2][4][2], const Unit& u, int wr, int wc, int fr, int fq) const {
;     ...
;         for (int j = 0; j < 8; ++j) { const int ai = j >> 2, m = j & 3; const int row = row0 + ai * HALF + m * 16; const size_t off = (size_t)row * DM + col0; float ss = 0.f;
;             if (MODE < 3 && j < 6) ldgrp(nx2, (size_t)(row0 + ((j + 2) >> 2) * HALF + ((j + 2) & 3) * 16) * DM + col0);
; #pragma unroll
;             for (int bj = 0; bj < 2; ++bj) { f32x4 o[2];
; #pragma unroll
;                 for (int n = 0; n < 2; ++n) { const int cc = bj * HALF + 4 * n;
;                     f32x4 v = acc[ai][bj][m][n];
;                     if (bias) { v = (v + *(const f32x4*)(bias + col0 + cc)) * *(const f32x4*)(scale + col0 + cc); }
;                     f32x4 b;
;                     if (MODE >= 3) b = (f32x4){0.f, 0.f, 0.f, 0.f};
;                     else if (MODE == 0) b = __builtin_bit_cast(f32x4, cur[bj][n]);
;                     else { const unsigned w0 = n ? cur[bj][0].z : cur[bj][0].x, w1 = n ? cur[bj][0].w : cur[bj][0].y; b = (f32x4){bflo(w0), bfhi(w0), bflo(w1), bfhi(w1)}; }
;                     o[n] = b + v;
;                     if (MODE == 2 || MODE == 4) *(f32x4*)(out + off + cc) = o[n];
;                     ss += (o[n][0] * o[n][0] + o[n][1] * o[n][1]) + (o[n][2] * o[n][2] + o[n][3] * o[n][3]); }
;                 if (MODE != 2 && MODE != 4) { u32x4 w; w.x = pk2(o[0][0], o[0][1]); w.y = pk2(o[0][2], o[0][3]); w.z = pk2(o[1][0], o[1][1]); w.w = pk2(o[1][2], o[1][3]); *(u32x4*)(xb + off + bj * HALF) = w; } }
.LBB0_798:
	v_lshlrev_b32_e32 v110, 16, v134
	v_and_b32_e32 v111, 0xffff0000, v134
	v_lshlrev_b32_e32 v112, 16, v135
	v_and_b32_e32 v113, 0xffff0000, v135
	v_pk_add_f32 v[94:95], v[94:95], v[112:113]
	v_pk_add_f32 v[92:93], v[92:93], v[110:111]
	v_lshlrev_b32_e32 v110, 16, v136
	v_and_b32_e32 v111, 0xffff0000, v136
	v_lshlrev_b32_e32 v112, 16, v137
	v_and_b32_e32 v113, 0xffff0000, v137
	v_pk_add_f32 v[90:91], v[90:91], v[112:113]
	v_pk_add_f32 v[88:89], v[88:89], v[110:111]
	v_cvt_pk_bf16_f32 v110, v92, v93
	v_cvt_pk_bf16_f32 v111, v94, v95
	v_cvt_pk_bf16_f32 v112, v88, v89
	v_cvt_pk_bf16_f32 v113, v90, v91
	s_and_b64 vcc, exec, s[8:9]
	global_store_dwordx4 v[174:175], v[110:113], off sc0 sc1
	s_cbranch_vccnz .LBB0_800
	global_load_dwordx4 v[110:113], v[166:167], off offset:512
	s_waitcnt vmcnt(0)
	v_pk_add_f32 v[112:113], v[86:87], v[112:113]
	v_pk_add_f32 v[110:111], v[84:85], v[110:111]
	global_load_dwordx4 v[84:87], v[164:165], off offset:512
	s_waitcnt vmcnt(0)
	v_pk_mul_f32 v[86:87], v[112:113], v[86:87]
	v_pk_mul_f32 v[84:85], v[110:111], v[84:85]

; __device__ __forceinline__ unsigned pk2(float lo, float hi) { f32x2 v = {lo, hi}; bf16x2_t b = __builtin_convertvector(v, bf16x2_t); return __builtin_bit_cast(unsigned, b); }
; __device__ __forceinline__ float bflo(unsigned w) { return __uint_as_float(w << 16); }
; __device__ __forceinline__ float bfhi(unsigned w) { return __uint_as_float(w & 0xffff0000u); }
;     __device__ __forceinline__ void operator()(const f32x4 (&acc)[2][2][4][2], const Unit& u, int wr, int wc, int fr, int fq) const {
;     ...
;         for (int j = 0; j < 8; ++j) { const int ai = j >> 2, m = j & 3; const int row = row0 + ai * HALF + m * 16; const size_t off = (size_t)row * DM + col0; float ss = 0.f;
;             if (MODE < 3 && j < 6) ldgrp(nx2, (size_t)(row0 + ((j + 2) >> 2) * HALF + ((j + 2) & 3) * 16) * DM + col0);
; #pragma unroll
;             for (int bj = 0; bj < 2; ++bj) { f32x4 o[2];
; #pragma unroll
;                 for (int n = 0; n < 2; ++n) { const int cc = bj * HALF + 4 * n;
;                     f32x4 v = acc[ai][bj][m][n];
;                     if (bias) { v = (v + *(const f32x4*)(bias + col0 + cc)) * *(const f32x4*)(scale + col0 + cc); }
;                     f32x4 b;
;                     if (MODE >= 3) b = (f32x4){0.f, 0.f, 0.f, 0.f};
;                     else if (MODE == 0) b = __builtin_bit_cast(f32x4, cur[bj][n]);
;                     else { const unsigned w0 = n ? cur[bj][0].z : cur[bj][0].x, w1 = n ? cur[bj][0].w : cur[bj][0].y; b = (f32x4){bflo(w0), bfhi(w0), bflo(w1), bfhi(w1)}; }
;                     o[n] = b + v;
;                     if (MODE == 2 || MODE == 4) *(f32x4*)(out + off + cc) = o[n];
;                     ss += (o[n][0] * o[n][0] + o[n][1] * o[n][1]) + (o[n][2] * o[n][2] + o[n][3] * o[n][3]); }
;                 if (MODE != 2 && MODE != 4) { u32x4 w; w.x = pk2(o[0][0], o[0][1]); w.y = pk2(o[0][2], o[0][3]); w.z = pk2(o[1][0], o[1][1]); w.w = pk2(o[1][2], o[1][3]); *(u32x4*)(xb + off + bj * HALF) = w; } }
;             if (MODE != 2 && MODE != 4 && rsq) { ss += __shfl_xor(ss, 16); ss += __shfl_xor(ss, 32); if (fq == 0) rsq[(size_t)row * 64 + u.pn * 4 + wc] = ss; }
.LBB0_802:
	v_lshlrev_b32_e32 v110, 16, v122
	v_and_b32_e32 v111, 0xffff0000, v122
	v_lshlrev_b32_e32 v112, 16, v123
	v_and_b32_e32 v113, 0xffff0000, v123
	v_pk_add_f32 v[86:87], v[86:87], v[112:113]
	v_pk_add_f32 v[84:85], v[84:85], v[110:111]
	v_lshlrev_b32_e32 v110, 16, v124
	v_and_b32_e32 v111, 0xffff0000, v124
	v_lshlrev_b32_e32 v112, 16, v125
	v_and_b32_e32 v113, 0xffff0000, v125
	v_pk_add_f32 v[82:83], v[82:83], v[112:113]
	v_pk_add_f32 v[80:81], v[80:81], v[110:111]
	v_cvt_pk_bf16_f32 v110, v84, v85
	v_cvt_pk_bf16_f32 v111, v86, v87
	v_cvt_pk_bf16_f32 v112, v80, v81
	v_cvt_pk_bf16_f32 v113, v82, v83
	s_and_b64 vcc, exec, s[10:11]
	global_store_dwordx4 v[174:175], v[110:113], off offset:256 sc0 sc1
	s_cbranch_vccnz .LBB0_806
	v_mul_f32_e32 v93, v93, v93
	v_mul_f32_e32 v89, v89, v89
	v_mul_f32_e32 v81, v81, v81
	v_fmac_f32_e32 v93, v92, v92
	v_mul_f32_e32 v92, v95, v95
	v_fmac_f32_e32 v89, v88, v88
	v_mul_f32_e32 v88, v91, v91
	v_mul_f32_e32 v85, v85, v85
	v_fmac_f32_e32 v81, v80, v80
	v_mul_f32_e32 v80, v83, v83
	v_fmac_f32_e32 v92, v94, v94
	v_fmac_f32_e32 v88, v90, v90
	v_fmac_f32_e32 v85, v84, v84
	v_mul_f32_e32 v84, v87, v87
	v_fmac_f32_e32 v80, v82, v82
	v_and_b32_e32 v82, 64, v251
	v_add_f32_e32 v92, v93, v92
	v_add_f32_e32 v88, v89, v88
	v_fmac_f32_e32 v84, v86, v86
	v_add_f32_e32 v80, v81, v80
	v_xor_b32_e32 v81, 16, v251
	v_add_u32_e32 v82, 64, v82
	v_add_f32_e32 v88, v92, v88
	v_add_f32_e32 v84, v85, v84
	v_cmp_lt_i32_e32 vcc, v81, v82
	v_add_f32_e32 v84, v88, v84
	v_add_f32_e32 v80, v84, v80
	v_cndmask_b32_e32 v81, v251, v81, vcc
	v_lshlrev_b32_e32 v81, 2, v81
	ds_bpermute_b32 v81, v81, v80
	s_waitcnt lgkmcnt(0)
	v_add_f32_e32 v80, v80, v81
	v_xor_b32_e32 v81, 32, v251
	v_cmp_lt_i32_e32 vcc, v81, v82
	s_nop 1
	v_cndmask_b32_e32 v81, v251, v81, vcc
	v_lshlrev_b32_e32 v81, 2, v81
	ds_bpermute_b32 v81, v81, v80
	s_and_saveexec_b64 s[16:17], s[4:5]
	s_cbranch_execz .LBB0_805
	v_lshlrev_b64 v[82:83], 8, v[172:173]
	v_lshl_add_u64 v[82:83], s[62:63], 0, v[82:83]
	v_lshl_add_u64 v[82:83], s[78:79], 2, v[82:83]
	s_lshl_b32 s18, s28, 2
	v_lshl_add_u64 v[82:83], v[82:83], 0, s[18:19]
	s_waitcnt lgkmcnt(0)
	v_add_f32_e32 v80, v80, v81
	global_store_dword v[82:83], v80, off

; __device__ __forceinline__ unsigned pk2(float lo, float hi) { f32x2 v = {lo, hi}; bf16x2_t b = __builtin_convertvector(v, bf16x2_t); return __builtin_bit_cast(unsigned, b); }
; __device__ __forceinline__ float bflo(unsigned w) { return __uint_as_float(w << 16); }
; __device__ __forceinline__ float bfhi(unsigned w) { return __uint_as_float(w & 0xffff0000u); }
;     __device__ __forceinline__ void operator()(const f32x4 (&acc)[2][2][4][2], const Unit& u, int wr, int wc, int fr, int fq) const {
;     ...
;         for (int j = 0; j < 8; ++j) { const int ai = j >> 2, m = j & 3; const int row = row0 + ai * HALF + m * 16; const size_t off = (size_t)row * DM + col0; float ss = 0.f;
;             if (MODE < 3 && j < 6) ldgrp(nx2, (size_t)(row0 + ((j + 2) >> 2) * HALF + ((j + 2) & 3) * 16) * DM + col0);
; #pragma unroll
;             for (int bj = 0; bj < 2; ++bj) { f32x4 o[2];
; #pragma unroll
;                 for (int n = 0; n < 2; ++n) { const int cc = bj * HALF + 4 * n;
;                     f32x4 v = acc[ai][bj][m][n];
;                     if (bias) { v = (v + *(const f32x4*)(bias + col0 + cc)) * *(const f32x4*)(scale + col0 + cc); }
;                     f32x4 b;
;                     if (MODE >= 3) b = (f32x4){0.f, 0.f, 0.f, 0.f};
;                     else if (MODE == 0) b = __builtin_bit_cast(f32x4, cur[bj][n]);
;                     else { const unsigned w0 = n ? cur[bj][0].z : cur[bj][0].x, w1 = n ? cur[bj][0].w : cur[bj][0].y; b = (f32x4){bflo(w0), bfhi(w0), bflo(w1), bfhi(w1)}; }
;                     o[n] = b + v;
;                     if (MODE == 2 || MODE == 4) *(f32x4*)(out + off + cc) = o[n];
;                     ss += (o[n][0] * o[n][0] + o[n][1] * o[n][1]) + (o[n][2] * o[n][2] + o[n][3] * o[n][3]); }
;                 if (MODE != 2 && MODE != 4) { u32x4 w; w.x = pk2(o[0][0], o[0][1]); w.y = pk2(o[0][2], o[0][3]); w.z = pk2(o[1][0], o[1][1]); w.w = pk2(o[1][2], o[1][3]); *(u32x4*)(xb + off + bj * HALF) = w; } }
.LBB0_810:
	s_waitcnt vmcnt(9)
	v_lshlrev_b32_e32 v90, 16, v118
	v_and_b32_e32 v91, 0xffff0000, v118
	v_lshlrev_b32_e32 v92, 16, v119
	v_and_b32_e32 v93, 0xffff0000, v119
	v_pk_add_f32 v[78:79], v[78:79], v[92:93]
	v_pk_add_f32 v[76:77], v[76:77], v[90:91]
	v_lshlrev_b32_e32 v90, 16, v120
	v_and_b32_e32 v91, 0xffff0000, v120
	v_lshlrev_b32_e32 v92, 16, v121
	v_and_b32_e32 v93, 0xffff0000, v121
	v_pk_add_f32 v[74:75], v[74:75], v[92:93]
	v_pk_add_f32 v[72:73], v[72:73], v[90:91]
	v_cvt_pk_bf16_f32 v90, v76, v77
	v_cvt_pk_bf16_f32 v91, v78, v79
	v_cvt_pk_bf16_f32 v92, v72, v73
	v_cvt_pk_bf16_f32 v93, v74, v75
	s_and_b64 vcc, exec, s[8:9]
	global_store_dwordx4 v[128:129], v[90:93], off sc0 sc1
	s_cbranch_vccnz .LBB0_812
	global_load_dwordx4 v[90:93], v[166:167], off offset:512
	s_waitcnt vmcnt(0)
	v_pk_add_f32 v[92:93], v[70:71], v[92:93]
	v_pk_add_f32 v[90:91], v[68:69], v[90:91]
	global_load_dwordx4 v[68:71], v[164:165], off offset:512
	s_waitcnt vmcnt(0)
	v_pk_mul_f32 v[70:71], v[92:93], v[70:71]
	v_pk_mul_f32 v[68:69], v[90:91], v[68:69]

; __device__ __forceinline__ unsigned pk2(float lo, float hi) { f32x2 v = {lo, hi}; bf16x2_t b = __builtin_convertvector(v, bf16x2_t); return __builtin_bit_cast(unsigned, b); }
; __device__ __forceinline__ float bflo(unsigned w) { return __uint_as_float(w << 16); }
; __device__ __forceinline__ float bfhi(unsigned w) { return __uint_as_float(w & 0xffff0000u); }
;     __device__ __forceinline__ void operator()(const f32x4 (&acc)[2][2][4][2], const Unit& u, int wr, int wc, int fr, int fq) const {
;     ...
;         for (int j = 0; j < 8; ++j) { const int ai = j >> 2, m = j & 3; const int row = row0 + ai * HALF + m * 16; const size_t off = (size_t)row * DM + col0; float ss = 0.f;
;             if (MODE < 3 && j < 6) ldgrp(nx2, (size_t)(row0 + ((j + 2) >> 2) * HALF + ((j + 2) & 3) * 16) * DM + col0);
; #pragma unroll
;             for (int bj = 0; bj < 2; ++bj) { f32x4 o[2];
; #pragma unroll
;                 for (int n = 0; n < 2; ++n) { const int cc = bj * HALF + 4 * n;
;                     f32x4 v = acc[ai][bj][m][n];
;                     if (bias) { v = (v + *(const f32x4*)(bias + col0 + cc)) * *(const f32x4*)(scale + col0 + cc); }
;                     f32x4 b;
;                     if (MODE >= 3) b = (f32x4){0.f, 0.f, 0.f, 0.f};
;                     else if (MODE == 0) b = __builtin_bit_cast(f32x4, cur[bj][n]);
;                     else { const unsigned w0 = n ? cur[bj][0].z : cur[bj][0].x, w1 = n ? cur[bj][0].w : cur[bj][0].y; b = (f32x4){bflo(w0), bfhi(w0), bflo(w1), bfhi(w1)}; }
;                     o[n] = b + v;
;                     if (MODE == 2 || MODE == 4) *(f32x4*)(out + off + cc) = o[n];
;                     ss += (o[n][0] * o[n][0] + o[n][1] * o[n][1]) + (o[n][2] * o[n][2] + o[n][3] * o[n][3]); }
;                 if (MODE != 2 && MODE != 4) { u32x4 w; w.x = pk2(o[0][0], o[0][1]); w.y = pk2(o[0][2], o[0][3]); w.z = pk2(o[1][0], o[1][1]); w.w = pk2(o[1][2], o[1][3]); *(u32x4*)(xb + off + bj * HALF) = w; } }
;             if (MODE != 2 && MODE != 4 && rsq) { ss += __shfl_xor(ss, 16); ss += __shfl_xor(ss, 32); if (fq == 0) rsq[(size_t)row * 64 + u.pn * 4 + wc] = ss; }
.LBB0_814:
	s_waitcnt vmcnt(9)
	v_lshlrev_b32_e32 v90, 16, v114
	v_and_b32_e32 v91, 0xffff0000, v114
	v_lshlrev_b32_e32 v92, 16, v115
	v_and_b32_e32 v93, 0xffff0000, v115
	v_pk_add_f32 v[70:71], v[70:71], v[92:93]
	v_pk_add_f32 v[68:69], v[68:69], v[90:91]
	v_lshlrev_b32_e32 v90, 16, v116
	v_and_b32_e32 v91, 0xffff0000, v116
	v_lshlrev_b32_e32 v92, 16, v117
	v_and_b32_e32 v93, 0xffff0000, v117
	v_pk_add_f32 v[66:67], v[66:67], v[92:93]
	v_pk_add_f32 v[64:65], v[64:65], v[90:91]
	v_cvt_pk_bf16_f32 v90, v68, v69
	v_cvt_pk_bf16_f32 v91, v70, v71
	v_cvt_pk_bf16_f32 v92, v64, v65
	v_cvt_pk_bf16_f32 v93, v66, v67
	s_and_b64 vcc, exec, s[10:11]
	global_store_dwordx4 v[128:129], v[90:93], off offset:256 sc0 sc1
	s_cbranch_vccnz .LBB0_818
	v_mul_f32_e32 v77, v77, v77
	v_mul_f32_e32 v73, v73, v73
	v_mul_f32_e32 v65, v65, v65
	v_fmac_f32_e32 v77, v76, v76
	v_mul_f32_e32 v76, v79, v79
	v_fmac_f32_e32 v73, v72, v72
	v_mul_f32_e32 v72, v75, v75
	v_mul_f32_e32 v69, v69, v69
	v_fmac_f32_e32 v65, v64, v64
	v_mul_f32_e32 v64, v67, v67
	v_fmac_f32_e32 v76, v78, v78
	v_fmac_f32_e32 v72, v74, v74
	v_fmac_f32_e32 v69, v68, v68
	v_mul_f32_e32 v68, v71, v71
	v_fmac_f32_e32 v64, v66, v66
	v_and_b32_e32 v66, 64, v251
	v_add_f32_e32 v76, v77, v76
	v_add_f32_e32 v72, v73, v72
	v_fmac_f32_e32 v68, v70, v70
	v_add_f32_e32 v64, v65, v64
	v_xor_b32_e32 v65, 16, v251
	v_add_u32_e32 v66, 64, v66
	v_add_f32_e32 v72, v76, v72
	v_add_f32_e32 v68, v69, v68
	v_cmp_lt_i32_e32 vcc, v65, v66
	v_add_f32_e32 v68, v72, v68
	v_add_f32_e32 v64, v68, v64
	v_cndmask_b32_e32 v65, v251, v65, vcc
	v_lshlrev_b32_e32 v65, 2, v65
	ds_bpermute_b32 v65, v65, v64
	s_waitcnt lgkmcnt(0)
	v_add_f32_e32 v64, v64, v65
	v_xor_b32_e32 v65, 32, v251
	v_cmp_lt_i32_e32 vcc, v65, v66
	s_nop 1
	v_cndmask_b32_e32 v65, v251, v65, vcc
	v_lshlrev_b32_e32 v65, 2, v65
	ds_bpermute_b32 v65, v65, v64
	s_and_saveexec_b64 s[16:17], s[4:5]
	s_cbranch_execz .LBB0_817
	v_lshlrev_b64 v[66:67], 8, v[126:127]
	v_lshl_add_u64 v[66:67], s[62:63], 0, v[66:67]
	v_lshl_add_u64 v[66:67], s[78:79], 2, v[66:67]
	s_lshl_b32 s18, s28, 2
	v_lshl_add_u64 v[66:67], v[66:67], 0, s[18:19]
	s_waitcnt lgkmcnt(0)
	v_add_f32_e32 v64, v64, v65
	global_store_dword v[66:67], v64, off

; __device__ __forceinline__ unsigned pk2(float lo, float hi) { f32x2 v = {lo, hi}; bf16x2_t b = __builtin_convertvector(v, bf16x2_t); return __builtin_bit_cast(unsigned, b); }
; __device__ __forceinline__ float bflo(unsigned w) { return __uint_as_float(w << 16); }
; __device__ __forceinline__ float bfhi(unsigned w) { return __uint_as_float(w & 0xffff0000u); }
;     __device__ __forceinline__ void operator()(const f32x4 (&acc)[2][2][4][2], const Unit& u, int wr, int wc, int fr, int fq) const {
;     ...
;         for (int j = 0; j < 8; ++j) { const int ai = j >> 2, m = j & 3; const int row = row0 + ai * HALF + m * 16; const size_t off = (size_t)row * DM + col0; float ss = 0.f;
;             if (MODE < 3 && j < 6) ldgrp(nx2, (size_t)(row0 + ((j + 2) >> 2) * HALF + ((j + 2) & 3) * 16) * DM + col0);
; #pragma unroll
;             for (int bj = 0; bj < 2; ++bj) { f32x4 o[2];
; #pragma unroll
;                 for (int n = 0; n < 2; ++n) { const int cc = bj * HALF + 4 * n;
;                     f32x4 v = acc[ai][bj][m][n];
;                     if (bias) { v = (v + *(const f32x4*)(bias + col0 + cc)) * *(const f32x4*)(scale + col0 + cc); }
;                     f32x4 b;
;                     if (MODE >= 3) b = (f32x4){0.f, 0.f, 0.f, 0.f};
;                     else if (MODE == 0) b = __builtin_bit_cast(f32x4, cur[bj][n]);
;                     else { const unsigned w0 = n ? cur[bj][0].z : cur[bj][0].x, w1 = n ? cur[bj][0].w : cur[bj][0].y; b = (f32x4){bflo(w0), bfhi(w0), bflo(w1), bfhi(w1)}; }
;                     o[n] = b + v;
;                     if (MODE == 2 || MODE == 4) *(f32x4*)(out + off + cc) = o[n];
;                     ss += (o[n][0] * o[n][0] + o[n][1] * o[n][1]) + (o[n][2] * o[n][2] + o[n][3] * o[n][3]); }
;                 if (MODE != 2 && MODE != 4) { u32x4 w; w.x = pk2(o[0][0], o[0][1]); w.y = pk2(o[0][2], o[0][3]); w.z = pk2(o[1][0], o[1][1]); w.w = pk2(o[1][2], o[1][3]); *(u32x4*)(xb + off + bj * HALF) = w; } }
.LBB0_822:
	s_waitcnt vmcnt(9)
	v_lshlrev_b32_e32 v76, 16, v102
	v_and_b32_e32 v77, 0xffff0000, v102
	v_lshlrev_b32_e32 v78, 16, v103
	v_and_b32_e32 v79, 0xffff0000, v103
	v_pk_add_f32 v[62:63], v[62:63], v[78:79]
	v_pk_add_f32 v[60:61], v[60:61], v[76:77]
	v_lshlrev_b32_e32 v76, 16, v104
	v_and_b32_e32 v77, 0xffff0000, v104
	v_lshlrev_b32_e32 v78, 16, v105
	v_and_b32_e32 v79, 0xffff0000, v105
	v_pk_add_f32 v[58:59], v[58:59], v[78:79]
	v_pk_add_f32 v[56:57], v[56:57], v[76:77]
	v_cvt_pk_bf16_f32 v76, v60, v61
	v_cvt_pk_bf16_f32 v77, v62, v63
	v_cvt_pk_bf16_f32 v78, v56, v57
	v_cvt_pk_bf16_f32 v79, v58, v59
	s_and_b64 vcc, exec, s[8:9]
	global_store_dwordx4 v[108:109], v[76:79], off sc0 sc1
	s_cbranch_vccnz .LBB0_824
	global_load_dwordx4 v[76:79], v[166:167], off offset:512
	s_waitcnt vmcnt(0)
	v_pk_add_f32 v[78:79], v[54:55], v[78:79]
	v_pk_add_f32 v[76:77], v[52:53], v[76:77]
	global_load_dwordx4 v[52:55], v[164:165], off offset:512
	s_waitcnt vmcnt(0)
	v_pk_mul_f32 v[54:55], v[78:79], v[54:55]
	v_pk_mul_f32 v[52:53], v[76:77], v[52:53]

; __device__ __forceinline__ unsigned pk2(float lo, float hi) { f32x2 v = {lo, hi}; bf16x2_t b = __builtin_convertvector(v, bf16x2_t); return __builtin_bit_cast(unsigned, b); }
; __device__ __forceinline__ float bflo(unsigned w) { return __uint_as_float(w << 16); }
; __device__ __forceinline__ float bfhi(unsigned w) { return __uint_as_float(w & 0xffff0000u); }
;     __device__ __forceinline__ void operator()(const f32x4 (&acc)[2][2][4][2], const Unit& u, int wr, int wc, int fr, int fq) const {
;     ...
;         for (int j = 0; j < 8; ++j) { const int ai = j >> 2, m = j & 3; const int row = row0 + ai * HALF + m * 16; const size_t off = (size_t)row * DM + col0; float ss = 0.f;
;             if (MODE < 3 && j < 6) ldgrp(nx2, (size_t)(row0 + ((j + 2) >> 2) * HALF + ((j + 2) & 3) * 16) * DM + col0);
; #pragma unroll
;             for (int bj = 0; bj < 2; ++bj) { f32x4 o[2];
; #pragma unroll
;                 for (int n = 0; n < 2; ++n) { const int cc = bj * HALF + 4 * n;
;                     f32x4 v = acc[ai][bj][m][n];
;                     if (bias) { v = (v + *(const f32x4*)(bias + col0 + cc)) * *(const f32x4*)(scale + col0 + cc); }
;                     f32x4 b;
;                     if (MODE >= 3) b = (f32x4){0.f, 0.f, 0.f, 0.f};
;                     else if (MODE == 0) b = __builtin_bit_cast(f32x4, cur[bj][n]);
;                     else { const unsigned w0 = n ? cur[bj][0].z : cur[bj][0].x, w1 = n ? cur[bj][0].w : cur[bj][0].y; b = (f32x4){bflo(w0), bfhi(w0), bflo(w1), bfhi(w1)}; }
;                     o[n] = b + v;
;                     if (MODE == 2 || MODE == 4) *(f32x4*)(out + off + cc) = o[n];
;                     ss += (o[n][0] * o[n][0] + o[n][1] * o[n][1]) + (o[n][2] * o[n][2] + o[n][3] * o[n][3]); }
;                 if (MODE != 2 && MODE != 4) { u32x4 w; w.x = pk2(o[0][0], o[0][1]); w.y = pk2(o[0][2], o[0][3]); w.z = pk2(o[1][0], o[1][1]); w.w = pk2(o[1][2], o[1][3]); *(u32x4*)(xb + off + bj * HALF) = w; } }
;             if (MODE != 2 && MODE != 4 && rsq) { ss += __shfl_xor(ss, 16); ss += __shfl_xor(ss, 32); if (fq == 0) rsq[(size_t)row * 64 + u.pn * 4 + wc] = ss; }
.LBB0_826:
	s_waitcnt vmcnt(9)
	v_lshlrev_b32_e32 v76, 16, v98
	v_and_b32_e32 v77, 0xffff0000, v98
	v_lshlrev_b32_e32 v78, 16, v99
	v_and_b32_e32 v79, 0xffff0000, v99
	v_pk_add_f32 v[54:55], v[54:55], v[78:79]
	v_pk_add_f32 v[52:53], v[52:53], v[76:77]
	v_lshlrev_b32_e32 v76, 16, v100
	v_and_b32_e32 v77, 0xffff0000, v100
	v_lshlrev_b32_e32 v78, 16, v101
	v_and_b32_e32 v79, 0xffff0000, v101
	v_pk_add_f32 v[50:51], v[50:51], v[78:79]
	v_pk_add_f32 v[48:49], v[48:49], v[76:77]
	v_cvt_pk_bf16_f32 v76, v52, v53
	v_cvt_pk_bf16_f32 v77, v54, v55
	v_cvt_pk_bf16_f32 v78, v48, v49
	v_cvt_pk_bf16_f32 v79, v50, v51
	s_and_b64 vcc, exec, s[10:11]
	global_store_dwordx4 v[108:109], v[76:79], off offset:256 sc0 sc1
	s_cbranch_vccnz .LBB0_830
	v_mul_f32_e32 v61, v61, v61
	v_mul_f32_e32 v57, v57, v57
	v_mul_f32_e32 v49, v49, v49
	v_fmac_f32_e32 v61, v60, v60
	v_mul_f32_e32 v60, v63, v63
	v_fmac_f32_e32 v57, v56, v56
	v_mul_f32_e32 v56, v59, v59
	v_mul_f32_e32 v53, v53, v53
	v_fmac_f32_e32 v49, v48, v48
	v_mul_f32_e32 v48, v51, v51
	v_fmac_f32_e32 v60, v62, v62
	v_fmac_f32_e32 v56, v58, v58
	v_fmac_f32_e32 v53, v52, v52
	v_mul_f32_e32 v52, v55, v55
	v_fmac_f32_e32 v48, v50, v50
	v_and_b32_e32 v50, 64, v251
	v_add_f32_e32 v60, v61, v60
	v_add_f32_e32 v56, v57, v56
	v_fmac_f32_e32 v52, v54, v54
	v_add_f32_e32 v48, v49, v48
	v_xor_b32_e32 v49, 16, v251
	v_add_u32_e32 v50, 64, v50
	v_add_f32_e32 v56, v60, v56
	v_add_f32_e32 v52, v53, v52
	v_cmp_lt_i32_e32 vcc, v49, v50
	v_add_f32_e32 v52, v56, v52
	v_add_f32_e32 v48, v52, v48
	v_cndmask_b32_e32 v49, v251, v49, vcc
	v_lshlrev_b32_e32 v49, 2, v49
	ds_bpermute_b32 v49, v49, v48
	s_waitcnt lgkmcnt(0)
	v_add_f32_e32 v48, v48, v49
	v_xor_b32_e32 v49, 32, v251
	v_cmp_lt_i32_e32 vcc, v49, v50
	s_nop 1
	v_cndmask_b32_e32 v49, v251, v49, vcc
	v_lshlrev_b32_e32 v49, 2, v49
	ds_bpermute_b32 v49, v49, v48
	s_and_saveexec_b64 s[16:17], s[4:5]
	s_cbranch_execz .LBB0_829
	v_lshlrev_b64 v[50:51], 8, v[106:107]
	v_lshl_add_u64 v[50:51], s[62:63], 0, v[50:51]
	v_lshl_add_u64 v[50:51], s[78:79], 2, v[50:51]
	s_lshl_b32 s18, s28, 2
	v_lshl_add_u64 v[50:51], v[50:51], 0, s[18:19]
	s_waitcnt lgkmcnt(0)
	v_add_f32_e32 v48, v48, v49
	global_store_dword v[50:51], v48, off

; __device__ __forceinline__ unsigned pk2(float lo, float hi) { f32x2 v = {lo, hi}; bf16x2_t b = __builtin_convertvector(v, bf16x2_t); return __builtin_bit_cast(unsigned, b); }
; __device__ __forceinline__ float bflo(unsigned w) { return __uint_as_float(w << 16); }
; __device__ __forceinline__ float bfhi(unsigned w) { return __uint_as_float(w & 0xffff0000u); }
;     __device__ __forceinline__ void operator()(const f32x4 (&acc)[2][2][4][2], const Unit& u, int wr, int wc, int fr, int fq) const {
;     ...
;         for (int j = 0; j < 8; ++j) { const int ai = j >> 2, m = j & 3; const int row = row0 + ai * HALF + m * 16; const size_t off = (size_t)row * DM + col0; float ss = 0.f;
;             if (MODE < 3 && j < 6) ldgrp(nx2, (size_t)(row0 + ((j + 2) >> 2) * HALF + ((j + 2) & 3) * 16) * DM + col0);
; #pragma unroll
;             for (int bj = 0; bj < 2; ++bj) { f32x4 o[2];
; #pragma unroll
;                 for (int n = 0; n < 2; ++n) { const int cc = bj * HALF + 4 * n;
;                     f32x4 v = acc[ai][bj][m][n];
;                     if (bias) { v = (v + *(const f32x4*)(bias + col0 + cc)) * *(const f32x4*)(scale + col0 + cc); }
;                     f32x4 b;
;                     if (MODE >= 3) b = (f32x4){0.f, 0.f, 0.f, 0.f};
;                     else if (MODE == 0) b = __builtin_bit_cast(f32x4, cur[bj][n]);
;                     else { const unsigned w0 = n ? cur[bj][0].z : cur[bj][0].x, w1 = n ? cur[bj][0].w : cur[bj][0].y; b = (f32x4){bflo(w0), bfhi(w0), bflo(w1), bfhi(w1)}; }
;                     o[n] = b + v;
;                     if (MODE == 2 || MODE == 4) *(f32x4*)(out + off + cc) = o[n];
;                     ss += (o[n][0] * o[n][0] + o[n][1] * o[n][1]) + (o[n][2] * o[n][2] + o[n][3] * o[n][3]); }
;                 if (MODE != 2 && MODE != 4) { u32x4 w; w.x = pk2(o[0][0], o[0][1]); w.y = pk2(o[0][2], o[0][3]); w.z = pk2(o[1][0], o[1][1]); w.w = pk2(o[1][2], o[1][3]); *(u32x4*)(xb + off + bj * HALF) = w; } }
.LBB0_834:
	s_waitcnt vmcnt(9)
	v_lshlrev_b32_e32 v60, 16, v84
	v_and_b32_e32 v61, 0xffff0000, v84
	v_lshlrev_b32_e32 v62, 16, v85
	v_and_b32_e32 v63, 0xffff0000, v85
	v_pk_add_f32 v[46:47], v[46:47], v[62:63]
	v_pk_add_f32 v[44:45], v[44:45], v[60:61]
	v_lshlrev_b32_e32 v60, 16, v86
	v_and_b32_e32 v61, 0xffff0000, v86
	v_lshlrev_b32_e32 v62, 16, v87
	v_and_b32_e32 v63, 0xffff0000, v87
	v_pk_add_f32 v[42:43], v[42:43], v[62:63]
	v_pk_add_f32 v[40:41], v[40:41], v[60:61]
	v_cvt_pk_bf16_f32 v60, v44, v45
	v_cvt_pk_bf16_f32 v61, v46, v47
	v_cvt_pk_bf16_f32 v62, v40, v41
	v_cvt_pk_bf16_f32 v63, v42, v43
	s_and_b64 vcc, exec, s[8:9]
	global_store_dwordx4 v[88:89], v[60:63], off sc0 sc1
	s_cbranch_vccnz .LBB0_836
	global_load_dwordx4 v[60:63], v[166:167], off offset:512
	s_waitcnt vmcnt(0)
	v_pk_add_f32 v[62:63], v[38:39], v[62:63]
	v_pk_add_f32 v[60:61], v[36:37], v[60:61]
	global_load_dwordx4 v[36:39], v[164:165], off offset:512
	s_waitcnt vmcnt(0)
	v_pk_mul_f32 v[38:39], v[62:63], v[38:39]
	v_pk_mul_f32 v[36:37], v[60:61], v[36:37]

; __device__ __forceinline__ unsigned pk2(float lo, float hi) { f32x2 v = {lo, hi}; bf16x2_t b = __builtin_convertvector(v, bf16x2_t); return __builtin_bit_cast(unsigned, b); }
; __device__ __forceinline__ float bflo(unsigned w) { return __uint_as_float(w << 16); }
; __device__ __forceinline__ float bfhi(unsigned w) { return __uint_as_float(w & 0xffff0000u); }
;     __device__ __forceinline__ void operator()(const f32x4 (&acc)[2][2][4][2], const Unit& u, int wr, int wc, int fr, int fq) const {
;     ...
;         for (int j = 0; j < 8; ++j) { const int ai = j >> 2, m = j & 3; const int row = row0 + ai * HALF + m * 16; const size_t off = (size_t)row * DM + col0; float ss = 0.f;
;             if (MODE < 3 && j < 6) ldgrp(nx2, (size_t)(row0 + ((j + 2) >> 2) * HALF + ((j + 2) & 3) * 16) * DM + col0);
; #pragma unroll
;             for (int bj = 0; bj < 2; ++bj) { f32x4 o[2];
; #pragma unroll
;                 for (int n = 0; n < 2; ++n) { const int cc = bj * HALF + 4 * n;
;                     f32x4 v = acc[ai][bj][m][n];
;                     if (bias) { v = (v + *(const f32x4*)(bias + col0 + cc)) * *(const f32x4*)(scale + col0 + cc); }
;                     f32x4 b;
;                     if (MODE >= 3) b = (f32x4){0.f, 0.f, 0.f, 0.f};
;                     else if (MODE == 0) b = __builtin_bit_cast(f32x4, cur[bj][n]);
;                     else { const unsigned w0 = n ? cur[bj][0].z : cur[bj][0].x, w1 = n ? cur[bj][0].w : cur[bj][0].y; b = (f32x4){bflo(w0), bfhi(w0), bflo(w1), bfhi(w1)}; }
;                     o[n] = b + v;
;                     if (MODE == 2 || MODE == 4) *(f32x4*)(out + off + cc) = o[n];
;                     ss += (o[n][0] * o[n][0] + o[n][1] * o[n][1]) + (o[n][2] * o[n][2] + o[n][3] * o[n][3]); }
;                 if (MODE != 2 && MODE != 4) { u32x4 w; w.x = pk2(o[0][0], o[0][1]); w.y = pk2(o[0][2], o[0][3]); w.z = pk2(o[1][0], o[1][1]); w.w = pk2(o[1][2], o[1][3]); *(u32x4*)(xb + off + bj * HALF) = w; } }
;             if (MODE != 2 && MODE != 4 && rsq) { ss += __shfl_xor(ss, 16); ss += __shfl_xor(ss, 32); if (fq == 0) rsq[(size_t)row * 64 + u.pn * 4 + wc] = ss; }
.LBB0_838:
	s_waitcnt vmcnt(9)
	v_lshlrev_b32_e32 v60, 16, v80
	v_and_b32_e32 v61, 0xffff0000, v80
	v_lshlrev_b32_e32 v62, 16, v81
	v_and_b32_e32 v63, 0xffff0000, v81
	v_pk_add_f32 v[38:39], v[38:39], v[62:63]
	v_pk_add_f32 v[36:37], v[36:37], v[60:61]
	v_lshlrev_b32_e32 v60, 16, v82
	v_and_b32_e32 v61, 0xffff0000, v82
	v_lshlrev_b32_e32 v62, 16, v83
	v_and_b32_e32 v63, 0xffff0000, v83
	v_pk_add_f32 v[34:35], v[34:35], v[62:63]
	v_pk_add_f32 v[32:33], v[32:33], v[60:61]
	v_cvt_pk_bf16_f32 v60, v36, v37
	v_cvt_pk_bf16_f32 v61, v38, v39
	v_cvt_pk_bf16_f32 v62, v32, v33
	v_cvt_pk_bf16_f32 v63, v34, v35
	s_and_b64 vcc, exec, s[10:11]
	global_store_dwordx4 v[88:89], v[60:63], off offset:256 sc0 sc1
	s_cbranch_vccnz .LBB0_842
	v_mul_f32_e32 v45, v45, v45
	v_mul_f32_e32 v41, v41, v41
	v_mul_f32_e32 v33, v33, v33
	v_fmac_f32_e32 v45, v44, v44
	v_mul_f32_e32 v44, v47, v47
	v_fmac_f32_e32 v41, v40, v40
	v_mul_f32_e32 v40, v43, v43
	v_mul_f32_e32 v37, v37, v37
	v_fmac_f32_e32 v33, v32, v32
	v_mul_f32_e32 v32, v35, v35
	v_fmac_f32_e32 v44, v46, v46
	v_fmac_f32_e32 v40, v42, v42
	v_fmac_f32_e32 v37, v36, v36
	v_mul_f32_e32 v36, v39, v39
	v_fmac_f32_e32 v32, v34, v34
	v_and_b32_e32 v34, 64, v251
	v_add_f32_e32 v44, v45, v44
	v_add_f32_e32 v40, v41, v40
	v_fmac_f32_e32 v36, v38, v38
	v_add_f32_e32 v32, v33, v32
	v_xor_b32_e32 v33, 16, v251
	v_add_u32_e32 v34, 64, v34
	v_add_f32_e32 v40, v44, v40
	v_add_f32_e32 v36, v37, v36
	v_cmp_lt_i32_e32 vcc, v33, v34
	v_add_f32_e32 v36, v40, v36
	v_add_f32_e32 v32, v36, v32
	v_cndmask_b32_e32 v33, v251, v33, vcc
	v_lshlrev_b32_e32 v33, 2, v33
	ds_bpermute_b32 v33, v33, v32
	s_waitcnt lgkmcnt(0)
	v_add_f32_e32 v32, v32, v33
	v_xor_b32_e32 v33, 32, v251
	v_cmp_lt_i32_e32 vcc, v33, v34
	s_nop 1
	v_cndmask_b32_e32 v33, v251, v33, vcc
	v_lshlrev_b32_e32 v33, 2, v33
	ds_bpermute_b32 v33, v33, v32
	s_and_saveexec_b64 s[16:17], s[4:5]
	s_cbranch_execz .LBB0_841
	v_or_b32_e32 v34, 16, v106
	v_ashrrev_i32_e32 v35, 31, v34
	v_lshlrev_b64 v[34:35], 8, v[34:35]
	v_lshl_add_u64 v[34:35], s[62:63], 0, v[34:35]
	v_lshl_add_u64 v[34:35], s[78:79], 2, v[34:35]
	s_lshl_b32 s18, s28, 2
	v_lshl_add_u64 v[34:35], v[34:35], 0, s[18:19]
	s_waitcnt lgkmcnt(0)
	v_add_f32_e32 v32, v32, v33
	global_store_dword v[34:35], v32, off

; __device__ __forceinline__ unsigned pk2(float lo, float hi) { f32x2 v = {lo, hi}; bf16x2_t b = __builtin_convertvector(v, bf16x2_t); return __builtin_bit_cast(unsigned, b); }
; __device__ __forceinline__ float bflo(unsigned w) { return __uint_as_float(w << 16); }
; __device__ __forceinline__ float bfhi(unsigned w) { return __uint_as_float(w & 0xffff0000u); }
;     __device__ __forceinline__ void operator()(const f32x4 (&acc)[2][2][4][2], const Unit& u, int wr, int wc, int fr, int fq) const {
;     ...
;         for (int j = 0; j < 8; ++j) { const int ai = j >> 2, m = j & 3; const int row = row0 + ai * HALF + m * 16; const size_t off = (size_t)row * DM + col0; float ss = 0.f;
;             if (MODE < 3 && j < 6) ldgrp(nx2, (size_t)(row0 + ((j + 2) >> 2) * HALF + ((j + 2) & 3) * 16) * DM + col0);
; #pragma unroll
;             for (int bj = 0; bj < 2; ++bj) { f32x4 o[2];
; #pragma unroll
;                 for (int n = 0; n < 2; ++n) { const int cc = bj * HALF + 4 * n;
;                     f32x4 v = acc[ai][bj][m][n];
;                     if (bias) { v = (v + *(const f32x4*)(bias + col0 + cc)) * *(const f32x4*)(scale + col0 + cc); }
;                     f32x4 b;
;                     if (MODE >= 3) b = (f32x4){0.f, 0.f, 0.f, 0.f};
;                     else if (MODE == 0) b = __builtin_bit_cast(f32x4, cur[bj][n]);
;                     else { const unsigned w0 = n ? cur[bj][0].z : cur[bj][0].x, w1 = n ? cur[bj][0].w : cur[bj][0].y; b = (f32x4){bflo(w0), bfhi(w0), bflo(w1), bfhi(w1)}; }
;                     o[n] = b + v;
;                     if (MODE == 2 || MODE == 4) *(f32x4*)(out + off + cc) = o[n];
;                     ss += (o[n][0] * o[n][0] + o[n][1] * o[n][1]) + (o[n][2] * o[n][2] + o[n][3] * o[n][3]); }
;                 if (MODE != 2 && MODE != 4) { u32x4 w; w.x = pk2(o[0][0], o[0][1]); w.y = pk2(o[0][2], o[0][3]); w.z = pk2(o[1][0], o[1][1]); w.w = pk2(o[1][2], o[1][3]); *(u32x4*)(xb + off + bj * HALF) = w; } }
.LBB0_846:
	s_waitcnt vmcnt(7)
	v_lshlrev_b32_e32 v32, 16, v68
	s_waitcnt lgkmcnt(0)
	v_and_b32_e32 v33, 0xffff0000, v68
	v_lshlrev_b32_e32 v34, 16, v69
	v_and_b32_e32 v35, 0xffff0000, v69
	v_pk_add_f32 v[30:31], v[30:31], v[34:35]
	v_pk_add_f32 v[28:29], v[28:29], v[32:33]
	v_lshlrev_b32_e32 v32, 16, v70
	v_and_b32_e32 v33, 0xffff0000, v70
	v_lshlrev_b32_e32 v34, 16, v71
	v_and_b32_e32 v35, 0xffff0000, v71
	v_pk_add_f32 v[26:27], v[26:27], v[34:35]
	v_pk_add_f32 v[24:25], v[24:25], v[32:33]
	v_cvt_pk_bf16_f32 v32, v28, v29
	v_cvt_pk_bf16_f32 v33, v30, v31
	v_cvt_pk_bf16_f32 v34, v24, v25
	v_cvt_pk_bf16_f32 v35, v26, v27
	s_and_b64 vcc, exec, s[8:9]
	global_store_dwordx4 v[74:75], v[32:35], off sc0 sc1
	s_cbranch_vccnz .LBB0_848
	global_load_dwordx4 v[32:35], v[166:167], off offset:512
	s_waitcnt vmcnt(0)
	v_pk_add_f32 v[34:35], v[22:23], v[34:35]
	v_pk_add_f32 v[32:33], v[20:21], v[32:33]
	global_load_dwordx4 v[20:23], v[164:165], off offset:512
	s_waitcnt vmcnt(0)
	v_pk_mul_f32 v[22:23], v[34:35], v[22:23]
	v_pk_mul_f32 v[20:21], v[32:33], v[20:21]

; __device__ __forceinline__ unsigned pk2(float lo, float hi) { f32x2 v = {lo, hi}; bf16x2_t b = __builtin_convertvector(v, bf16x2_t); return __builtin_bit_cast(unsigned, b); }
; __device__ __forceinline__ float bflo(unsigned w) { return __uint_as_float(w << 16); }
; __device__ __forceinline__ float bfhi(unsigned w) { return __uint_as_float(w & 0xffff0000u); }
;     __device__ __forceinline__ void operator()(const f32x4 (&acc)[2][2][4][2], const Unit& u, int wr, int wc, int fr, int fq) const {
;     ...
;         for (int j = 0; j < 8; ++j) { const int ai = j >> 2, m = j & 3; const int row = row0 + ai * HALF + m * 16; const size_t off = (size_t)row * DM + col0; float ss = 0.f;
;             if (MODE < 3 && j < 6) ldgrp(nx2, (size_t)(row0 + ((j + 2) >> 2) * HALF + ((j + 2) & 3) * 16) * DM + col0);
; #pragma unroll
;             for (int bj = 0; bj < 2; ++bj) { f32x4 o[2];
; #pragma unroll
;                 for (int n = 0; n < 2; ++n) { const int cc = bj * HALF + 4 * n;
;                     f32x4 v = acc[ai][bj][m][n];
;                     if (bias) { v = (v + *(const f32x4*)(bias + col0 + cc)) * *(const f32x4*)(scale + col0 + cc); }
;                     f32x4 b;
;                     if (MODE >= 3) b = (f32x4){0.f, 0.f, 0.f, 0.f};
;                     else if (MODE == 0) b = __builtin_bit_cast(f32x4, cur[bj][n]);
;                     else { const unsigned w0 = n ? cur[bj][0].z : cur[bj][0].x, w1 = n ? cur[bj][0].w : cur[bj][0].y; b = (f32x4){bflo(w0), bfhi(w0), bflo(w1), bfhi(w1)}; }
;                     o[n] = b + v;
;                     if (MODE == 2 || MODE == 4) *(f32x4*)(out + off + cc) = o[n];
;                     ss += (o[n][0] * o[n][0] + o[n][1] * o[n][1]) + (o[n][2] * o[n][2] + o[n][3] * o[n][3]); }
;                 if (MODE != 2 && MODE != 4) { u32x4 w; w.x = pk2(o[0][0], o[0][1]); w.y = pk2(o[0][2], o[0][3]); w.z = pk2(o[1][0], o[1][1]); w.w = pk2(o[1][2], o[1][3]); *(u32x4*)(xb + off + bj * HALF) = w; } }
;             if (MODE != 2 && MODE != 4 && rsq) { ss += __shfl_xor(ss, 16); ss += __shfl_xor(ss, 32); if (fq == 0) rsq[(size_t)row * 64 + u.pn * 4 + wc] = ss; }
.LBB0_850:
	s_waitcnt vmcnt(7)
	v_lshlrev_b32_e32 v32, 16, v64
	v_and_b32_e32 v33, 0xffff0000, v64
	v_lshlrev_b32_e32 v34, 16, v65
	v_and_b32_e32 v35, 0xffff0000, v65
	v_pk_add_f32 v[22:23], v[22:23], v[34:35]
	v_pk_add_f32 v[20:21], v[20:21], v[32:33]
	v_lshlrev_b32_e32 v32, 16, v66
	v_and_b32_e32 v33, 0xffff0000, v66
	v_lshlrev_b32_e32 v34, 16, v67
	v_and_b32_e32 v35, 0xffff0000, v67
	v_pk_add_f32 v[18:19], v[18:19], v[34:35]
	v_pk_add_f32 v[16:17], v[16:17], v[32:33]
	v_cvt_pk_bf16_f32 v32, v20, v21
	v_cvt_pk_bf16_f32 v33, v22, v23
	v_cvt_pk_bf16_f32 v34, v16, v17
	v_cvt_pk_bf16_f32 v35, v18, v19
	s_and_b64 vcc, exec, s[10:11]
	global_store_dwordx4 v[74:75], v[32:35], off offset:256 sc0 sc1
	s_cbranch_vccnz .LBB0_854
	v_mul_f32_e32 v29, v29, v29
	v_mul_f32_e32 v25, v25, v25
	v_mul_f32_e32 v17, v17, v17
	v_fmac_f32_e32 v29, v28, v28
	v_mul_f32_e32 v28, v31, v31
	v_fmac_f32_e32 v25, v24, v24
	v_mul_f32_e32 v24, v27, v27
	v_mul_f32_e32 v21, v21, v21
	v_fmac_f32_e32 v17, v16, v16
	v_mul_f32_e32 v16, v19, v19
	v_fmac_f32_e32 v28, v30, v30
	v_fmac_f32_e32 v24, v26, v26
	v_fmac_f32_e32 v21, v20, v20
	v_mul_f32_e32 v20, v23, v23
	v_fmac_f32_e32 v16, v18, v18
	v_and_b32_e32 v18, 64, v251
	v_add_f32_e32 v28, v29, v28
	v_add_f32_e32 v24, v25, v24
	v_fmac_f32_e32 v20, v22, v22
	v_add_f32_e32 v16, v17, v16
	v_xor_b32_e32 v17, 16, v251
	v_add_u32_e32 v18, 64, v18
	v_add_f32_e32 v24, v28, v24
	v_add_f32_e32 v20, v21, v20
	v_cmp_lt_i32_e32 vcc, v17, v18
	v_add_f32_e32 v20, v24, v20
	v_add_f32_e32 v16, v20, v16
	v_cndmask_b32_e32 v17, v251, v17, vcc
	v_lshlrev_b32_e32 v17, 2, v17
	ds_bpermute_b32 v17, v17, v16
	s_waitcnt lgkmcnt(0)
	v_add_f32_e32 v16, v16, v17
	v_xor_b32_e32 v17, 32, v251
	v_cmp_lt_i32_e32 vcc, v17, v18
	s_nop 1
	v_cndmask_b32_e32 v17, v251, v17, vcc
	v_lshlrev_b32_e32 v17, 2, v17
	ds_bpermute_b32 v17, v17, v16
	s_and_saveexec_b64 s[16:17], s[4:5]
	s_cbranch_execz .LBB0_853
	v_lshlrev_b64 v[18:19], 8, v[72:73]
	v_lshl_add_u64 v[18:19], s[62:63], 0, v[18:19]
	v_lshl_add_u64 v[18:19], s[78:79], 2, v[18:19]
	s_lshl_b32 s18, s28, 2
	v_lshl_add_u64 v[18:19], v[18:19], 0, s[18:19]
	s_waitcnt lgkmcnt(0)
	v_add_f32_e32 v16, v16, v17
	global_store_dword v[18:19], v16, off

; __device__ __forceinline__ unsigned pk2(float lo, float hi) { f32x2 v = {lo, hi}; bf16x2_t b = __builtin_convertvector(v, bf16x2_t); return __builtin_bit_cast(unsigned, b); }
; __device__ __forceinline__ float bflo(unsigned w) { return __uint_as_float(w << 16); }
; __device__ __forceinline__ float bfhi(unsigned w) { return __uint_as_float(w & 0xffff0000u); }
;     __device__ __forceinline__ void operator()(const f32x4 (&acc)[2][2][4][2], const Unit& u, int wr, int wc, int fr, int fq) const {
;     ...
;         for (int j = 0; j < 8; ++j) { const int ai = j >> 2, m = j & 3; const int row = row0 + ai * HALF + m * 16; const size_t off = (size_t)row * DM + col0; float ss = 0.f;
;             if (MODE < 3 && j < 6) ldgrp(nx2, (size_t)(row0 + ((j + 2) >> 2) * HALF + ((j + 2) & 3) * 16) * DM + col0);
; #pragma unroll
;             for (int bj = 0; bj < 2; ++bj) { f32x4 o[2];
; #pragma unroll
;                 for (int n = 0; n < 2; ++n) { const int cc = bj * HALF + 4 * n;
;                     f32x4 v = acc[ai][bj][m][n];
;                     if (bias) { v = (v + *(const f32x4*)(bias + col0 + cc)) * *(const f32x4*)(scale + col0 + cc); }
;                     f32x4 b;
;                     if (MODE >= 3) b = (f32x4){0.f, 0.f, 0.f, 0.f};
;                     else if (MODE == 0) b = __builtin_bit_cast(f32x4, cur[bj][n]);
;                     else { const unsigned w0 = n ? cur[bj][0].z : cur[bj][0].x, w1 = n ? cur[bj][0].w : cur[bj][0].y; b = (f32x4){bflo(w0), bfhi(w0), bflo(w1), bfhi(w1)}; }
;                     o[n] = b + v;
;                     if (MODE == 2 || MODE == 4) *(f32x4*)(out + off + cc) = o[n];
;                     ss += (o[n][0] * o[n][0] + o[n][1] * o[n][1]) + (o[n][2] * o[n][2] + o[n][3] * o[n][3]); }
;                 if (MODE != 2 && MODE != 4) { u32x4 w; w.x = pk2(o[0][0], o[0][1]); w.y = pk2(o[0][2], o[0][3]); w.z = pk2(o[1][0], o[1][1]); w.w = pk2(o[1][2], o[1][3]); *(u32x4*)(xb + off + bj * HALF) = w; } }
.LBB0_858:
	s_waitcnt vmcnt(5)
	v_lshlrev_b32_e32 v16, 16, v52
	s_waitcnt lgkmcnt(0)
	v_and_b32_e32 v17, 0xffff0000, v52
	v_lshlrev_b32_e32 v18, 16, v53
	v_and_b32_e32 v19, 0xffff0000, v53
	v_pk_add_f32 v[14:15], v[14:15], v[18:19]
	v_pk_add_f32 v[12:13], v[12:13], v[16:17]
	v_lshlrev_b32_e32 v16, 16, v54
	v_and_b32_e32 v17, 0xffff0000, v54
	v_lshlrev_b32_e32 v18, 16, v55
	v_and_b32_e32 v19, 0xffff0000, v55
	v_pk_add_f32 v[10:11], v[10:11], v[18:19]
	v_pk_add_f32 v[8:9], v[8:9], v[16:17]
	v_cvt_pk_bf16_f32 v16, v12, v13
	v_cvt_pk_bf16_f32 v17, v14, v15
	v_cvt_pk_bf16_f32 v18, v8, v9
	v_cvt_pk_bf16_f32 v19, v10, v11
	s_and_b64 vcc, exec, s[8:9]
	global_store_dwordx4 v[58:59], v[16:19], off sc0 sc1
	s_cbranch_vccnz .LBB0_860
	global_load_dwordx4 v[16:19], v[166:167], off offset:512
	s_waitcnt vmcnt(0)
	v_pk_add_f32 v[18:19], v[6:7], v[18:19]
	v_pk_add_f32 v[16:17], v[4:5], v[16:17]
	global_load_dwordx4 v[4:7], v[164:165], off offset:512
	s_waitcnt vmcnt(0)
	v_pk_mul_f32 v[6:7], v[18:19], v[6:7]
	v_pk_mul_f32 v[4:5], v[16:17], v[4:5]

; __device__ __forceinline__ unsigned pk2(float lo, float hi) { f32x2 v = {lo, hi}; bf16x2_t b = __builtin_convertvector(v, bf16x2_t); return __builtin_bit_cast(unsigned, b); }
; __device__ __forceinline__ float bflo(unsigned w) { return __uint_as_float(w << 16); }
; __device__ __forceinline__ float bfhi(unsigned w) { return __uint_as_float(w & 0xffff0000u); }
;     __device__ __forceinline__ void operator()(const f32x4 (&acc)[2][2][4][2], const Unit& u, int wr, int wc, int fr, int fq) const {
;     ...
;         for (int j = 0; j < 8; ++j) { const int ai = j >> 2, m = j & 3; const int row = row0 + ai * HALF + m * 16; const size_t off = (size_t)row * DM + col0; float ss = 0.f;
;             if (MODE < 3 && j < 6) ldgrp(nx2, (size_t)(row0 + ((j + 2) >> 2) * HALF + ((j + 2) & 3) * 16) * DM + col0);
; #pragma unroll
;             for (int bj = 0; bj < 2; ++bj) { f32x4 o[2];
; #pragma unroll
;                 for (int n = 0; n < 2; ++n) { const int cc = bj * HALF + 4 * n;
;                     f32x4 v = acc[ai][bj][m][n];
;                     if (bias) { v = (v + *(const f32x4*)(bias + col0 + cc)) * *(const f32x4*)(scale + col0 + cc); }
;                     f32x4 b;
;                     if (MODE >= 3) b = (f32x4){0.f, 0.f, 0.f, 0.f};
;                     else if (MODE == 0) b = __builtin_bit_cast(f32x4, cur[bj][n]);
;                     else { const unsigned w0 = n ? cur[bj][0].z : cur[bj][0].x, w1 = n ? cur[bj][0].w : cur[bj][0].y; b = (f32x4){bflo(w0), bfhi(w0), bflo(w1), bfhi(w1)}; }
;                     o[n] = b + v;
;                     if (MODE == 2 || MODE == 4) *(f32x4*)(out + off + cc) = o[n];
;                     ss += (o[n][0] * o[n][0] + o[n][1] * o[n][1]) + (o[n][2] * o[n][2] + o[n][3] * o[n][3]); }
;                 if (MODE != 2 && MODE != 4) { u32x4 w; w.x = pk2(o[0][0], o[0][1]); w.y = pk2(o[0][2], o[0][3]); w.z = pk2(o[1][0], o[1][1]); w.w = pk2(o[1][2], o[1][3]); *(u32x4*)(xb + off + bj * HALF) = w; } }
;             if (MODE != 2 && MODE != 4 && rsq) { ss += __shfl_xor(ss, 16); ss += __shfl_xor(ss, 32); if (fq == 0) rsq[(size_t)row * 64 + u.pn * 4 + wc] = ss; }
.LBB0_862:
	s_waitcnt vmcnt(5)
	v_lshlrev_b32_e32 v16, 16, v48
	v_and_b32_e32 v17, 0xffff0000, v48
	v_lshlrev_b32_e32 v18, 16, v49
	v_and_b32_e32 v19, 0xffff0000, v49
	v_pk_add_f32 v[6:7], v[6:7], v[18:19]
	v_pk_add_f32 v[4:5], v[4:5], v[16:17]
	v_lshlrev_b32_e32 v16, 16, v50
	v_and_b32_e32 v17, 0xffff0000, v50
	v_lshlrev_b32_e32 v18, 16, v51
	v_and_b32_e32 v19, 0xffff0000, v51
	v_pk_add_f32 v[2:3], v[2:3], v[18:19]
	v_pk_add_f32 v[0:1], v[0:1], v[16:17]
	v_cvt_pk_bf16_f32 v16, v4, v5
	v_cvt_pk_bf16_f32 v17, v6, v7
	v_cvt_pk_bf16_f32 v18, v0, v1
	v_cvt_pk_bf16_f32 v19, v2, v3
	s_and_b64 vcc, exec, s[10:11]
	global_store_dwordx4 v[58:59], v[16:19], off offset:256 sc0 sc1
	s_cbranch_vccnz .LBB0_866
	v_mul_f32_e32 v13, v13, v13
	v_mul_f32_e32 v9, v9, v9
	v_mul_f32_e32 v1, v1, v1
	v_fmac_f32_e32 v13, v12, v12
	v_mul_f32_e32 v12, v15, v15
	v_fmac_f32_e32 v9, v8, v8
	v_mul_f32_e32 v8, v11, v11
	v_mul_f32_e32 v5, v5, v5
	v_fmac_f32_e32 v1, v0, v0
	v_mul_f32_e32 v0, v3, v3
	v_fmac_f32_e32 v12, v14, v14
	v_fmac_f32_e32 v8, v10, v10
	v_fmac_f32_e32 v5, v4, v4
	v_mul_f32_e32 v4, v7, v7
	v_fmac_f32_e32 v0, v2, v2
	v_and_b32_e32 v2, 64, v251
	v_add_f32_e32 v12, v13, v12
	v_add_f32_e32 v8, v9, v8
	v_fmac_f32_e32 v4, v6, v6
	v_add_f32_e32 v0, v1, v0
	v_xor_b32_e32 v1, 16, v251
	v_add_u32_e32 v2, 64, v2
	v_add_f32_e32 v8, v12, v8
	v_add_f32_e32 v4, v5, v4
	v_cmp_lt_i32_e32 vcc, v1, v2
	v_add_f32_e32 v4, v8, v4
	v_add_f32_e32 v0, v4, v0
	v_cndmask_b32_e32 v1, v251, v1, vcc
	v_lshlrev_b32_e32 v1, 2, v1
	ds_bpermute_b32 v1, v1, v0
	s_waitcnt lgkmcnt(0)
	v_add_f32_e32 v0, v0, v1
	v_xor_b32_e32 v1, 32, v251
	v_cmp_lt_i32_e32 vcc, v1, v2
	s_nop 1
	v_cndmask_b32_e32 v1, v251, v1, vcc
	v_lshlrev_b32_e32 v1, 2, v1
	ds_bpermute_b32 v1, v1, v0
	s_and_saveexec_b64 s[8:9], s[4:5]
	s_cbranch_execz .LBB0_865
	v_lshlrev_b64 v[2:3], 8, v[56:57]
	v_lshl_add_u64 v[2:3], s[62:63], 0, v[2:3]
	v_lshl_add_u64 v[2:3], s[78:79], 2, v[2:3]
	s_lshl_b32 s18, s28, 2
	v_lshl_add_u64 v[2:3], v[2:3], 0, s[18:19]
	s_waitcnt lgkmcnt(0)
	v_add_f32_e32 v0, v0, v1
	global_store_dword v[2:3], v0, off

; __device__ __forceinline__ unsigned pk2(float lo, float hi) { f32x2 v = {lo, hi}; bf16x2_t b = __builtin_convertvector(v, bf16x2_t); return __builtin_bit_cast(unsigned, b); }
; __device__ __forceinline__ float bflo(unsigned w) { return __uint_as_float(w << 16); }
; __device__ __forceinline__ float bfhi(unsigned w) { return __uint_as_float(w & 0xffff0000u); }
;     __device__ __forceinline__ void operator()(const f32x4 (&acc)[2][2][4][2], const Unit& u, int wr, int wc, int fr, int fq) const {
;     ...
;         for (int j = 0; j < 8; ++j) { const int ai = j >> 2, m = j & 3; const int row = row0 + ai * HALF + m * 16; const size_t off = (size_t)row * DM + col0; float ss = 0.f;
;             if (MODE < 3 && j < 6) ldgrp(nx2, (size_t)(row0 + ((j + 2) >> 2) * HALF + ((j + 2) & 3) * 16) * DM + col0);
; #pragma unroll
;             for (int bj = 0; bj < 2; ++bj) { f32x4 o[2];
; #pragma unroll
;                 for (int n = 0; n < 2; ++n) { const int cc = bj * HALF + 4 * n;
;                     f32x4 v = acc[ai][bj][m][n];
;                     if (bias) { v = (v + *(const f32x4*)(bias + col0 + cc)) * *(const f32x4*)(scale + col0 + cc); }
;                     f32x4 b;
;                     if (MODE >= 3) b = (f32x4){0.f, 0.f, 0.f, 0.f};
;                     else if (MODE == 0) b = __builtin_bit_cast(f32x4, cur[bj][n]);
;                     else { const unsigned w0 = n ? cur[bj][0].z : cur[bj][0].x, w1 = n ? cur[bj][0].w : cur[bj][0].y; b = (f32x4){bflo(w0), bfhi(w0), bflo(w1), bfhi(w1)}; }
;                     o[n] = b + v;
;                     if (MODE == 2 || MODE == 4) *(f32x4*)(out + off + cc) = o[n];
;                     ss += (o[n][0] * o[n][0] + o[n][1] * o[n][1]) + (o[n][2] * o[n][2] + o[n][3] * o[n][3]); }
;                 if (MODE != 2 && MODE != 4) { u32x4 w; w.x = pk2(o[0][0], o[0][1]); w.y = pk2(o[0][2], o[0][3]); w.z = pk2(o[1][0], o[1][1]); w.w = pk2(o[1][2], o[1][3]); *(u32x4*)(xb + off + bj * HALF) = w; } }
.LBB0_900:
	s_waitcnt vmcnt(0)
	v_pk_add_f32 v[136:137], v[176:177], v[136:137]
	v_lshlrev_b64 v[176:177], 12, v[198:199]
	v_pk_add_f32 v[134:135], v[174:175], v[134:135]
	v_pk_add_f32 v[128:129], v[172:173], v[128:129]
	v_pk_add_f32 v[126:127], v[170:171], v[126:127]
	v_lshl_add_u64 v[170:171], s[62:63], 0, v[176:177]
	v_cvt_pk_bf16_f32 v172, v134, v135
	v_cvt_pk_bf16_f32 v173, v136, v137
	v_cvt_pk_bf16_f32 v174, v126, v127
	v_cvt_pk_bf16_f32 v175, v128, v129
	v_lshl_add_u64 v[170:171], v[192:193], 1, v[170:171]
	s_and_b64 vcc, exec, s[8:9]
	global_store_dwordx4 v[170:171], v[172:175], off sc0 sc1
	s_cbranch_vccnz .LBB0_902
	global_load_dwordx4 v[172:175], v[190:191], off offset:512
	s_waitcnt vmcnt(0)
	v_pk_add_f32 v[174:175], v[120:121], v[174:175]
	v_pk_add_f32 v[172:173], v[118:119], v[172:173]
	global_load_dwordx4 v[118:121], v[188:189], off offset:512
	s_waitcnt vmcnt(0)
	v_pk_mul_f32 v[120:121], v[174:175], v[120:121]
	v_pk_mul_f32 v[118:119], v[172:173], v[118:119]

; __device__ __forceinline__ unsigned pk2(float lo, float hi) { f32x2 v = {lo, hi}; bf16x2_t b = __builtin_convertvector(v, bf16x2_t); return __builtin_bit_cast(unsigned, b); }
;     __device__ __forceinline__ void operator()(const f32x4 (&acc)[2][2][4][2], const Unit& u, int wr, int wc, int fr, int fq) const {
;     ...
;                     o[n] = b + v;
;                     if (MODE == 2 || MODE == 4) *(f32x4*)(out + off + cc) = o[n];
;                     ss += (o[n][0] * o[n][0] + o[n][1] * o[n][1]) + (o[n][2] * o[n][2] + o[n][3] * o[n][3]); }
;                 if (MODE != 2 && MODE != 4) { u32x4 w; w.x = pk2(o[0][0], o[0][1]); w.y = pk2(o[0][2], o[0][3]); w.z = pk2(o[1][0], o[1][1]); w.w = pk2(o[1][2], o[1][3]); *(u32x4*)(xb + off + bj * HALF) = w; } }
;             if (MODE != 2 && MODE != 4 && rsq) { ss += __shfl_xor(ss, 16); ss += __shfl_xor(ss, 32); if (fq == 0) rsq[(size_t)row * 64 + u.pn * 4 + wc] = ss; }
.LBB0_904:
	v_pk_add_f32 v[120:121], v[168:169], v[120:121]
	v_pk_add_f32 v[118:119], v[166:167], v[118:119]
	s_lshl_b32 s52, s10, 2
	v_pk_add_f32 v[116:117], v[164:165], v[116:117]
	v_pk_add_f32 v[114:115], v[162:163], v[114:115]
	v_cndmask_b32_e64 v166, 0, 1, s[70:71]
	s_ashr_i32 s53, s52, 31
	v_cvt_pk_bf16_f32 v162, v118, v119
	v_cvt_pk_bf16_f32 v163, v120, v121
	v_cvt_pk_bf16_f32 v164, v114, v115
	v_cvt_pk_bf16_f32 v165, v116, v117
	v_cmp_ne_u32_e64 s[10:11], 1, v166
	s_andn2_b64 vcc, exec, s[70:71]
	global_store_dwordx4 v[170:171], v[162:165], off offset:256 sc0 sc1
	s_cbranch_vccnz .LBB0_908
	v_mul_f32_e32 v135, v135, v135
	v_mul_f32_e32 v127, v127, v127
	v_mul_f32_e32 v115, v115, v115
	v_fmac_f32_e32 v135, v134, v134
	v_mul_f32_e32 v134, v137, v137
	v_fmac_f32_e32 v127, v126, v126
	v_mul_f32_e32 v126, v129, v129
	v_mul_f32_e32 v119, v119, v119
	v_fmac_f32_e32 v115, v114, v114
	v_mul_f32_e32 v114, v117, v117
	v_fmac_f32_e32 v134, v136, v136
	v_fmac_f32_e32 v126, v128, v128
	v_fmac_f32_e32 v119, v118, v118
	v_mul_f32_e32 v118, v121, v121
	v_fmac_f32_e32 v114, v116, v116
	v_and_b32_e32 v116, 64, v251
	v_add_f32_e32 v134, v135, v134
	v_add_f32_e32 v126, v127, v126
	v_fmac_f32_e32 v118, v120, v120
	v_add_f32_e32 v114, v115, v114
	v_xor_b32_e32 v115, 16, v251
	v_add_u32_e32 v116, 64, v116
	v_add_f32_e32 v126, v134, v126
	v_add_f32_e32 v118, v119, v118
	v_cmp_lt_i32_e32 vcc, v115, v116
	v_add_f32_e32 v118, v126, v118
	v_add_f32_e32 v114, v118, v114
	v_cndmask_b32_e32 v115, v251, v115, vcc
	v_lshlrev_b32_e32 v115, 2, v115
	ds_bpermute_b32 v115, v115, v114
	s_waitcnt lgkmcnt(0)
	v_add_f32_e32 v114, v114, v115
	v_xor_b32_e32 v115, 32, v251
	v_cmp_lt_i32_e32 vcc, v115, v116
	s_nop 1
	v_cndmask_b32_e32 v115, v251, v115, vcc
	v_lshlrev_b32_e32 v115, 2, v115
	ds_bpermute_b32 v115, v115, v114
	s_and_saveexec_b64 s[16:17], s[4:5]
	s_cbranch_execz .LBB0_907
	v_lshlrev_b64 v[116:117], 8, v[198:199]
	v_lshl_add_u64 v[116:117], s[64:65], 0, v[116:117]
	v_lshl_add_u64 v[116:117], s[52:53], 2, v[116:117]
	s_lshl_b32 s18, s28, 2
	v_lshl_add_u64 v[116:117], v[116:117], 0, s[18:19]
	s_waitcnt lgkmcnt(0)
	v_add_f32_e32 v114, v114, v115
	global_store_dword v[116:117], v114, off

; __device__ __forceinline__ unsigned pk2(float lo, float hi) { f32x2 v = {lo, hi}; bf16x2_t b = __builtin_convertvector(v, bf16x2_t); return __builtin_bit_cast(unsigned, b); }
; __device__ __forceinline__ float bflo(unsigned w) { return __uint_as_float(w << 16); }
; __device__ __forceinline__ float bfhi(unsigned w) { return __uint_as_float(w & 0xffff0000u); }
;     __device__ __forceinline__ void operator()(const f32x4 (&acc)[2][2][4][2], const Unit& u, int wr, int wc, int fr, int fq) const {
;     ...
;                     if (bias) { v = (v + *(const f32x4*)(bias + col0 + cc)) * *(const f32x4*)(scale + col0 + cc); }
;                     f32x4 b;
;                     if (MODE >= 3) b = (f32x4){0.f, 0.f, 0.f, 0.f};
;                     else if (MODE == 0) b = __builtin_bit_cast(f32x4, cur[bj][n]);
;                     else { const unsigned w0 = n ? cur[bj][0].z : cur[bj][0].x, w1 = n ? cur[bj][0].w : cur[bj][0].y; b = (f32x4){bflo(w0), bfhi(w0), bflo(w1), bfhi(w1)}; }
;                     o[n] = b + v;
;                     if (MODE == 2 || MODE == 4) *(f32x4*)(out + off + cc) = o[n];
;                     ss += (o[n][0] * o[n][0] + o[n][1] * o[n][1]) + (o[n][2] * o[n][2] + o[n][3] * o[n][3]); }
;                 if (MODE != 2 && MODE != 4) { u32x4 w; w.x = pk2(o[0][0], o[0][1]); w.y = pk2(o[0][2], o[0][3]); w.z = pk2(o[1][0], o[1][1]); w.w = pk2(o[1][2], o[1][3]); *(u32x4*)(xb + off + bj * HALF) = w; } }
.LBB0_912:
	v_pk_add_f32 v[112:113], v[160:161], v[112:113]
	v_lshlrev_b64 v[160:161], 12, v[200:201]
	v_pk_add_f32 v[110:111], v[158:159], v[110:111]
	v_pk_add_f32 v[108:109], v[156:157], v[108:109]
	v_pk_add_f32 v[106:107], v[154:155], v[106:107]
	v_lshl_add_u64 v[154:155], s[62:63], 0, v[160:161]
	v_cvt_pk_bf16_f32 v156, v110, v111
	v_cvt_pk_bf16_f32 v157, v112, v113
	v_cvt_pk_bf16_f32 v158, v106, v107
	v_cvt_pk_bf16_f32 v159, v108, v109
	v_lshl_add_u64 v[154:155], v[192:193], 1, v[154:155]
	s_and_b64 vcc, exec, s[8:9]
	global_store_dwordx4 v[154:155], v[156:159], off sc0 sc1
	s_cbranch_vccnz .LBB0_914
	global_load_dwordx4 v[156:159], v[190:191], off offset:512
	s_waitcnt vmcnt(0)
	v_pk_add_f32 v[158:159], v[104:105], v[158:159]
	v_pk_add_f32 v[156:157], v[102:103], v[156:157]
	global_load_dwordx4 v[102:105], v[188:189], off offset:512
	s_waitcnt vmcnt(0)
	v_pk_mul_f32 v[104:105], v[158:159], v[104:105]
	v_pk_mul_f32 v[102:103], v[156:157], v[102:103]

; __device__ __forceinline__ unsigned pk2(float lo, float hi) { f32x2 v = {lo, hi}; bf16x2_t b = __builtin_convertvector(v, bf16x2_t); return __builtin_bit_cast(unsigned, b); }
;     __device__ __forceinline__ void operator()(const f32x4 (&acc)[2][2][4][2], const Unit& u, int wr, int wc, int fr, int fq) const {
;     ...
;                     o[n] = b + v;
;                     if (MODE == 2 || MODE == 4) *(f32x4*)(out + off + cc) = o[n];
;                     ss += (o[n][0] * o[n][0] + o[n][1] * o[n][1]) + (o[n][2] * o[n][2] + o[n][3] * o[n][3]); }
;                 if (MODE != 2 && MODE != 4) { u32x4 w; w.x = pk2(o[0][0], o[0][1]); w.y = pk2(o[0][2], o[0][3]); w.z = pk2(o[1][0], o[1][1]); w.w = pk2(o[1][2], o[1][3]); *(u32x4*)(xb + off + bj * HALF) = w; } }
;             if (MODE != 2 && MODE != 4 && rsq) { ss += __shfl_xor(ss, 16); ss += __shfl_xor(ss, 32); if (fq == 0) rsq[(size_t)row * 64 + u.pn * 4 + wc] = ss; }
.LBB0_916:
	v_pk_add_f32 v[104:105], v[152:153], v[104:105]
	v_pk_add_f32 v[102:103], v[150:151], v[102:103]
	v_pk_add_f32 v[100:101], v[148:149], v[100:101]
	v_pk_add_f32 v[98:99], v[146:147], v[98:99]
	v_cvt_pk_bf16_f32 v146, v102, v103
	v_cvt_pk_bf16_f32 v147, v104, v105
	v_cvt_pk_bf16_f32 v148, v98, v99
	v_cvt_pk_bf16_f32 v149, v100, v101
	s_and_b64 vcc, exec, s[10:11]
	global_store_dwordx4 v[154:155], v[146:149], off offset:256 sc0 sc1
	s_cbranch_vccnz .LBB0_920
	v_mul_f32_e32 v111, v111, v111
	v_mul_f32_e32 v107, v107, v107
	v_mul_f32_e32 v99, v99, v99
	v_fmac_f32_e32 v111, v110, v110
	v_mul_f32_e32 v110, v113, v113
	v_fmac_f32_e32 v107, v106, v106
	v_mul_f32_e32 v106, v109, v109
	v_mul_f32_e32 v103, v103, v103
	v_fmac_f32_e32 v99, v98, v98
	v_mul_f32_e32 v98, v101, v101
	v_fmac_f32_e32 v110, v112, v112
	v_fmac_f32_e32 v106, v108, v108
	v_fmac_f32_e32 v103, v102, v102
	v_mul_f32_e32 v102, v105, v105
	v_fmac_f32_e32 v98, v100, v100
	v_and_b32_e32 v100, 64, v251
	v_add_f32_e32 v110, v111, v110
	v_add_f32_e32 v106, v107, v106
	v_fmac_f32_e32 v102, v104, v104
	v_add_f32_e32 v98, v99, v98
	v_xor_b32_e32 v99, 16, v251
	v_add_u32_e32 v100, 64, v100
	v_add_f32_e32 v106, v110, v106
	v_add_f32_e32 v102, v103, v102
	v_cmp_lt_i32_e32 vcc, v99, v100
	v_add_f32_e32 v102, v106, v102
	v_add_f32_e32 v98, v102, v98
	v_cndmask_b32_e32 v99, v251, v99, vcc
	v_lshlrev_b32_e32 v99, 2, v99
	ds_bpermute_b32 v99, v99, v98
	s_waitcnt lgkmcnt(0)
	v_add_f32_e32 v98, v98, v99
	v_xor_b32_e32 v99, 32, v251
	v_cmp_lt_i32_e32 vcc, v99, v100
	s_nop 1
	v_cndmask_b32_e32 v99, v251, v99, vcc
	v_lshlrev_b32_e32 v99, 2, v99
	ds_bpermute_b32 v99, v99, v98
	s_and_saveexec_b64 s[16:17], s[4:5]
	s_cbranch_execz .LBB0_919
	v_lshlrev_b64 v[100:101], 8, v[200:201]
	v_lshl_add_u64 v[100:101], s[64:65], 0, v[100:101]
	v_lshl_add_u64 v[100:101], s[52:53], 2, v[100:101]
	s_lshl_b32 s18, s28, 2
	v_lshl_add_u64 v[100:101], v[100:101], 0, s[18:19]
	s_waitcnt lgkmcnt(0)
	v_add_f32_e32 v98, v98, v99
	global_store_dword v[100:101], v98, off

; __device__ __forceinline__ unsigned pk2(float lo, float hi) { f32x2 v = {lo, hi}; bf16x2_t b = __builtin_convertvector(v, bf16x2_t); return __builtin_bit_cast(unsigned, b); }
; __device__ __forceinline__ float bflo(unsigned w) { return __uint_as_float(w << 16); }
; __device__ __forceinline__ float bfhi(unsigned w) { return __uint_as_float(w & 0xffff0000u); }
;     __device__ __forceinline__ void operator()(const f32x4 (&acc)[2][2][4][2], const Unit& u, int wr, int wc, int fr, int fq) const {
;     ...
;                     if (bias) { v = (v + *(const f32x4*)(bias + col0 + cc)) * *(const f32x4*)(scale + col0 + cc); }
;                     f32x4 b;
;                     if (MODE >= 3) b = (f32x4){0.f, 0.f, 0.f, 0.f};
;                     else if (MODE == 0) b = __builtin_bit_cast(f32x4, cur[bj][n]);
;                     else { const unsigned w0 = n ? cur[bj][0].z : cur[bj][0].x, w1 = n ? cur[bj][0].w : cur[bj][0].y; b = (f32x4){bflo(w0), bfhi(w0), bflo(w1), bfhi(w1)}; }
;                     o[n] = b + v;
;                     if (MODE == 2 || MODE == 4) *(f32x4*)(out + off + cc) = o[n];
;                     ss += (o[n][0] * o[n][0] + o[n][1] * o[n][1]) + (o[n][2] * o[n][2] + o[n][3] * o[n][3]); }
;                 if (MODE != 2 && MODE != 4) { u32x4 w; w.x = pk2(o[0][0], o[0][1]); w.y = pk2(o[0][2], o[0][3]); w.z = pk2(o[1][0], o[1][1]); w.w = pk2(o[1][2], o[1][3]); *(u32x4*)(xb + off + bj * HALF) = w; } }
.LBB0_924:
	v_pk_add_f32 v[94:95], v[144:145], v[94:95]
	v_lshlrev_b64 v[144:145], 12, v[196:197]
	v_pk_add_f32 v[92:93], v[142:143], v[92:93]
	v_pk_add_f32 v[90:91], v[140:141], v[90:91]
	v_pk_add_f32 v[88:89], v[138:139], v[88:89]
	v_lshl_add_u64 v[138:139], s[62:63], 0, v[144:145]
	v_cvt_pk_bf16_f32 v140, v92, v93
	v_cvt_pk_bf16_f32 v141, v94, v95
	v_cvt_pk_bf16_f32 v142, v88, v89
	v_cvt_pk_bf16_f32 v143, v90, v91
	v_lshl_add_u64 v[138:139], v[192:193], 1, v[138:139]
	s_and_b64 vcc, exec, s[8:9]
	global_store_dwordx4 v[138:139], v[140:143], off sc0 sc1
	s_cbranch_vccnz .LBB0_926
	global_load_dwordx4 v[140:143], v[190:191], off offset:512
	s_waitcnt vmcnt(0)
	v_pk_add_f32 v[142:143], v[86:87], v[142:143]
	v_pk_add_f32 v[140:141], v[84:85], v[140:141]
	global_load_dwordx4 v[84:87], v[188:189], off offset:512
	s_waitcnt vmcnt(0)
	v_pk_mul_f32 v[86:87], v[142:143], v[86:87]
	v_pk_mul_f32 v[84:85], v[140:141], v[84:85]

; __device__ __forceinline__ unsigned pk2(float lo, float hi) { f32x2 v = {lo, hi}; bf16x2_t b = __builtin_convertvector(v, bf16x2_t); return __builtin_bit_cast(unsigned, b); }
;     __device__ __forceinline__ void operator()(const f32x4 (&acc)[2][2][4][2], const Unit& u, int wr, int wc, int fr, int fq) const {
;     ...
;                     o[n] = b + v;
;                     if (MODE == 2 || MODE == 4) *(f32x4*)(out + off + cc) = o[n];
;                     ss += (o[n][0] * o[n][0] + o[n][1] * o[n][1]) + (o[n][2] * o[n][2] + o[n][3] * o[n][3]); }
;                 if (MODE != 2 && MODE != 4) { u32x4 w; w.x = pk2(o[0][0], o[0][1]); w.y = pk2(o[0][2], o[0][3]); w.z = pk2(o[1][0], o[1][1]); w.w = pk2(o[1][2], o[1][3]); *(u32x4*)(xb + off + bj * HALF) = w; } }
;             if (MODE != 2 && MODE != 4 && rsq) { ss += __shfl_xor(ss, 16); ss += __shfl_xor(ss, 32); if (fq == 0) rsq[(size_t)row * 64 + u.pn * 4 + wc] = ss; }
.LBB0_928:
	v_pk_add_f32 v[86:87], v[132:133], v[86:87]
	v_pk_add_f32 v[84:85], v[130:131], v[84:85]
	v_pk_add_f32 v[82:83], v[124:125], v[82:83]
	v_pk_add_f32 v[80:81], v[122:123], v[80:81]
	v_cvt_pk_bf16_f32 v122, v84, v85
	v_cvt_pk_bf16_f32 v123, v86, v87
	v_cvt_pk_bf16_f32 v124, v80, v81
	v_cvt_pk_bf16_f32 v125, v82, v83
	s_and_b64 vcc, exec, s[10:11]
	global_store_dwordx4 v[138:139], v[122:125], off offset:256 sc0 sc1
	s_cbranch_vccnz .LBB0_932
	v_mul_f32_e32 v93, v93, v93
	v_mul_f32_e32 v89, v89, v89
	v_mul_f32_e32 v81, v81, v81
	v_fmac_f32_e32 v93, v92, v92
	v_mul_f32_e32 v92, v95, v95
	v_fmac_f32_e32 v89, v88, v88
	v_mul_f32_e32 v88, v91, v91
	v_mul_f32_e32 v85, v85, v85
	v_fmac_f32_e32 v81, v80, v80
	v_mul_f32_e32 v80, v83, v83
	v_fmac_f32_e32 v92, v94, v94
	v_fmac_f32_e32 v88, v90, v90
	v_fmac_f32_e32 v85, v84, v84
	v_mul_f32_e32 v84, v87, v87
	v_fmac_f32_e32 v80, v82, v82
	v_and_b32_e32 v82, 64, v251
	v_add_f32_e32 v92, v93, v92
	v_add_f32_e32 v88, v89, v88
	v_fmac_f32_e32 v84, v86, v86
	v_add_f32_e32 v80, v81, v80
	v_xor_b32_e32 v81, 16, v251
	v_add_u32_e32 v82, 64, v82
	v_add_f32_e32 v88, v92, v88
	v_add_f32_e32 v84, v85, v84
	v_cmp_lt_i32_e32 vcc, v81, v82
	v_add_f32_e32 v84, v88, v84
	v_add_f32_e32 v80, v84, v80
	v_cndmask_b32_e32 v81, v251, v81, vcc
	v_lshlrev_b32_e32 v81, 2, v81
	ds_bpermute_b32 v81, v81, v80
	s_waitcnt lgkmcnt(0)
	v_add_f32_e32 v80, v80, v81
	v_xor_b32_e32 v81, 32, v251
	v_cmp_lt_i32_e32 vcc, v81, v82
	s_nop 1
	v_cndmask_b32_e32 v81, v251, v81, vcc
	v_lshlrev_b32_e32 v81, 2, v81
	ds_bpermute_b32 v81, v81, v80
	s_and_saveexec_b64 s[16:17], s[4:5]
	s_cbranch_execz .LBB0_931
	v_lshlrev_b64 v[82:83], 8, v[196:197]
	v_lshl_add_u64 v[82:83], s[64:65], 0, v[82:83]
	v_lshl_add_u64 v[82:83], s[52:53], 2, v[82:83]
	s_lshl_b32 s18, s28, 2
	v_lshl_add_u64 v[82:83], v[82:83], 0, s[18:19]
	s_waitcnt lgkmcnt(0)
	v_add_f32_e32 v80, v80, v81
	global_store_dword v[82:83], v80, off

; __device__ __forceinline__ unsigned pk2(float lo, float hi) { f32x2 v = {lo, hi}; bf16x2_t b = __builtin_convertvector(v, bf16x2_t); return __builtin_bit_cast(unsigned, b); }
; __device__ __forceinline__ float bflo(unsigned w) { return __uint_as_float(w << 16); }
; __device__ __forceinline__ float bfhi(unsigned w) { return __uint_as_float(w & 0xffff0000u); }
;     __device__ __forceinline__ void operator()(const f32x4 (&acc)[2][2][4][2], const Unit& u, int wr, int wc, int fr, int fq) const {
;     ...
;                     if (bias) { v = (v + *(const f32x4*)(bias + col0 + cc)) * *(const f32x4*)(scale + col0 + cc); }
;                     f32x4 b;
;                     if (MODE >= 3) b = (f32x4){0.f, 0.f, 0.f, 0.f};
;                     else if (MODE == 0) b = __builtin_bit_cast(f32x4, cur[bj][n]);
;                     else { const unsigned w0 = n ? cur[bj][0].z : cur[bj][0].x, w1 = n ? cur[bj][0].w : cur[bj][0].y; b = (f32x4){bflo(w0), bfhi(w0), bflo(w1), bfhi(w1)}; }
;                     o[n] = b + v;
;                     if (MODE == 2 || MODE == 4) *(f32x4*)(out + off + cc) = o[n];
;                     ss += (o[n][0] * o[n][0] + o[n][1] * o[n][1]) + (o[n][2] * o[n][2] + o[n][3] * o[n][3]); }
;                 if (MODE != 2 && MODE != 4) { u32x4 w; w.x = pk2(o[0][0], o[0][1]); w.y = pk2(o[0][2], o[0][3]); w.z = pk2(o[1][0], o[1][1]); w.w = pk2(o[1][2], o[1][3]); *(u32x4*)(xb + off + bj * HALF) = w; } }
.LBB0_936:
	v_lshlrev_b64 v[122:123], 12, v[162:163]
	s_waitcnt vmcnt(14)
	v_pk_add_f32 v[78:79], v[136:137], v[78:79]
	v_pk_add_f32 v[76:77], v[134:135], v[76:77]
	v_pk_add_f32 v[74:75], v[128:129], v[74:75]
	v_pk_add_f32 v[72:73], v[126:127], v[72:73]
	v_lshl_add_u64 v[122:123], s[62:63], 0, v[122:123]
	v_cvt_pk_bf16_f32 v124, v76, v77
	v_cvt_pk_bf16_f32 v125, v78, v79
	v_cvt_pk_bf16_f32 v126, v72, v73
	v_cvt_pk_bf16_f32 v127, v74, v75
	v_lshl_add_u64 v[122:123], v[192:193], 1, v[122:123]
	s_and_b64 vcc, exec, s[8:9]
	global_store_dwordx4 v[122:123], v[124:127], off sc0 sc1
	s_cbranch_vccnz .LBB0_938
	global_load_dwordx4 v[124:127], v[190:191], off offset:512
	s_waitcnt vmcnt(0)
	v_pk_add_f32 v[126:127], v[70:71], v[126:127]
	v_pk_add_f32 v[124:125], v[68:69], v[124:125]
	global_load_dwordx4 v[68:71], v[188:189], off offset:512
	s_waitcnt vmcnt(0)
	v_pk_mul_f32 v[70:71], v[126:127], v[70:71]
	v_pk_mul_f32 v[68:69], v[124:125], v[68:69]

; __device__ __forceinline__ unsigned pk2(float lo, float hi) { f32x2 v = {lo, hi}; bf16x2_t b = __builtin_convertvector(v, bf16x2_t); return __builtin_bit_cast(unsigned, b); }
;     __device__ __forceinline__ void operator()(const f32x4 (&acc)[2][2][4][2], const Unit& u, int wr, int wc, int fr, int fq) const {
;     ...
;                     o[n] = b + v;
;                     if (MODE == 2 || MODE == 4) *(f32x4*)(out + off + cc) = o[n];
;                     ss += (o[n][0] * o[n][0] + o[n][1] * o[n][1]) + (o[n][2] * o[n][2] + o[n][3] * o[n][3]); }
;                 if (MODE != 2 && MODE != 4) { u32x4 w; w.x = pk2(o[0][0], o[0][1]); w.y = pk2(o[0][2], o[0][3]); w.z = pk2(o[1][0], o[1][1]); w.w = pk2(o[1][2], o[1][3]); *(u32x4*)(xb + off + bj * HALF) = w; } }
;             if (MODE != 2 && MODE != 4 && rsq) { ss += __shfl_xor(ss, 16); ss += __shfl_xor(ss, 32); if (fq == 0) rsq[(size_t)row * 64 + u.pn * 4 + wc] = ss; }
.LBB0_940:
	s_waitcnt vmcnt(13)
	v_pk_add_f32 v[70:71], v[120:121], v[70:71]
	v_pk_add_f32 v[68:69], v[118:119], v[68:69]
	v_pk_add_f32 v[66:67], v[116:117], v[66:67]
	v_pk_add_f32 v[64:65], v[114:115], v[64:65]
	v_cvt_pk_bf16_f32 v114, v68, v69
	v_cvt_pk_bf16_f32 v115, v70, v71
	v_cvt_pk_bf16_f32 v116, v64, v65
	v_cvt_pk_bf16_f32 v117, v66, v67
	s_and_b64 vcc, exec, s[10:11]
	global_store_dwordx4 v[122:123], v[114:117], off offset:256 sc0 sc1
	s_cbranch_vccnz .LBB0_944
	v_mul_f32_e32 v77, v77, v77
	v_mul_f32_e32 v73, v73, v73
	v_mul_f32_e32 v65, v65, v65
	v_fmac_f32_e32 v77, v76, v76
	v_mul_f32_e32 v76, v79, v79
	v_fmac_f32_e32 v73, v72, v72
	v_mul_f32_e32 v72, v75, v75
	v_mul_f32_e32 v69, v69, v69
	v_fmac_f32_e32 v65, v64, v64
	v_mul_f32_e32 v64, v67, v67
	v_fmac_f32_e32 v76, v78, v78
	v_fmac_f32_e32 v72, v74, v74
	v_fmac_f32_e32 v69, v68, v68
	v_mul_f32_e32 v68, v71, v71
	v_fmac_f32_e32 v64, v66, v66
	v_and_b32_e32 v66, 64, v251
	v_add_f32_e32 v76, v77, v76
	v_add_f32_e32 v72, v73, v72
	v_fmac_f32_e32 v68, v70, v70
	v_add_f32_e32 v64, v65, v64
	v_xor_b32_e32 v65, 16, v251
	v_add_u32_e32 v66, 64, v66
	v_add_f32_e32 v72, v76, v72
	v_add_f32_e32 v68, v69, v68
	v_cmp_lt_i32_e32 vcc, v65, v66
	v_add_f32_e32 v68, v72, v68
	v_add_f32_e32 v64, v68, v64
	v_cndmask_b32_e32 v65, v251, v65, vcc
	v_lshlrev_b32_e32 v65, 2, v65
	ds_bpermute_b32 v65, v65, v64
	s_waitcnt lgkmcnt(0)
	v_add_f32_e32 v64, v64, v65
	v_xor_b32_e32 v65, 32, v251
	v_cmp_lt_i32_e32 vcc, v65, v66
	s_nop 1
	v_cndmask_b32_e32 v65, v251, v65, vcc
	v_lshlrev_b32_e32 v65, 2, v65
	ds_bpermute_b32 v65, v65, v64
	s_and_saveexec_b64 s[16:17], s[4:5]
	s_cbranch_execz .LBB0_943
	v_lshlrev_b64 v[66:67], 8, v[162:163]
	v_lshl_add_u64 v[66:67], s[64:65], 0, v[66:67]
	v_lshl_add_u64 v[66:67], s[52:53], 2, v[66:67]
	s_lshl_b32 s18, s28, 2
	v_lshl_add_u64 v[66:67], v[66:67], 0, s[18:19]
	s_waitcnt lgkmcnt(0)
	v_add_f32_e32 v64, v64, v65
	global_store_dword v[66:67], v64, off

; __device__ __forceinline__ unsigned pk2(float lo, float hi) { f32x2 v = {lo, hi}; bf16x2_t b = __builtin_convertvector(v, bf16x2_t); return __builtin_bit_cast(unsigned, b); }
; __device__ __forceinline__ float bflo(unsigned w) { return __uint_as_float(w << 16); }
; __device__ __forceinline__ float bfhi(unsigned w) { return __uint_as_float(w & 0xffff0000u); }
;     __device__ __forceinline__ void operator()(const f32x4 (&acc)[2][2][4][2], const Unit& u, int wr, int wc, int fr, int fq) const {
;     ...
;                     if (bias) { v = (v + *(const f32x4*)(bias + col0 + cc)) * *(const f32x4*)(scale + col0 + cc); }
;                     f32x4 b;
;                     if (MODE >= 3) b = (f32x4){0.f, 0.f, 0.f, 0.f};
;                     else if (MODE == 0) b = __builtin_bit_cast(f32x4, cur[bj][n]);
;                     else { const unsigned w0 = n ? cur[bj][0].z : cur[bj][0].x, w1 = n ? cur[bj][0].w : cur[bj][0].y; b = (f32x4){bflo(w0), bfhi(w0), bflo(w1), bfhi(w1)}; }
;                     o[n] = b + v;
;                     if (MODE == 2 || MODE == 4) *(f32x4*)(out + off + cc) = o[n];
;                     ss += (o[n][0] * o[n][0] + o[n][1] * o[n][1]) + (o[n][2] * o[n][2] + o[n][3] * o[n][3]); }
;                 if (MODE != 2 && MODE != 4) { u32x4 w; w.x = pk2(o[0][0], o[0][1]); w.y = pk2(o[0][2], o[0][3]); w.z = pk2(o[1][0], o[1][1]); w.w = pk2(o[1][2], o[1][3]); *(u32x4*)(xb + off + bj * HALF) = w; } }
.LBB0_948:
	s_waitcnt vmcnt(14)
	v_pk_add_f32 v[62:63], v[112:113], v[62:63]
	v_lshlrev_b64 v[112:113], 12, v[146:147]
	v_pk_add_f32 v[60:61], v[110:111], v[60:61]
	v_pk_add_f32 v[58:59], v[108:109], v[58:59]
	v_pk_add_f32 v[56:57], v[106:107], v[56:57]
	v_lshl_add_u64 v[106:107], s[62:63], 0, v[112:113]
	v_cvt_pk_bf16_f32 v108, v60, v61
	v_cvt_pk_bf16_f32 v109, v62, v63
	v_cvt_pk_bf16_f32 v110, v56, v57
	v_cvt_pk_bf16_f32 v111, v58, v59
	v_lshl_add_u64 v[106:107], v[192:193], 1, v[106:107]
	s_and_b64 vcc, exec, s[8:9]
	global_store_dwordx4 v[106:107], v[108:111], off sc0 sc1
	s_cbranch_vccnz .LBB0_950
	global_load_dwordx4 v[108:111], v[190:191], off offset:512
	s_waitcnt vmcnt(0)
	v_pk_add_f32 v[110:111], v[54:55], v[110:111]
	v_pk_add_f32 v[108:109], v[52:53], v[108:109]
	global_load_dwordx4 v[52:55], v[188:189], off offset:512
	s_waitcnt vmcnt(0)
	v_pk_mul_f32 v[54:55], v[110:111], v[54:55]
	v_pk_mul_f32 v[52:53], v[108:109], v[52:53]

; __device__ __forceinline__ unsigned pk2(float lo, float hi) { f32x2 v = {lo, hi}; bf16x2_t b = __builtin_convertvector(v, bf16x2_t); return __builtin_bit_cast(unsigned, b); }
;     __device__ __forceinline__ void operator()(const f32x4 (&acc)[2][2][4][2], const Unit& u, int wr, int wc, int fr, int fq) const {
;     ...
;                     o[n] = b + v;
;                     if (MODE == 2 || MODE == 4) *(f32x4*)(out + off + cc) = o[n];
;                     ss += (o[n][0] * o[n][0] + o[n][1] * o[n][1]) + (o[n][2] * o[n][2] + o[n][3] * o[n][3]); }
;                 if (MODE != 2 && MODE != 4) { u32x4 w; w.x = pk2(o[0][0], o[0][1]); w.y = pk2(o[0][2], o[0][3]); w.z = pk2(o[1][0], o[1][1]); w.w = pk2(o[1][2], o[1][3]); *(u32x4*)(xb + off + bj * HALF) = w; } }
;             if (MODE != 2 && MODE != 4 && rsq) { ss += __shfl_xor(ss, 16); ss += __shfl_xor(ss, 32); if (fq == 0) rsq[(size_t)row * 64 + u.pn * 4 + wc] = ss; }
.LBB0_952:
	s_waitcnt vmcnt(13)
	v_pk_add_f32 v[54:55], v[104:105], v[54:55]
	v_pk_add_f32 v[52:53], v[102:103], v[52:53]
	v_pk_add_f32 v[50:51], v[100:101], v[50:51]
	v_pk_add_f32 v[48:49], v[98:99], v[48:49]
	v_cvt_pk_bf16_f32 v98, v52, v53
	v_cvt_pk_bf16_f32 v99, v54, v55
	v_cvt_pk_bf16_f32 v100, v48, v49
	v_cvt_pk_bf16_f32 v101, v50, v51
	s_and_b64 vcc, exec, s[10:11]
	global_store_dwordx4 v[106:107], v[98:101], off offset:256 sc0 sc1
	s_cbranch_vccnz .LBB0_956
	v_mul_f32_e32 v61, v61, v61
	v_mul_f32_e32 v57, v57, v57
	v_mul_f32_e32 v49, v49, v49
	v_fmac_f32_e32 v61, v60, v60
	v_mul_f32_e32 v60, v63, v63
	v_fmac_f32_e32 v57, v56, v56
	v_mul_f32_e32 v56, v59, v59
	v_mul_f32_e32 v53, v53, v53
	v_fmac_f32_e32 v49, v48, v48
	v_mul_f32_e32 v48, v51, v51
	v_fmac_f32_e32 v60, v62, v62
	v_fmac_f32_e32 v56, v58, v58
	v_fmac_f32_e32 v53, v52, v52
	v_mul_f32_e32 v52, v55, v55
	v_fmac_f32_e32 v48, v50, v50
	v_and_b32_e32 v50, 64, v251
	v_add_f32_e32 v60, v61, v60
	v_add_f32_e32 v56, v57, v56
	v_fmac_f32_e32 v52, v54, v54
	v_add_f32_e32 v48, v49, v48
	v_xor_b32_e32 v49, 16, v251
	v_add_u32_e32 v50, 64, v50
	v_add_f32_e32 v56, v60, v56
	v_add_f32_e32 v52, v53, v52
	v_cmp_lt_i32_e32 vcc, v49, v50
	v_add_f32_e32 v52, v56, v52
	v_add_f32_e32 v48, v52, v48
	v_cndmask_b32_e32 v49, v251, v49, vcc
	v_lshlrev_b32_e32 v49, 2, v49
	ds_bpermute_b32 v49, v49, v48
	s_waitcnt lgkmcnt(0)
	v_add_f32_e32 v48, v48, v49
	v_xor_b32_e32 v49, 32, v251
	v_cmp_lt_i32_e32 vcc, v49, v50
	s_nop 1
	v_cndmask_b32_e32 v49, v251, v49, vcc
	v_lshlrev_b32_e32 v49, 2, v49
	ds_bpermute_b32 v49, v49, v48
	s_and_saveexec_b64 s[16:17], s[4:5]
	s_cbranch_execz .LBB0_955
	v_lshlrev_b64 v[50:51], 8, v[146:147]
	v_lshl_add_u64 v[50:51], s[64:65], 0, v[50:51]
	v_lshl_add_u64 v[50:51], s[52:53], 2, v[50:51]
	s_lshl_b32 s18, s28, 2
	v_lshl_add_u64 v[50:51], v[50:51], 0, s[18:19]
	s_waitcnt lgkmcnt(0)
	v_add_f32_e32 v48, v48, v49
	global_store_dword v[50:51], v48, off

; __device__ __forceinline__ unsigned pk2(float lo, float hi) { f32x2 v = {lo, hi}; bf16x2_t b = __builtin_convertvector(v, bf16x2_t); return __builtin_bit_cast(unsigned, b); }
; __device__ __forceinline__ float bflo(unsigned w) { return __uint_as_float(w << 16); }
; __device__ __forceinline__ float bfhi(unsigned w) { return __uint_as_float(w & 0xffff0000u); }
;     __device__ __forceinline__ void operator()(const f32x4 (&acc)[2][2][4][2], const Unit& u, int wr, int wc, int fr, int fq) const {
;     ...
;                     if (bias) { v = (v + *(const f32x4*)(bias + col0 + cc)) * *(const f32x4*)(scale + col0 + cc); }
;                     f32x4 b;
;                     if (MODE >= 3) b = (f32x4){0.f, 0.f, 0.f, 0.f};
;                     else if (MODE == 0) b = __builtin_bit_cast(f32x4, cur[bj][n]);
;                     else { const unsigned w0 = n ? cur[bj][0].z : cur[bj][0].x, w1 = n ? cur[bj][0].w : cur[bj][0].y; b = (f32x4){bflo(w0), bfhi(w0), bflo(w1), bfhi(w1)}; }
;                     o[n] = b + v;
;                     if (MODE == 2 || MODE == 4) *(f32x4*)(out + off + cc) = o[n];
;                     ss += (o[n][0] * o[n][0] + o[n][1] * o[n][1]) + (o[n][2] * o[n][2] + o[n][3] * o[n][3]); }
;                 if (MODE != 2 && MODE != 4) { u32x4 w; w.x = pk2(o[0][0], o[0][1]); w.y = pk2(o[0][2], o[0][3]); w.z = pk2(o[1][0], o[1][1]); w.w = pk2(o[1][2], o[1][3]); *(u32x4*)(xb + off + bj * HALF) = w; } }
.LBB0_960:
	s_waitcnt vmcnt(15)
	v_pk_add_f32 v[92:93], v[92:93], v[44:45]
	v_or_b32_e32 v44, 16, v146
	v_ashrrev_i32_e32 v45, 31, v44
	v_pk_add_f32 v[46:47], v[94:95], v[46:47]
	v_lshlrev_b64 v[94:95], 12, v[44:45]
	s_waitcnt vmcnt(13)
	v_pk_add_f32 v[42:43], v[90:91], v[42:43]
	v_pk_add_f32 v[40:41], v[88:89], v[40:41]
	v_lshl_add_u64 v[88:89], s[62:63], 0, v[94:95]
	v_cvt_pk_bf16_f32 v100, v92, v93
	v_cvt_pk_bf16_f32 v101, v46, v47
	v_cvt_pk_bf16_f32 v102, v40, v41
	v_cvt_pk_bf16_f32 v103, v42, v43
	v_lshl_add_u64 v[88:89], v[192:193], 1, v[88:89]
	s_and_b64 vcc, exec, s[8:9]
	global_store_dwordx4 v[88:89], v[100:103], off sc0 sc1
	s_cbranch_vccnz .LBB0_962
	global_load_dwordx4 v[100:103], v[190:191], off offset:512
	s_waitcnt vmcnt(0)
	v_pk_add_f32 v[90:91], v[38:39], v[102:103]
	v_pk_add_f32 v[94:95], v[36:37], v[100:101]
	global_load_dwordx4 v[36:39], v[188:189], off offset:512
	s_waitcnt vmcnt(0)
	v_pk_mul_f32 v[38:39], v[90:91], v[38:39]
	v_pk_mul_f32 v[36:37], v[94:95], v[36:37]

; __device__ __forceinline__ unsigned pk2(float lo, float hi) { f32x2 v = {lo, hi}; bf16x2_t b = __builtin_convertvector(v, bf16x2_t); return __builtin_bit_cast(unsigned, b); }
;     __device__ __forceinline__ void operator()(const f32x4 (&acc)[2][2][4][2], const Unit& u, int wr, int wc, int fr, int fq) const {
;     ...
;                     o[n] = b + v;
;                     if (MODE == 2 || MODE == 4) *(f32x4*)(out + off + cc) = o[n];
;                     ss += (o[n][0] * o[n][0] + o[n][1] * o[n][1]) + (o[n][2] * o[n][2] + o[n][3] * o[n][3]); }
;                 if (MODE != 2 && MODE != 4) { u32x4 w; w.x = pk2(o[0][0], o[0][1]); w.y = pk2(o[0][2], o[0][3]); w.z = pk2(o[1][0], o[1][1]); w.w = pk2(o[1][2], o[1][3]); *(u32x4*)(xb + off + bj * HALF) = w; } }
;             if (MODE != 2 && MODE != 4 && rsq) { ss += __shfl_xor(ss, 16); ss += __shfl_xor(ss, 32); if (fq == 0) rsq[(size_t)row * 64 + u.pn * 4 + wc] = ss; }
.LBB0_964:
	s_waitcnt vmcnt(13)
	v_pk_add_f32 v[38:39], v[86:87], v[38:39]
	v_pk_add_f32 v[36:37], v[84:85], v[36:37]
	v_pk_add_f32 v[34:35], v[82:83], v[34:35]
	v_pk_add_f32 v[32:33], v[80:81], v[32:33]
	v_cvt_pk_bf16_f32 v80, v36, v37
	v_cvt_pk_bf16_f32 v81, v38, v39
	v_cvt_pk_bf16_f32 v82, v32, v33
	v_cvt_pk_bf16_f32 v83, v34, v35
	s_and_b64 vcc, exec, s[10:11]
	global_store_dwordx4 v[88:89], v[80:83], off offset:256 sc0 sc1
	s_cbranch_vccnz .LBB0_968
	v_mul_f32_e32 v41, v41, v41
	v_mul_f32_e32 v33, v33, v33
	v_mul_f32_e32 v80, v93, v93
	v_mul_f32_e32 v47, v47, v47
	v_fmac_f32_e32 v41, v40, v40
	v_mul_f32_e32 v40, v43, v43
	v_mul_f32_e32 v37, v37, v37
	v_fmac_f32_e32 v33, v32, v32
	v_mul_f32_e32 v32, v35, v35
	v_fmac_f32_e32 v80, v92, v92
	v_fmac_f32_e32 v47, v46, v46
	v_fmac_f32_e32 v40, v42, v42
	v_fmac_f32_e32 v37, v36, v36
	v_mul_f32_e32 v36, v39, v39
	v_fmac_f32_e32 v32, v34, v34
	v_and_b32_e32 v34, 64, v251
	v_add_f32_e32 v46, v80, v47
	v_add_f32_e32 v40, v41, v40
	v_fmac_f32_e32 v36, v38, v38
	v_add_f32_e32 v32, v33, v32
	v_xor_b32_e32 v33, 16, v251
	v_add_u32_e32 v34, 64, v34
	v_add_f32_e32 v40, v46, v40
	v_add_f32_e32 v36, v37, v36
	v_cmp_lt_i32_e32 vcc, v33, v34
	v_add_f32_e32 v36, v40, v36
	v_add_f32_e32 v32, v36, v32
	v_cndmask_b32_e32 v33, v251, v33, vcc
	v_lshlrev_b32_e32 v33, 2, v33
	ds_bpermute_b32 v33, v33, v32
	s_waitcnt lgkmcnt(0)
	v_add_f32_e32 v32, v32, v33
	v_xor_b32_e32 v33, 32, v251
	v_cmp_lt_i32_e32 vcc, v33, v34
	s_nop 1
	v_cndmask_b32_e32 v33, v251, v33, vcc
	v_lshlrev_b32_e32 v33, 2, v33
	ds_bpermute_b32 v33, v33, v32
	s_and_saveexec_b64 s[16:17], s[4:5]
	s_cbranch_execz .LBB0_967
	v_lshlrev_b64 v[34:35], 8, v[44:45]
	v_lshl_add_u64 v[34:35], s[64:65], 0, v[34:35]
	v_lshl_add_u64 v[34:35], s[52:53], 2, v[34:35]
	s_lshl_b32 s18, s28, 2
	v_lshl_add_u64 v[34:35], v[34:35], 0, s[18:19]
	s_waitcnt lgkmcnt(0)
	v_add_f32_e32 v32, v32, v33
	global_store_dword v[34:35], v32, off

; __device__ __forceinline__ unsigned pk2(float lo, float hi) { f32x2 v = {lo, hi}; bf16x2_t b = __builtin_convertvector(v, bf16x2_t); return __builtin_bit_cast(unsigned, b); }
; __device__ __forceinline__ float bflo(unsigned w) { return __uint_as_float(w << 16); }
; __device__ __forceinline__ float bfhi(unsigned w) { return __uint_as_float(w & 0xffff0000u); }
;     __device__ __forceinline__ void operator()(const f32x4 (&acc)[2][2][4][2], const Unit& u, int wr, int wc, int fr, int fq) const {
;     ...
;                     if (bias) { v = (v + *(const f32x4*)(bias + col0 + cc)) * *(const f32x4*)(scale + col0 + cc); }
;                     f32x4 b;
;                     if (MODE >= 3) b = (f32x4){0.f, 0.f, 0.f, 0.f};
;                     else if (MODE == 0) b = __builtin_bit_cast(f32x4, cur[bj][n]);
;                     else { const unsigned w0 = n ? cur[bj][0].z : cur[bj][0].x, w1 = n ? cur[bj][0].w : cur[bj][0].y; b = (f32x4){bflo(w0), bfhi(w0), bflo(w1), bfhi(w1)}; }
;                     o[n] = b + v;
;                     if (MODE == 2 || MODE == 4) *(f32x4*)(out + off + cc) = o[n];
;                     ss += (o[n][0] * o[n][0] + o[n][1] * o[n][1]) + (o[n][2] * o[n][2] + o[n][3] * o[n][3]); }
;                 if (MODE != 2 && MODE != 4) { u32x4 w; w.x = pk2(o[0][0], o[0][1]); w.y = pk2(o[0][2], o[0][3]); w.z = pk2(o[1][0], o[1][1]); w.w = pk2(o[1][2], o[1][3]); *(u32x4*)(xb + off + bj * HALF) = w; } }
.LBB0_972:
	s_waitcnt lgkmcnt(0)
	v_lshlrev_b64 v[32:33], 12, v[114:115]
	s_waitcnt vmcnt(10)
	v_pk_add_f32 v[30:31], v[78:79], v[30:31]
	v_pk_add_f32 v[28:29], v[76:77], v[28:29]
	v_pk_add_f32 v[26:27], v[74:75], v[26:27]
	v_pk_add_f32 v[24:25], v[72:73], v[24:25]
	v_lshl_add_u64 v[32:33], s[62:63], 0, v[32:33]
	v_cvt_pk_bf16_f32 v34, v28, v29
	v_cvt_pk_bf16_f32 v35, v30, v31
	v_cvt_pk_bf16_f32 v36, v24, v25
	v_cvt_pk_bf16_f32 v37, v26, v27
	v_lshl_add_u64 v[32:33], v[192:193], 1, v[32:33]
	s_and_b64 vcc, exec, s[8:9]
	global_store_dwordx4 v[32:33], v[34:37], off sc0 sc1
	s_cbranch_vccnz .LBB0_974
	global_load_dwordx4 v[34:37], v[190:191], off offset:512
	s_waitcnt vmcnt(0)
	v_pk_add_f32 v[36:37], v[22:23], v[36:37]
	v_pk_add_f32 v[34:35], v[20:21], v[34:35]
	global_load_dwordx4 v[20:23], v[188:189], off offset:512
	s_waitcnt vmcnt(0)
	v_pk_mul_f32 v[22:23], v[36:37], v[22:23]
	v_pk_mul_f32 v[20:21], v[34:35], v[20:21]

; __device__ __forceinline__ unsigned pk2(float lo, float hi) { f32x2 v = {lo, hi}; bf16x2_t b = __builtin_convertvector(v, bf16x2_t); return __builtin_bit_cast(unsigned, b); }
;     __device__ __forceinline__ void operator()(const f32x4 (&acc)[2][2][4][2], const Unit& u, int wr, int wc, int fr, int fq) const {
;     ...
;                     o[n] = b + v;
;                     if (MODE == 2 || MODE == 4) *(f32x4*)(out + off + cc) = o[n];
;                     ss += (o[n][0] * o[n][0] + o[n][1] * o[n][1]) + (o[n][2] * o[n][2] + o[n][3] * o[n][3]); }
;                 if (MODE != 2 && MODE != 4) { u32x4 w; w.x = pk2(o[0][0], o[0][1]); w.y = pk2(o[0][2], o[0][3]); w.z = pk2(o[1][0], o[1][1]); w.w = pk2(o[1][2], o[1][3]); *(u32x4*)(xb + off + bj * HALF) = w; } }
;             if (MODE != 2 && MODE != 4 && rsq) { ss += __shfl_xor(ss, 16); ss += __shfl_xor(ss, 32); if (fq == 0) rsq[(size_t)row * 64 + u.pn * 4 + wc] = ss; }
.LBB0_976:
	s_waitcnt vmcnt(9)
	v_pk_add_f32 v[22:23], v[70:71], v[22:23]
	v_pk_add_f32 v[20:21], v[68:69], v[20:21]
	v_pk_add_f32 v[18:19], v[66:67], v[18:19]
	v_pk_add_f32 v[16:17], v[64:65], v[16:17]
	v_cvt_pk_bf16_f32 v34, v20, v21
	v_cvt_pk_bf16_f32 v35, v22, v23
	v_cvt_pk_bf16_f32 v36, v16, v17
	v_cvt_pk_bf16_f32 v37, v18, v19
	s_and_b64 vcc, exec, s[10:11]
	global_store_dwordx4 v[32:33], v[34:37], off offset:256 sc0 sc1
	s_cbranch_vccnz .LBB0_980
	v_mul_f32_e32 v29, v29, v29
	v_mul_f32_e32 v25, v25, v25
	v_mul_f32_e32 v17, v17, v17
	v_fmac_f32_e32 v29, v28, v28
	v_mul_f32_e32 v28, v31, v31
	v_fmac_f32_e32 v25, v24, v24
	v_mul_f32_e32 v24, v27, v27
	v_mul_f32_e32 v21, v21, v21
	v_fmac_f32_e32 v17, v16, v16
	v_mul_f32_e32 v16, v19, v19
	v_fmac_f32_e32 v28, v30, v30
	v_fmac_f32_e32 v24, v26, v26
	v_fmac_f32_e32 v21, v20, v20
	v_mul_f32_e32 v20, v23, v23
	v_fmac_f32_e32 v16, v18, v18
	v_and_b32_e32 v18, 64, v251
	v_add_f32_e32 v28, v29, v28
	v_add_f32_e32 v24, v25, v24
	v_fmac_f32_e32 v20, v22, v22
	v_add_f32_e32 v16, v17, v16
	v_xor_b32_e32 v17, 16, v251
	v_add_u32_e32 v18, 64, v18
	v_add_f32_e32 v24, v28, v24
	v_add_f32_e32 v20, v21, v20
	v_cmp_lt_i32_e32 vcc, v17, v18
	v_add_f32_e32 v20, v24, v20
	v_add_f32_e32 v16, v20, v16
	v_cndmask_b32_e32 v17, v251, v17, vcc
	v_lshlrev_b32_e32 v17, 2, v17
	ds_bpermute_b32 v17, v17, v16
	s_waitcnt lgkmcnt(0)
	v_add_f32_e32 v16, v16, v17
	v_xor_b32_e32 v17, 32, v251
	v_cmp_lt_i32_e32 vcc, v17, v18
	s_nop 1
	v_cndmask_b32_e32 v17, v251, v17, vcc
	v_lshlrev_b32_e32 v17, 2, v17
	ds_bpermute_b32 v17, v17, v16
	s_and_saveexec_b64 s[16:17], s[4:5]
	s_cbranch_execz .LBB0_979
	v_lshlrev_b64 v[18:19], 8, v[114:115]
	v_lshl_add_u64 v[18:19], s[64:65], 0, v[18:19]
	v_lshl_add_u64 v[18:19], s[52:53], 2, v[18:19]
	s_lshl_b32 s18, s28, 2
	v_lshl_add_u64 v[18:19], v[18:19], 0, s[18:19]
	s_waitcnt lgkmcnt(0)
	v_add_f32_e32 v16, v16, v17
	global_store_dword v[18:19], v16, off

; __device__ __forceinline__ unsigned pk2(float lo, float hi) { f32x2 v = {lo, hi}; bf16x2_t b = __builtin_convertvector(v, bf16x2_t); return __builtin_bit_cast(unsigned, b); }
; __device__ __forceinline__ float bflo(unsigned w) { return __uint_as_float(w << 16); }
; __device__ __forceinline__ float bfhi(unsigned w) { return __uint_as_float(w & 0xffff0000u); }
;     __device__ __forceinline__ void operator()(const f32x4 (&acc)[2][2][4][2], const Unit& u, int wr, int wc, int fr, int fq) const {
;     ...
;                     if (bias) { v = (v + *(const f32x4*)(bias + col0 + cc)) * *(const f32x4*)(scale + col0 + cc); }
;                     f32x4 b;
;                     if (MODE >= 3) b = (f32x4){0.f, 0.f, 0.f, 0.f};
;                     else if (MODE == 0) b = __builtin_bit_cast(f32x4, cur[bj][n]);
;                     else { const unsigned w0 = n ? cur[bj][0].z : cur[bj][0].x, w1 = n ? cur[bj][0].w : cur[bj][0].y; b = (f32x4){bflo(w0), bfhi(w0), bflo(w1), bfhi(w1)}; }
;                     o[n] = b + v;
;                     if (MODE == 2 || MODE == 4) *(f32x4*)(out + off + cc) = o[n];
;                     ss += (o[n][0] * o[n][0] + o[n][1] * o[n][1]) + (o[n][2] * o[n][2] + o[n][3] * o[n][3]); }
;                 if (MODE != 2 && MODE != 4) { u32x4 w; w.x = pk2(o[0][0], o[0][1]); w.y = pk2(o[0][2], o[0][3]); w.z = pk2(o[1][0], o[1][1]); w.w = pk2(o[1][2], o[1][3]); *(u32x4*)(xb + off + bj * HALF) = w; } }
.LBB0_984:
	s_waitcnt lgkmcnt(0)
	v_lshlrev_b64 v[16:17], 12, v[98:99]
	s_waitcnt vmcnt(6)
	v_pk_add_f32 v[14:15], v[62:63], v[14:15]
	v_pk_add_f32 v[12:13], v[60:61], v[12:13]
	v_pk_add_f32 v[10:11], v[58:59], v[10:11]
	v_pk_add_f32 v[8:9], v[56:57], v[8:9]
	v_lshl_add_u64 v[16:17], s[62:63], 0, v[16:17]
	v_cvt_pk_bf16_f32 v18, v12, v13
	v_cvt_pk_bf16_f32 v19, v14, v15
	v_cvt_pk_bf16_f32 v20, v8, v9
	v_cvt_pk_bf16_f32 v21, v10, v11
	v_lshl_add_u64 v[16:17], v[192:193], 1, v[16:17]
	s_and_b64 vcc, exec, s[8:9]
	global_store_dwordx4 v[16:17], v[18:21], off sc0 sc1
	s_cbranch_vccnz .LBB0_986
	global_load_dwordx4 v[18:21], v[190:191], off offset:512
	s_waitcnt vmcnt(0)
	v_pk_add_f32 v[20:21], v[6:7], v[20:21]
	v_pk_add_f32 v[18:19], v[4:5], v[18:19]
	global_load_dwordx4 v[4:7], v[188:189], off offset:512
	s_waitcnt vmcnt(0)
	v_pk_mul_f32 v[6:7], v[20:21], v[6:7]
	v_pk_mul_f32 v[4:5], v[18:19], v[4:5]

; __device__ __forceinline__ unsigned pk2(float lo, float hi) { f32x2 v = {lo, hi}; bf16x2_t b = __builtin_convertvector(v, bf16x2_t); return __builtin_bit_cast(unsigned, b); }
;     __device__ __forceinline__ void operator()(const f32x4 (&acc)[2][2][4][2], const Unit& u, int wr, int wc, int fr, int fq) const {
;     ...
;                     o[n] = b + v;
;                     if (MODE == 2 || MODE == 4) *(f32x4*)(out + off + cc) = o[n];
;                     ss += (o[n][0] * o[n][0] + o[n][1] * o[n][1]) + (o[n][2] * o[n][2] + o[n][3] * o[n][3]); }
;                 if (MODE != 2 && MODE != 4) { u32x4 w; w.x = pk2(o[0][0], o[0][1]); w.y = pk2(o[0][2], o[0][3]); w.z = pk2(o[1][0], o[1][1]); w.w = pk2(o[1][2], o[1][3]); *(u32x4*)(xb + off + bj * HALF) = w; } }
;             if (MODE != 2 && MODE != 4 && rsq) { ss += __shfl_xor(ss, 16); ss += __shfl_xor(ss, 32); if (fq == 0) rsq[(size_t)row * 64 + u.pn * 4 + wc] = ss; }
.LBB0_988:
	s_waitcnt vmcnt(5)
	v_pk_add_f32 v[6:7], v[54:55], v[6:7]
	v_pk_add_f32 v[4:5], v[52:53], v[4:5]
	v_pk_add_f32 v[2:3], v[50:51], v[2:3]
	v_pk_add_f32 v[0:1], v[48:49], v[0:1]
	v_cvt_pk_bf16_f32 v18, v4, v5
	v_cvt_pk_bf16_f32 v19, v6, v7
	v_cvt_pk_bf16_f32 v20, v0, v1
	v_cvt_pk_bf16_f32 v21, v2, v3
	s_and_b64 vcc, exec, s[10:11]
	global_store_dwordx4 v[16:17], v[18:21], off offset:256 sc0 sc1
	s_cbranch_vccnz .LBB0_992
	v_mul_f32_e32 v13, v13, v13
	v_mul_f32_e32 v9, v9, v9
	v_mul_f32_e32 v1, v1, v1
	v_fmac_f32_e32 v13, v12, v12
	v_mul_f32_e32 v12, v15, v15
	v_fmac_f32_e32 v9, v8, v8
	v_mul_f32_e32 v8, v11, v11
	v_mul_f32_e32 v5, v5, v5
	v_fmac_f32_e32 v1, v0, v0
	v_mul_f32_e32 v0, v3, v3
	v_fmac_f32_e32 v12, v14, v14
	v_fmac_f32_e32 v8, v10, v10
	v_fmac_f32_e32 v5, v4, v4
	v_mul_f32_e32 v4, v7, v7
	v_fmac_f32_e32 v0, v2, v2
	v_and_b32_e32 v2, 64, v251
	v_add_f32_e32 v12, v13, v12
	v_add_f32_e32 v8, v9, v8
	v_fmac_f32_e32 v4, v6, v6
	v_add_f32_e32 v0, v1, v0
	v_xor_b32_e32 v1, 16, v251
	v_add_u32_e32 v2, 64, v2
	v_add_f32_e32 v8, v12, v8
	v_add_f32_e32 v4, v5, v4
	v_cmp_lt_i32_e32 vcc, v1, v2
	v_add_f32_e32 v4, v8, v4
	v_add_f32_e32 v0, v4, v0
	v_cndmask_b32_e32 v1, v251, v1, vcc
	v_lshlrev_b32_e32 v1, 2, v1
	ds_bpermute_b32 v1, v1, v0
	s_waitcnt lgkmcnt(0)
	v_add_f32_e32 v0, v0, v1
	v_xor_b32_e32 v1, 32, v251
	v_cmp_lt_i32_e32 vcc, v1, v2
	s_nop 1
	v_cndmask_b32_e32 v1, v251, v1, vcc
	v_lshlrev_b32_e32 v1, 2, v1
	ds_bpermute_b32 v1, v1, v0
	s_and_saveexec_b64 s[8:9], s[4:5]
	s_cbranch_execz .LBB0_991
	v_lshlrev_b64 v[2:3], 8, v[98:99]
	v_lshl_add_u64 v[2:3], s[64:65], 0, v[2:3]
	v_lshl_add_u64 v[2:3], s[52:53], 2, v[2:3]
	s_lshl_b32 s18, s28, 2
	v_lshl_add_u64 v[2:3], v[2:3], 0, s[18:19]
	s_waitcnt lgkmcnt(0)
	v_add_f32_e32 v0, v0, v1
	global_store_dword v[2:3], v0, off

; __device__ __forceinline__ unsigned pk2(float lo, float hi) { f32x2 v = {lo, hi}; bf16x2_t b = __builtin_convertvector(v, bf16x2_t); return __builtin_bit_cast(unsigned, b); }
; __device__ __forceinline__ float bflo(unsigned w) { return __uint_as_float(w << 16); }
; __device__ __forceinline__ float bfhi(unsigned w) { return __uint_as_float(w & 0xffff0000u); }
;     __device__ __forceinline__ void operator()(const f32x4 (&acc)[2][2][4][2], const Unit& u, int wr, int wc, int fr, int fq) const {
;     ...
;                 for (int n = 0; n < 2; ++n) { const int cc = bj * HALF + 4 * n;
;                     f32x4 v = acc[ai][bj][m][n];
;                     if (bias) { v = (v + *(const f32x4*)(bias + col0 + cc)) * *(const f32x4*)(scale + col0 + cc); }
;                     f32x4 b;
;                     if (MODE >= 3) b = (f32x4){0.f, 0.f, 0.f, 0.f};
;                     else if (MODE == 0) b = __builtin_bit_cast(f32x4, cur[bj][n]);
;                     else { const unsigned w0 = n ? cur[bj][0].z : cur[bj][0].x, w1 = n ? cur[bj][0].w : cur[bj][0].y; b = (f32x4){bflo(w0), bfhi(w0), bflo(w1), bfhi(w1)}; }
;                     o[n] = b + v;
;                     if (MODE == 2 || MODE == 4) *(f32x4*)(out + off + cc) = o[n];
;                     ss += (o[n][0] * o[n][0] + o[n][1] * o[n][1]) + (o[n][2] * o[n][2] + o[n][3] * o[n][3]); }
;                 if (MODE != 2 && MODE != 4) { u32x4 w; w.x = pk2(o[0][0], o[0][1]); w.y = pk2(o[0][2], o[0][3]); w.z = pk2(o[1][0], o[1][1]); w.w = pk2(o[1][2], o[1][3]); *(u32x4*)(xb + off + bj * HALF) = w; } }
;             if (MODE != 2 && MODE != 4 && rsq) { ss += __shfl_xor(ss, 16); ss += __shfl_xor(ss, 32); if (fq == 0) rsq[(size_t)row * 64 + u.pn * 4 + wc] = ss; }
.LBB0_1373:
	v_lshl_add_u32 v142, s43, 8, v149
	v_ashrrev_i32_e32 v143, 31, v142
	v_lshl_or_b32 v140, s18, 8, v151
	v_lshlrev_b64 v[146:147], 12, v[142:143]
	v_ashrrev_i32_e32 v141, 31, v140
	v_pk_add_f32 v[144:145], v[114:115], 0 op_sel_hi:[1,0]
	v_pk_add_f32 v[114:115], v[120:121], 0 op_sel_hi:[1,0]
	v_pk_add_f32 v[120:121], v[118:119], 0 op_sel_hi:[1,0]
	v_lshl_add_u64 v[118:119], s[10:11], 0, v[146:147]
	s_lshl_b32 s16, s18, 2
	v_pk_add_f32 v[116:117], v[116:117], 0 op_sel_hi:[1,0]
	v_lshl_add_u64 v[158:159], v[140:141], 1, v[118:119]
	v_pk_add_f32 v[124:125], v[124:125], 0 op_sel_hi:[1,0]
	v_pk_add_f32 v[146:147], v[122:123], 0 op_sel_hi:[1,0]
	v_pk_add_f32 v[118:119], v[128:129], 0 op_sel_hi:[1,0]
	v_pk_add_f32 v[122:123], v[126:127], 0 op_sel_hi:[1,0]
	v_cndmask_b32_e64 v153, 0, 1, s[56:57]
	s_ashr_i32 s17, s16, 31
	v_cvt_pk_bf16_f32 v154, v144, v145
	v_cvt_pk_bf16_f32 v155, v116, v117
	v_cvt_pk_bf16_f32 v156, v120, v121
	v_cvt_pk_bf16_f32 v157, v114, v115
	v_cvt_pk_bf16_f32 v126, v146, v147
	v_cvt_pk_bf16_f32 v127, v124, v125
	v_cvt_pk_bf16_f32 v128, v122, v123
	v_cvt_pk_bf16_f32 v129, v118, v119
	v_cmp_ne_u32_e64 s[8:9], 1, v153
	s_andn2_b64 vcc, exec, s[56:57]
	global_store_dwordx4 v[158:159], v[154:157], off sc0 sc1
	global_store_dwordx4 v[158:159], v[126:129], off offset:256 sc0 sc1
	s_cbranch_vccnz .LBB0_1377
	s_nop 0
	v_mul_f32_e32 v126, v145, v145
	v_mul_f32_e32 v117, v117, v117
	v_fmac_f32_e32 v126, v144, v144
	v_fmac_f32_e32 v117, v116, v116
	v_add_f32_e32 v116, v126, v117
	v_mul_f32_e32 v117, v121, v121
	v_mul_f32_e32 v115, v115, v115
	v_fmac_f32_e32 v117, v120, v120
	v_fmac_f32_e32 v115, v114, v114
	v_add_f32_e32 v114, v117, v115
	v_add_f32_e32 v114, v116, v114
	v_mul_f32_e32 v115, v147, v147
	v_mul_f32_e32 v116, v125, v125
	v_fmac_f32_e32 v115, v146, v146
	v_fmac_f32_e32 v116, v124, v124
	v_add_f32_e32 v115, v115, v116
	v_add_f32_e32 v114, v114, v115
	v_mul_f32_e32 v115, v123, v123
	v_mul_f32_e32 v116, v119, v119
	v_fmac_f32_e32 v115, v122, v122
	v_fmac_f32_e32 v116, v118, v118
	v_add_f32_e32 v115, v115, v116
	v_and_b32_e32 v116, 64, v251
	v_add_f32_e32 v114, v114, v115
	v_xor_b32_e32 v115, 16, v251
	v_add_u32_e32 v116, 64, v116
	v_cmp_lt_i32_e32 vcc, v115, v116
	s_nop 1
	v_cndmask_b32_e32 v115, v251, v115, vcc
	v_lshlrev_b32_e32 v115, 2, v115
	ds_bpermute_b32 v115, v115, v114
	s_waitcnt lgkmcnt(0)
	v_add_f32_e32 v114, v114, v115
	v_xor_b32_e32 v115, 32, v251
	v_cmp_lt_i32_e32 vcc, v115, v116
	s_nop 1
	v_cndmask_b32_e32 v115, v251, v115, vcc
	v_lshlrev_b32_e32 v115, 2, v115
	ds_bpermute_b32 v115, v115, v114
	s_and_saveexec_b64 s[54:55], s[4:5]
	s_cbranch_execz .LBB0_1376
	v_lshlrev_b64 v[116:117], 8, v[142:143]
	v_lshl_add_u64 v[116:117], s[14:15], 0, v[116:117]
	v_lshl_add_u64 v[116:117], s[16:17], 2, v[116:117]
	s_lshl_b32 s18, s2, 2
	v_lshl_add_u64 v[116:117], v[116:117], 0, s[18:19]
	s_waitcnt lgkmcnt(0)
	v_add_f32_e32 v114, v114, v115
	global_store_dword v[116:117], v114, off

; __device__ __forceinline__ unsigned pk2(float lo, float hi) { f32x2 v = {lo, hi}; bf16x2_t b = __builtin_convertvector(v, bf16x2_t); return __builtin_bit_cast(unsigned, b); }
; __device__ __forceinline__ float bflo(unsigned w) { return __uint_as_float(w << 16); }
; __device__ __forceinline__ float bfhi(unsigned w) { return __uint_as_float(w & 0xffff0000u); }
;     __device__ __forceinline__ void operator()(const f32x4 (&acc)[2][2][4][2], const Unit& u, int wr, int wc, int fr, int fq) const {
;     ...
;                 for (int n = 0; n < 2; ++n) { const int cc = bj * HALF + 4 * n;
;                     f32x4 v = acc[ai][bj][m][n];
;                     if (bias) { v = (v + *(const f32x4*)(bias + col0 + cc)) * *(const f32x4*)(scale + col0 + cc); }
;                     f32x4 b;
;                     if (MODE >= 3) b = (f32x4){0.f, 0.f, 0.f, 0.f};
;                     else if (MODE == 0) b = __builtin_bit_cast(f32x4, cur[bj][n]);
;                     else { const unsigned w0 = n ? cur[bj][0].z : cur[bj][0].x, w1 = n ? cur[bj][0].w : cur[bj][0].y; b = (f32x4){bflo(w0), bfhi(w0), bflo(w1), bfhi(w1)}; }
;                     o[n] = b + v;
;                     if (MODE == 2 || MODE == 4) *(f32x4*)(out + off + cc) = o[n];
;                     ss += (o[n][0] * o[n][0] + o[n][1] * o[n][1]) + (o[n][2] * o[n][2] + o[n][3] * o[n][3]); }
;                 if (MODE != 2 && MODE != 4) { u32x4 w; w.x = pk2(o[0][0], o[0][1]); w.y = pk2(o[0][2], o[0][3]); w.z = pk2(o[1][0], o[1][1]); w.w = pk2(o[1][2], o[1][3]); *(u32x4*)(xb + off + bj * HALF) = w; } }
;             if (MODE != 2 && MODE != 4 && rsq) { ss += __shfl_xor(ss, 16); ss += __shfl_xor(ss, 32); if (fq == 0) rsq[(size_t)row * 64 + u.pn * 4 + wc] = ss; }
.LBB0_1377:
	v_or_b32_e32 v114, 16, v142
	s_waitcnt lgkmcnt(0)
	v_ashrrev_i32_e32 v115, 31, v114
	v_lshlrev_b64 v[122:123], 12, v[114:115]
	v_pk_add_f32 v[100:101], v[100:101], 0 op_sel_hi:[1,0]
	v_pk_add_f32 v[116:117], v[98:99], 0 op_sel_hi:[1,0]
	v_pk_add_f32 v[98:99], v[104:105], 0 op_sel_hi:[1,0]
	v_pk_add_f32 v[104:105], v[102:103], 0 op_sel_hi:[1,0]
	v_lshl_add_u64 v[102:103], s[10:11], 0, v[122:123]
	v_cvt_pk_bf16_f32 v118, v116, v117
	v_cvt_pk_bf16_f32 v119, v100, v101
	v_cvt_pk_bf16_f32 v120, v104, v105
	v_cvt_pk_bf16_f32 v121, v98, v99
	v_lshl_add_u64 v[122:123], v[140:141], 1, v[102:103]
	global_store_dwordx4 v[122:123], v[118:121], off sc0 sc1
	v_pk_add_f32 v[108:109], v[108:109], 0 op_sel_hi:[1,0]
	v_pk_add_f32 v[102:103], v[112:113], 0 op_sel_hi:[1,0]
	v_pk_add_f32 v[118:119], v[106:107], 0 op_sel_hi:[1,0]
	v_pk_add_f32 v[106:107], v[110:111], 0 op_sel_hi:[1,0]
	v_cvt_pk_bf16_f32 v110, v118, v119
	v_cvt_pk_bf16_f32 v111, v108, v109
	v_cvt_pk_bf16_f32 v112, v106, v107
	v_cvt_pk_bf16_f32 v113, v102, v103
	s_and_b64 vcc, exec, s[8:9]
	global_store_dwordx4 v[122:123], v[110:113], off offset:256 sc0 sc1
	s_cbranch_vccnz .LBB0_1381
	s_nop 0
	v_mul_f32_e32 v110, v117, v117
	v_mul_f32_e32 v101, v101, v101
	v_fmac_f32_e32 v110, v116, v116
	v_fmac_f32_e32 v101, v100, v100
	v_add_f32_e32 v100, v110, v101
	v_mul_f32_e32 v101, v105, v105
	v_mul_f32_e32 v99, v99, v99
	v_fmac_f32_e32 v101, v104, v104
	v_fmac_f32_e32 v99, v98, v98
	v_add_f32_e32 v98, v101, v99
	v_add_f32_e32 v98, v100, v98
	v_mul_f32_e32 v99, v119, v119
	v_mul_f32_e32 v100, v109, v109
	v_fmac_f32_e32 v99, v118, v118
	v_fmac_f32_e32 v100, v108, v108
	v_add_f32_e32 v99, v99, v100
	v_add_f32_e32 v98, v98, v99
	v_mul_f32_e32 v99, v107, v107
	v_mul_f32_e32 v100, v103, v103
	v_fmac_f32_e32 v99, v106, v106
	v_fmac_f32_e32 v100, v102, v102
	v_add_f32_e32 v99, v99, v100
	v_and_b32_e32 v100, 64, v251
	v_add_f32_e32 v98, v98, v99
	v_xor_b32_e32 v99, 16, v251
	v_add_u32_e32 v100, 64, v100
	v_cmp_lt_i32_e32 vcc, v99, v100
	s_nop 1
	v_cndmask_b32_e32 v99, v251, v99, vcc
	v_lshlrev_b32_e32 v99, 2, v99
	ds_bpermute_b32 v99, v99, v98
	s_waitcnt lgkmcnt(0)
	v_add_f32_e32 v98, v98, v99
	v_xor_b32_e32 v99, 32, v251
	v_cmp_lt_i32_e32 vcc, v99, v100
	s_nop 1
	v_cndmask_b32_e32 v99, v251, v99, vcc
	v_lshlrev_b32_e32 v99, 2, v99
	ds_bpermute_b32 v99, v99, v98
	s_and_saveexec_b64 s[54:55], s[4:5]
	s_cbranch_execz .LBB0_1380
	v_lshlrev_b64 v[100:101], 8, v[114:115]
	v_lshl_add_u64 v[100:101], s[14:15], 0, v[100:101]
	v_lshl_add_u64 v[100:101], s[16:17], 2, v[100:101]
	s_lshl_b32 s18, s2, 2
	v_lshl_add_u64 v[100:101], v[100:101], 0, s[18:19]
	s_waitcnt lgkmcnt(0)
	v_add_f32_e32 v98, v98, v99
	global_store_dword v[100:101], v98, off

; __device__ __forceinline__ unsigned pk2(float lo, float hi) { f32x2 v = {lo, hi}; bf16x2_t b = __builtin_convertvector(v, bf16x2_t); return __builtin_bit_cast(unsigned, b); }
; __device__ __forceinline__ float bflo(unsigned w) { return __uint_as_float(w << 16); }
; __device__ __forceinline__ float bfhi(unsigned w) { return __uint_as_float(w & 0xffff0000u); }
;     __device__ __forceinline__ void operator()(const f32x4 (&acc)[2][2][4][2], const Unit& u, int wr, int wc, int fr, int fq) const {
;     ...
;                 for (int n = 0; n < 2; ++n) { const int cc = bj * HALF + 4 * n;
;                     f32x4 v = acc[ai][bj][m][n];
;                     if (bias) { v = (v + *(const f32x4*)(bias + col0 + cc)) * *(const f32x4*)(scale + col0 + cc); }
;                     f32x4 b;
;                     if (MODE >= 3) b = (f32x4){0.f, 0.f, 0.f, 0.f};
;                     else if (MODE == 0) b = __builtin_bit_cast(f32x4, cur[bj][n]);
;                     else { const unsigned w0 = n ? cur[bj][0].z : cur[bj][0].x, w1 = n ? cur[bj][0].w : cur[bj][0].y; b = (f32x4){bflo(w0), bfhi(w0), bflo(w1), bfhi(w1)}; }
;                     o[n] = b + v;
;                     if (MODE == 2 || MODE == 4) *(f32x4*)(out + off + cc) = o[n];
;                     ss += (o[n][0] * o[n][0] + o[n][1] * o[n][1]) + (o[n][2] * o[n][2] + o[n][3] * o[n][3]); }
;                 if (MODE != 2 && MODE != 4) { u32x4 w; w.x = pk2(o[0][0], o[0][1]); w.y = pk2(o[0][2], o[0][3]); w.z = pk2(o[1][0], o[1][1]); w.w = pk2(o[1][2], o[1][3]); *(u32x4*)(xb + off + bj * HALF) = w; } }
;             if (MODE != 2 && MODE != 4 && rsq) { ss += __shfl_xor(ss, 16); ss += __shfl_xor(ss, 32); if (fq == 0) rsq[(size_t)row * 64 + u.pn * 4 + wc] = ss; }
.LBB0_1381:
	v_or_b32_e32 v98, 32, v142
	s_waitcnt lgkmcnt(0)
	v_ashrrev_i32_e32 v99, 31, v98
	v_lshlrev_b64 v[106:107], 12, v[98:99]
	v_pk_add_f32 v[82:83], v[82:83], 0 op_sel_hi:[1,0]
	v_pk_add_f32 v[100:101], v[80:81], 0 op_sel_hi:[1,0]
	v_pk_add_f32 v[80:81], v[86:87], 0 op_sel_hi:[1,0]
	v_pk_add_f32 v[86:87], v[84:85], 0 op_sel_hi:[1,0]
	v_lshl_add_u64 v[84:85], s[10:11], 0, v[106:107]
	v_cvt_pk_bf16_f32 v102, v100, v101
	v_cvt_pk_bf16_f32 v103, v82, v83
	v_cvt_pk_bf16_f32 v104, v86, v87
	v_cvt_pk_bf16_f32 v105, v80, v81
	v_lshl_add_u64 v[106:107], v[140:141], 1, v[84:85]
	global_store_dwordx4 v[106:107], v[102:105], off sc0 sc1
	v_pk_add_f32 v[90:91], v[90:91], 0 op_sel_hi:[1,0]
	v_pk_add_f32 v[84:85], v[94:95], 0 op_sel_hi:[1,0]
	v_pk_add_f32 v[102:103], v[88:89], 0 op_sel_hi:[1,0]
	v_pk_add_f32 v[88:89], v[92:93], 0 op_sel_hi:[1,0]
	v_cvt_pk_bf16_f32 v92, v102, v103
	v_cvt_pk_bf16_f32 v93, v90, v91
	v_cvt_pk_bf16_f32 v94, v88, v89
	v_cvt_pk_bf16_f32 v95, v84, v85
	s_and_b64 vcc, exec, s[8:9]
	global_store_dwordx4 v[106:107], v[92:95], off offset:256 sc0 sc1
	s_cbranch_vccnz .LBB0_1385
	s_nop 0
	v_mul_f32_e32 v92, v101, v101
	v_mul_f32_e32 v83, v83, v83
	v_fmac_f32_e32 v92, v100, v100
	v_fmac_f32_e32 v83, v82, v82
	v_add_f32_e32 v82, v92, v83
	v_mul_f32_e32 v83, v87, v87
	v_mul_f32_e32 v81, v81, v81
	v_fmac_f32_e32 v83, v86, v86
	v_fmac_f32_e32 v81, v80, v80
	v_add_f32_e32 v80, v83, v81
	v_add_f32_e32 v80, v82, v80
	v_mul_f32_e32 v81, v103, v103
	v_mul_f32_e32 v82, v91, v91
	v_fmac_f32_e32 v81, v102, v102
	v_fmac_f32_e32 v82, v90, v90
	v_add_f32_e32 v81, v81, v82
	v_add_f32_e32 v80, v80, v81
	v_mul_f32_e32 v81, v89, v89
	v_mul_f32_e32 v82, v85, v85
	v_fmac_f32_e32 v81, v88, v88
	v_fmac_f32_e32 v82, v84, v84
	v_add_f32_e32 v81, v81, v82
	v_and_b32_e32 v82, 64, v251
	v_add_f32_e32 v80, v80, v81
	v_xor_b32_e32 v81, 16, v251
	v_add_u32_e32 v82, 64, v82
	v_cmp_lt_i32_e32 vcc, v81, v82
	s_nop 1
	v_cndmask_b32_e32 v81, v251, v81, vcc
	v_lshlrev_b32_e32 v81, 2, v81
	ds_bpermute_b32 v81, v81, v80
	s_waitcnt lgkmcnt(0)
	v_add_f32_e32 v80, v80, v81
	v_xor_b32_e32 v81, 32, v251
	v_cmp_lt_i32_e32 vcc, v81, v82
	s_nop 1
	v_cndmask_b32_e32 v81, v251, v81, vcc
	v_lshlrev_b32_e32 v81, 2, v81
	ds_bpermute_b32 v81, v81, v80
	s_and_saveexec_b64 s[54:55], s[4:5]
	s_cbranch_execz .LBB0_1384
	v_lshlrev_b64 v[82:83], 8, v[98:99]
	v_lshl_add_u64 v[82:83], s[14:15], 0, v[82:83]
	v_lshl_add_u64 v[82:83], s[16:17], 2, v[82:83]
	s_lshl_b32 s18, s2, 2
	v_lshl_add_u64 v[82:83], v[82:83], 0, s[18:19]
	s_waitcnt lgkmcnt(0)
	v_add_f32_e32 v80, v80, v81
	global_store_dword v[82:83], v80, off

; __device__ __forceinline__ unsigned pk2(float lo, float hi) { f32x2 v = {lo, hi}; bf16x2_t b = __builtin_convertvector(v, bf16x2_t); return __builtin_bit_cast(unsigned, b); }
; __device__ __forceinline__ float bflo(unsigned w) { return __uint_as_float(w << 16); }
; __device__ __forceinline__ float bfhi(unsigned w) { return __uint_as_float(w & 0xffff0000u); }
;     __device__ __forceinline__ void operator()(const f32x4 (&acc)[2][2][4][2], const Unit& u, int wr, int wc, int fr, int fq) const {
;     ...
;                 for (int n = 0; n < 2; ++n) { const int cc = bj * HALF + 4 * n;
;                     f32x4 v = acc[ai][bj][m][n];
;                     if (bias) { v = (v + *(const f32x4*)(bias + col0 + cc)) * *(const f32x4*)(scale + col0 + cc); }
;                     f32x4 b;
;                     if (MODE >= 3) b = (f32x4){0.f, 0.f, 0.f, 0.f};
;                     else if (MODE == 0) b = __builtin_bit_cast(f32x4, cur[bj][n]);
;                     else { const unsigned w0 = n ? cur[bj][0].z : cur[bj][0].x, w1 = n ? cur[bj][0].w : cur[bj][0].y; b = (f32x4){bflo(w0), bfhi(w0), bflo(w1), bfhi(w1)}; }
;                     o[n] = b + v;
;                     if (MODE == 2 || MODE == 4) *(f32x4*)(out + off + cc) = o[n];
;                     ss += (o[n][0] * o[n][0] + o[n][1] * o[n][1]) + (o[n][2] * o[n][2] + o[n][3] * o[n][3]); }
;                 if (MODE != 2 && MODE != 4) { u32x4 w; w.x = pk2(o[0][0], o[0][1]); w.y = pk2(o[0][2], o[0][3]); w.z = pk2(o[1][0], o[1][1]); w.w = pk2(o[1][2], o[1][3]); *(u32x4*)(xb + off + bj * HALF) = w; } }
;             if (MODE != 2 && MODE != 4 && rsq) { ss += __shfl_xor(ss, 16); ss += __shfl_xor(ss, 32); if (fq == 0) rsq[(size_t)row * 64 + u.pn * 4 + wc] = ss; }
.LBB0_1385:
	v_or_b32_e32 v80, 48, v142
	s_waitcnt lgkmcnt(0)
	v_ashrrev_i32_e32 v81, 31, v80
	v_lshlrev_b64 v[88:89], 12, v[80:81]
	v_pk_add_f32 v[50:51], v[50:51], 0 op_sel_hi:[1,0]
	v_pk_add_f32 v[82:83], v[48:49], 0 op_sel_hi:[1,0]
	v_pk_add_f32 v[48:49], v[54:55], 0 op_sel_hi:[1,0]
	v_pk_add_f32 v[54:55], v[52:53], 0 op_sel_hi:[1,0]
	v_lshl_add_u64 v[52:53], s[10:11], 0, v[88:89]
	v_cvt_pk_bf16_f32 v84, v82, v83
	v_cvt_pk_bf16_f32 v85, v50, v51
	v_cvt_pk_bf16_f32 v86, v54, v55
	v_cvt_pk_bf16_f32 v87, v48, v49
	v_lshl_add_u64 v[88:89], v[140:141], 1, v[52:53]
	global_store_dwordx4 v[88:89], v[84:87], off sc0 sc1
	v_pk_add_f32 v[70:71], v[70:71], 0 op_sel_hi:[1,0]
	v_pk_add_f32 v[52:53], v[78:79], 0 op_sel_hi:[1,0]
	v_pk_add_f32 v[84:85], v[68:69], 0 op_sel_hi:[1,0]
	v_pk_add_f32 v[68:69], v[76:77], 0 op_sel_hi:[1,0]
	v_cvt_pk_bf16_f32 v76, v84, v85
	v_cvt_pk_bf16_f32 v77, v70, v71
	v_cvt_pk_bf16_f32 v78, v68, v69
	v_cvt_pk_bf16_f32 v79, v52, v53
	s_and_b64 vcc, exec, s[8:9]
	global_store_dwordx4 v[88:89], v[76:79], off offset:256 sc0 sc1
	s_cbranch_vccnz .LBB0_1389
	s_nop 0
	v_mul_f32_e32 v76, v83, v83
	v_mul_f32_e32 v51, v51, v51
	v_fmac_f32_e32 v76, v82, v82
	v_fmac_f32_e32 v51, v50, v50
	v_add_f32_e32 v50, v76, v51
	v_mul_f32_e32 v51, v55, v55
	v_mul_f32_e32 v49, v49, v49
	v_fmac_f32_e32 v51, v54, v54
	v_fmac_f32_e32 v49, v48, v48
	v_add_f32_e32 v48, v51, v49
	v_add_f32_e32 v48, v50, v48
	v_mul_f32_e32 v49, v85, v85
	v_mul_f32_e32 v50, v71, v71
	v_fmac_f32_e32 v49, v84, v84
	v_fmac_f32_e32 v50, v70, v70
	v_add_f32_e32 v49, v49, v50
	v_add_f32_e32 v48, v48, v49
	v_mul_f32_e32 v49, v69, v69
	v_mul_f32_e32 v50, v53, v53
	v_fmac_f32_e32 v49, v68, v68
	v_fmac_f32_e32 v50, v52, v52
	v_add_f32_e32 v49, v49, v50
	v_and_b32_e32 v50, 64, v251
	v_add_f32_e32 v48, v48, v49
	v_xor_b32_e32 v49, 16, v251
	v_add_u32_e32 v50, 64, v50
	v_cmp_lt_i32_e32 vcc, v49, v50
	s_nop 1
	v_cndmask_b32_e32 v49, v251, v49, vcc
	v_lshlrev_b32_e32 v49, 2, v49
	ds_bpermute_b32 v49, v49, v48
	s_waitcnt lgkmcnt(0)
	v_add_f32_e32 v48, v48, v49
	v_xor_b32_e32 v49, 32, v251
	v_cmp_lt_i32_e32 vcc, v49, v50
	s_nop 1
	v_cndmask_b32_e32 v49, v251, v49, vcc
	v_lshlrev_b32_e32 v49, 2, v49
	ds_bpermute_b32 v49, v49, v48
	s_and_saveexec_b64 s[54:55], s[4:5]
	s_cbranch_execz .LBB0_1388
	v_lshlrev_b64 v[50:51], 8, v[80:81]
	v_lshl_add_u64 v[50:51], s[14:15], 0, v[50:51]
	v_lshl_add_u64 v[50:51], s[16:17], 2, v[50:51]
	s_lshl_b32 s18, s2, 2
	v_lshl_add_u64 v[50:51], v[50:51], 0, s[18:19]
	s_waitcnt lgkmcnt(0)
	v_add_f32_e32 v48, v48, v49
	global_store_dword v[50:51], v48, off

; __device__ __forceinline__ unsigned pk2(float lo, float hi) { f32x2 v = {lo, hi}; bf16x2_t b = __builtin_convertvector(v, bf16x2_t); return __builtin_bit_cast(unsigned, b); }
; __device__ __forceinline__ float bflo(unsigned w) { return __uint_as_float(w << 16); }
; __device__ __forceinline__ float bfhi(unsigned w) { return __uint_as_float(w & 0xffff0000u); }
;     __device__ __forceinline__ void operator()(const f32x4 (&acc)[2][2][4][2], const Unit& u, int wr, int wc, int fr, int fq) const {
;     ...
;                 for (int n = 0; n < 2; ++n) { const int cc = bj * HALF + 4 * n;
;                     f32x4 v = acc[ai][bj][m][n];
;                     if (bias) { v = (v + *(const f32x4*)(bias + col0 + cc)) * *(const f32x4*)(scale + col0 + cc); }
;                     f32x4 b;
;                     if (MODE >= 3) b = (f32x4){0.f, 0.f, 0.f, 0.f};
;                     else if (MODE == 0) b = __builtin_bit_cast(f32x4, cur[bj][n]);
;                     else { const unsigned w0 = n ? cur[bj][0].z : cur[bj][0].x, w1 = n ? cur[bj][0].w : cur[bj][0].y; b = (f32x4){bflo(w0), bfhi(w0), bflo(w1), bfhi(w1)}; }
;                     o[n] = b + v;
;                     if (MODE == 2 || MODE == 4) *(f32x4*)(out + off + cc) = o[n];
;                     ss += (o[n][0] * o[n][0] + o[n][1] * o[n][1]) + (o[n][2] * o[n][2] + o[n][3] * o[n][3]); }
;                 if (MODE != 2 && MODE != 4) { u32x4 w; w.x = pk2(o[0][0], o[0][1]); w.y = pk2(o[0][2], o[0][3]); w.z = pk2(o[1][0], o[1][1]); w.w = pk2(o[1][2], o[1][3]); *(u32x4*)(xb + off + bj * HALF) = w; } }
;             if (MODE != 2 && MODE != 4 && rsq) { ss += __shfl_xor(ss, 16); ss += __shfl_xor(ss, 32); if (fq == 0) rsq[(size_t)row * 64 + u.pn * 4 + wc] = ss; }
.LBB0_1389:
	v_add_u32_e32 v48, 0x80, v142
	s_waitcnt lgkmcnt(0)
	v_ashrrev_i32_e32 v49, 31, v48
	v_lshlrev_b64 v[68:69], 12, v[48:49]
	v_pk_add_f32 v[38:39], v[38:39], 0 op_sel_hi:[1,0]
	v_pk_add_f32 v[50:51], v[36:37], 0 op_sel_hi:[1,0]
	v_pk_add_f32 v[36:37], v[46:47], 0 op_sel_hi:[1,0]
	v_pk_add_f32 v[46:47], v[44:45], 0 op_sel_hi:[1,0]
	v_lshl_add_u64 v[44:45], s[10:11], 0, v[68:69]
	v_cvt_pk_bf16_f32 v52, v50, v51
	v_cvt_pk_bf16_f32 v53, v38, v39
	v_cvt_pk_bf16_f32 v54, v46, v47
	v_cvt_pk_bf16_f32 v55, v36, v37
	v_lshl_add_u64 v[68:69], v[140:141], 1, v[44:45]
	global_store_dwordx4 v[68:69], v[52:55], off sc0 sc1
	v_pk_add_f32 v[56:57], v[56:57], 0 op_sel_hi:[1,0]
	v_pk_add_f32 v[44:45], v[62:63], 0 op_sel_hi:[1,0]
	v_pk_add_f32 v[52:53], v[58:59], 0 op_sel_hi:[1,0]
	v_pk_add_f32 v[54:55], v[60:61], 0 op_sel_hi:[1,0]
	v_cvt_pk_bf16_f32 v58, v56, v57
	v_cvt_pk_bf16_f32 v59, v52, v53
	v_cvt_pk_bf16_f32 v60, v54, v55
	v_cvt_pk_bf16_f32 v61, v44, v45
	s_and_b64 vcc, exec, s[8:9]
	global_store_dwordx4 v[68:69], v[58:61], off offset:256 sc0 sc1
	s_cbranch_vccnz .LBB0_1393
	v_mul_f32_e32 v51, v51, v51
	v_mul_f32_e32 v39, v39, v39
	v_fmac_f32_e32 v51, v50, v50
	v_fmac_f32_e32 v39, v38, v38
	v_add_f32_e32 v38, v51, v39
	v_mul_f32_e32 v39, v47, v47
	v_mul_f32_e32 v37, v37, v37
	v_fmac_f32_e32 v39, v46, v46
	v_fmac_f32_e32 v37, v36, v36
	v_add_f32_e32 v36, v39, v37
	v_add_f32_e32 v36, v38, v36
	v_mul_f32_e32 v37, v57, v57
	v_mul_f32_e32 v38, v53, v53
	v_fmac_f32_e32 v37, v56, v56
	v_fmac_f32_e32 v38, v52, v52
	v_add_f32_e32 v37, v37, v38
	v_add_f32_e32 v36, v36, v37
	v_mul_f32_e32 v37, v55, v55
	v_mul_f32_e32 v38, v45, v45
	v_fmac_f32_e32 v37, v54, v54
	v_fmac_f32_e32 v38, v44, v44
	v_add_f32_e32 v37, v37, v38
	v_and_b32_e32 v38, 64, v251
	v_add_f32_e32 v36, v36, v37
	v_xor_b32_e32 v37, 16, v251
	v_add_u32_e32 v38, 64, v38
	v_cmp_lt_i32_e32 vcc, v37, v38
	s_nop 1
	v_cndmask_b32_e32 v37, v251, v37, vcc
	v_lshlrev_b32_e32 v37, 2, v37
	ds_bpermute_b32 v37, v37, v36
	s_waitcnt lgkmcnt(0)
	v_add_f32_e32 v36, v36, v37
	v_xor_b32_e32 v37, 32, v251
	v_cmp_lt_i32_e32 vcc, v37, v38
	s_nop 1
	v_cndmask_b32_e32 v37, v251, v37, vcc
	v_lshlrev_b32_e32 v37, 2, v37
	ds_bpermute_b32 v37, v37, v36
	s_and_saveexec_b64 s[54:55], s[4:5]
	s_cbranch_execz .LBB0_1392
	v_lshlrev_b64 v[38:39], 8, v[48:49]
	v_lshl_add_u64 v[38:39], s[14:15], 0, v[38:39]
	v_lshl_add_u64 v[38:39], s[16:17], 2, v[38:39]
	s_lshl_b32 s18, s2, 2
	v_lshl_add_u64 v[38:39], v[38:39], 0, s[18:19]
	s_waitcnt lgkmcnt(0)
	v_add_f32_e32 v36, v36, v37
	global_store_dword v[38:39], v36, off

; __device__ __forceinline__ unsigned pk2(float lo, float hi) { f32x2 v = {lo, hi}; bf16x2_t b = __builtin_convertvector(v, bf16x2_t); return __builtin_bit_cast(unsigned, b); }
; __device__ __forceinline__ float bflo(unsigned w) { return __uint_as_float(w << 16); }
; __device__ __forceinline__ float bfhi(unsigned w) { return __uint_as_float(w & 0xffff0000u); }
;     __device__ __forceinline__ void operator()(const f32x4 (&acc)[2][2][4][2], const Unit& u, int wr, int wc, int fr, int fq) const {
;     ...
;                 for (int n = 0; n < 2; ++n) { const int cc = bj * HALF + 4 * n;
;                     f32x4 v = acc[ai][bj][m][n];
;                     if (bias) { v = (v + *(const f32x4*)(bias + col0 + cc)) * *(const f32x4*)(scale + col0 + cc); }
;                     f32x4 b;
;                     if (MODE >= 3) b = (f32x4){0.f, 0.f, 0.f, 0.f};
;                     else if (MODE == 0) b = __builtin_bit_cast(f32x4, cur[bj][n]);
;                     else { const unsigned w0 = n ? cur[bj][0].z : cur[bj][0].x, w1 = n ? cur[bj][0].w : cur[bj][0].y; b = (f32x4){bflo(w0), bfhi(w0), bflo(w1), bfhi(w1)}; }
;                     o[n] = b + v;
;                     if (MODE == 2 || MODE == 4) *(f32x4*)(out + off + cc) = o[n];
;                     ss += (o[n][0] * o[n][0] + o[n][1] * o[n][1]) + (o[n][2] * o[n][2] + o[n][3] * o[n][3]); }
;                 if (MODE != 2 && MODE != 4) { u32x4 w; w.x = pk2(o[0][0], o[0][1]); w.y = pk2(o[0][2], o[0][3]); w.z = pk2(o[1][0], o[1][1]); w.w = pk2(o[1][2], o[1][3]); *(u32x4*)(xb + off + bj * HALF) = w; } }
;             if (MODE != 2 && MODE != 4 && rsq) { ss += __shfl_xor(ss, 16); ss += __shfl_xor(ss, 32); if (fq == 0) rsq[(size_t)row * 64 + u.pn * 4 + wc] = ss; }
.LBB0_1393:
	v_or_b32_e32 v36, 16, v48
	s_waitcnt lgkmcnt(0)
	v_ashrrev_i32_e32 v37, 31, v36
	v_lshlrev_b64 v[50:51], 12, v[36:37]
	v_pk_add_f32 v[14:15], v[14:15], 0 op_sel_hi:[1,0]
	v_pk_add_f32 v[38:39], v[12:13], 0 op_sel_hi:[1,0]
	v_pk_add_f32 v[12:13], v[22:23], 0 op_sel_hi:[1,0]
	v_pk_add_f32 v[22:23], v[20:21], 0 op_sel_hi:[1,0]
	v_lshl_add_u64 v[20:21], s[10:11], 0, v[50:51]
	v_cvt_pk_bf16_f32 v44, v38, v39
	v_cvt_pk_bf16_f32 v45, v14, v15
	v_cvt_pk_bf16_f32 v46, v22, v23
	v_cvt_pk_bf16_f32 v47, v12, v13
	v_lshl_add_u64 v[56:57], v[140:141], 1, v[20:21]
	global_store_dwordx4 v[56:57], v[44:47], off sc0 sc1
	v_pk_add_f32 v[50:51], v[64:65], 0 op_sel_hi:[1,0]
	v_pk_add_f32 v[20:21], v[74:75], 0 op_sel_hi:[1,0]
	v_pk_add_f32 v[44:45], v[66:67], 0 op_sel_hi:[1,0]
	v_pk_add_f32 v[46:47], v[72:73], 0 op_sel_hi:[1,0]
	v_cvt_pk_bf16_f32 v52, v50, v51
	v_cvt_pk_bf16_f32 v53, v44, v45
	v_cvt_pk_bf16_f32 v54, v46, v47
	v_cvt_pk_bf16_f32 v55, v20, v21
	s_and_b64 vcc, exec, s[8:9]
	global_store_dwordx4 v[56:57], v[52:55], off offset:256 sc0 sc1
	s_cbranch_vccnz .LBB0_1397
	v_mul_f32_e32 v39, v39, v39
	v_mul_f32_e32 v15, v15, v15
	v_fmac_f32_e32 v39, v38, v38
	v_fmac_f32_e32 v15, v14, v14
	v_add_f32_e32 v14, v39, v15
	v_mul_f32_e32 v15, v23, v23
	v_mul_f32_e32 v13, v13, v13
	v_fmac_f32_e32 v15, v22, v22
	v_fmac_f32_e32 v13, v12, v12
	v_add_f32_e32 v12, v15, v13
	v_add_f32_e32 v12, v14, v12
	v_mul_f32_e32 v13, v51, v51
	v_mul_f32_e32 v14, v45, v45
	v_fmac_f32_e32 v13, v50, v50
	v_fmac_f32_e32 v14, v44, v44
	v_add_f32_e32 v13, v13, v14
	v_add_f32_e32 v12, v12, v13
	v_mul_f32_e32 v13, v47, v47
	v_mul_f32_e32 v14, v21, v21
	v_fmac_f32_e32 v13, v46, v46
	v_fmac_f32_e32 v14, v20, v20
	v_add_f32_e32 v13, v13, v14
	v_and_b32_e32 v14, 64, v251
	v_add_f32_e32 v12, v12, v13
	v_xor_b32_e32 v13, 16, v251
	v_add_u32_e32 v14, 64, v14
	v_cmp_lt_i32_e32 vcc, v13, v14
	s_nop 1
	v_cndmask_b32_e32 v13, v251, v13, vcc
	v_lshlrev_b32_e32 v13, 2, v13
	ds_bpermute_b32 v13, v13, v12
	s_waitcnt lgkmcnt(0)
	v_add_f32_e32 v12, v12, v13
	v_xor_b32_e32 v13, 32, v251
	v_cmp_lt_i32_e32 vcc, v13, v14
	s_nop 1
	v_cndmask_b32_e32 v13, v251, v13, vcc
	v_lshlrev_b32_e32 v13, 2, v13
	ds_bpermute_b32 v13, v13, v12
	s_and_saveexec_b64 s[54:55], s[4:5]
	s_cbranch_execz .LBB0_1396
	v_lshlrev_b64 v[14:15], 8, v[36:37]
	v_lshl_add_u64 v[14:15], s[14:15], 0, v[14:15]
	v_lshl_add_u64 v[14:15], s[16:17], 2, v[14:15]
	s_lshl_b32 s18, s2, 2
	v_lshl_add_u64 v[14:15], v[14:15], 0, s[18:19]
	s_waitcnt lgkmcnt(0)
	v_add_f32_e32 v12, v12, v13
	global_store_dword v[14:15], v12, off

; __device__ __forceinline__ unsigned pk2(float lo, float hi) { f32x2 v = {lo, hi}; bf16x2_t b = __builtin_convertvector(v, bf16x2_t); return __builtin_bit_cast(unsigned, b); }
; __device__ __forceinline__ float bflo(unsigned w) { return __uint_as_float(w << 16); }
; __device__ __forceinline__ float bfhi(unsigned w) { return __uint_as_float(w & 0xffff0000u); }
;     __device__ __forceinline__ void operator()(const f32x4 (&acc)[2][2][4][2], const Unit& u, int wr, int wc, int fr, int fq) const {
;     ...
;                 for (int n = 0; n < 2; ++n) { const int cc = bj * HALF + 4 * n;
;                     f32x4 v = acc[ai][bj][m][n];
;                     if (bias) { v = (v + *(const f32x4*)(bias + col0 + cc)) * *(const f32x4*)(scale + col0 + cc); }
;                     f32x4 b;
;                     if (MODE >= 3) b = (f32x4){0.f, 0.f, 0.f, 0.f};
;                     else if (MODE == 0) b = __builtin_bit_cast(f32x4, cur[bj][n]);
;                     else { const unsigned w0 = n ? cur[bj][0].z : cur[bj][0].x, w1 = n ? cur[bj][0].w : cur[bj][0].y; b = (f32x4){bflo(w0), bfhi(w0), bflo(w1), bfhi(w1)}; }
;                     o[n] = b + v;
;                     if (MODE == 2 || MODE == 4) *(f32x4*)(out + off + cc) = o[n];
;                     ss += (o[n][0] * o[n][0] + o[n][1] * o[n][1]) + (o[n][2] * o[n][2] + o[n][3] * o[n][3]); }
;                 if (MODE != 2 && MODE != 4) { u32x4 w; w.x = pk2(o[0][0], o[0][1]); w.y = pk2(o[0][2], o[0][3]); w.z = pk2(o[1][0], o[1][1]); w.w = pk2(o[1][2], o[1][3]); *(u32x4*)(xb + off + bj * HALF) = w; } }
;             if (MODE != 2 && MODE != 4 && rsq) { ss += __shfl_xor(ss, 16); ss += __shfl_xor(ss, 32); if (fq == 0) rsq[(size_t)row * 64 + u.pn * 4 + wc] = ss; }
.LBB0_1397:
	v_or_b32_e32 v12, 32, v48
	s_waitcnt lgkmcnt(0)
	v_ashrrev_i32_e32 v13, 31, v12
	v_lshlrev_b64 v[22:23], 12, v[12:13]
	v_pk_add_f32 v[20:21], v[26:27], 0 op_sel_hi:[1,0]
	v_pk_add_f32 v[26:27], v[24:25], 0 op_sel_hi:[1,0]
	v_pk_add_f32 v[14:15], v[30:31], 0 op_sel_hi:[1,0]
	v_pk_add_f32 v[24:25], v[28:29], 0 op_sel_hi:[1,0]
	v_lshl_add_u64 v[22:23], s[10:11], 0, v[22:23]
	v_cvt_pk_bf16_f32 v28, v26, v27
	v_cvt_pk_bf16_f32 v29, v20, v21
	v_cvt_pk_bf16_f32 v30, v24, v25
	v_cvt_pk_bf16_f32 v31, v14, v15
	v_lshl_add_u64 v[38:39], v[140:141], 1, v[22:23]
	global_store_dwordx4 v[38:39], v[28:31], off sc0 sc1
	v_pk_add_f32 v[32:33], v[32:33], 0 op_sel_hi:[1,0]
	v_pk_add_f32 v[22:23], v[42:43], 0 op_sel_hi:[1,0]
	v_pk_add_f32 v[28:29], v[34:35], 0 op_sel_hi:[1,0]
	v_pk_add_f32 v[30:31], v[40:41], 0 op_sel_hi:[1,0]
	v_cvt_pk_bf16_f32 v34, v32, v33
	v_cvt_pk_bf16_f32 v35, v28, v29
	v_cvt_pk_bf16_f32 v36, v30, v31
	v_cvt_pk_bf16_f32 v37, v22, v23
	s_and_b64 vcc, exec, s[8:9]
	global_store_dwordx4 v[38:39], v[34:37], off offset:256 sc0 sc1
	s_cbranch_vccnz .LBB0_1401
	v_mul_f32_e32 v27, v27, v27
	v_mul_f32_e32 v21, v21, v21
	v_fmac_f32_e32 v27, v26, v26
	v_fmac_f32_e32 v21, v20, v20
	v_add_f32_e32 v20, v27, v21
	v_mul_f32_e32 v21, v25, v25
	v_mul_f32_e32 v15, v15, v15
	v_fmac_f32_e32 v21, v24, v24
	v_fmac_f32_e32 v15, v14, v14
	v_add_f32_e32 v14, v21, v15
	v_add_f32_e32 v14, v20, v14
	v_mul_f32_e32 v15, v33, v33
	v_mul_f32_e32 v20, v29, v29
	v_fmac_f32_e32 v15, v32, v32
	v_fmac_f32_e32 v20, v28, v28
	v_add_f32_e32 v15, v15, v20
	v_add_f32_e32 v14, v14, v15
	v_mul_f32_e32 v15, v31, v31
	v_mul_f32_e32 v20, v23, v23
	v_fmac_f32_e32 v15, v30, v30
	v_fmac_f32_e32 v20, v22, v22
	v_add_f32_e32 v15, v15, v20
	v_and_b32_e32 v20, 64, v251
	v_add_f32_e32 v14, v14, v15
	v_xor_b32_e32 v15, 16, v251
	v_add_u32_e32 v20, 64, v20
	v_cmp_lt_i32_e32 vcc, v15, v20
	s_nop 1
	v_cndmask_b32_e32 v15, v251, v15, vcc
	v_lshlrev_b32_e32 v15, 2, v15
	ds_bpermute_b32 v15, v15, v14
	s_waitcnt lgkmcnt(0)
	v_add_f32_e32 v14, v14, v15
	v_xor_b32_e32 v15, 32, v251
	v_cmp_lt_i32_e32 vcc, v15, v20
	s_nop 1
	v_cndmask_b32_e32 v15, v251, v15, vcc
	v_lshlrev_b32_e32 v15, 2, v15
	ds_bpermute_b32 v15, v15, v14
	s_and_saveexec_b64 s[54:55], s[4:5]
	s_cbranch_execz .LBB0_1400
	v_lshlrev_b64 v[12:13], 8, v[12:13]
	v_lshl_add_u64 v[12:13], s[14:15], 0, v[12:13]
	v_lshl_add_u64 v[12:13], s[16:17], 2, v[12:13]
	s_lshl_b32 s18, s2, 2
	v_lshl_add_u64 v[12:13], v[12:13], 0, s[18:19]
	s_waitcnt lgkmcnt(0)
	v_add_f32_e32 v14, v14, v15
	global_store_dword v[12:13], v14, off

; __device__ __forceinline__ unsigned pk2(float lo, float hi) { f32x2 v = {lo, hi}; bf16x2_t b = __builtin_convertvector(v, bf16x2_t); return __builtin_bit_cast(unsigned, b); }
; __device__ __forceinline__ float bflo(unsigned w) { return __uint_as_float(w << 16); }
; __device__ __forceinline__ float bfhi(unsigned w) { return __uint_as_float(w & 0xffff0000u); }
;     __device__ __forceinline__ void operator()(const f32x4 (&acc)[2][2][4][2], const Unit& u, int wr, int wc, int fr, int fq) const {
;     ...
;                 for (int n = 0; n < 2; ++n) { const int cc = bj * HALF + 4 * n;
;                     f32x4 v = acc[ai][bj][m][n];
;                     if (bias) { v = (v + *(const f32x4*)(bias + col0 + cc)) * *(const f32x4*)(scale + col0 + cc); }
;                     f32x4 b;
;                     if (MODE >= 3) b = (f32x4){0.f, 0.f, 0.f, 0.f};
;                     else if (MODE == 0) b = __builtin_bit_cast(f32x4, cur[bj][n]);
;                     else { const unsigned w0 = n ? cur[bj][0].z : cur[bj][0].x, w1 = n ? cur[bj][0].w : cur[bj][0].y; b = (f32x4){bflo(w0), bfhi(w0), bflo(w1), bfhi(w1)}; }
;                     o[n] = b + v;
;                     if (MODE == 2 || MODE == 4) *(f32x4*)(out + off + cc) = o[n];
;                     ss += (o[n][0] * o[n][0] + o[n][1] * o[n][1]) + (o[n][2] * o[n][2] + o[n][3] * o[n][3]); }
;                 if (MODE != 2 && MODE != 4) { u32x4 w; w.x = pk2(o[0][0], o[0][1]); w.y = pk2(o[0][2], o[0][3]); w.z = pk2(o[1][0], o[1][1]); w.w = pk2(o[1][2], o[1][3]); *(u32x4*)(xb + off + bj * HALF) = w; } }
;             if (MODE != 2 && MODE != 4 && rsq) { ss += __shfl_xor(ss, 16); ss += __shfl_xor(ss, 32); if (fq == 0) rsq[(size_t)row * 64 + u.pn * 4 + wc] = ss; }
.LBB0_1401:
	v_or_b32_e32 v12, 48, v48
	v_ashrrev_i32_e32 v13, 31, v12
	v_lshlrev_b64 v[24:25], 12, v[12:13]
	v_pk_add_f32 v[2:3], v[2:3], 0 op_sel_hi:[1,0]
	s_waitcnt lgkmcnt(0)
	v_pk_add_f32 v[14:15], v[0:1], 0 op_sel_hi:[1,0]
	v_pk_add_f32 v[0:1], v[6:7], 0 op_sel_hi:[1,0]
	v_pk_add_f32 v[6:7], v[4:5], 0 op_sel_hi:[1,0]
	v_lshl_add_u64 v[4:5], s[10:11], 0, v[24:25]
	v_cvt_pk_bf16_f32 v20, v14, v15
	v_cvt_pk_bf16_f32 v21, v2, v3
	v_cvt_pk_bf16_f32 v22, v6, v7
	v_cvt_pk_bf16_f32 v23, v0, v1
	v_lshl_add_u64 v[24:25], v[140:141], 1, v[4:5]
	global_store_dwordx4 v[24:25], v[20:23], off sc0 sc1
	v_pk_add_f32 v[10:11], v[10:11], 0 op_sel_hi:[1,0]
	v_pk_add_f32 v[4:5], v[18:19], 0 op_sel_hi:[1,0]
	v_pk_add_f32 v[20:21], v[8:9], 0 op_sel_hi:[1,0]
	v_pk_add_f32 v[8:9], v[16:17], 0 op_sel_hi:[1,0]
	v_cvt_pk_bf16_f32 v16, v20, v21
	v_cvt_pk_bf16_f32 v17, v10, v11
	v_cvt_pk_bf16_f32 v18, v8, v9
	v_cvt_pk_bf16_f32 v19, v4, v5
	s_and_b64 vcc, exec, s[8:9]
	global_store_dwordx4 v[24:25], v[16:19], off offset:256 sc0 sc1
	s_cbranch_vccnz .LBB0_1405
	v_mul_f32_e32 v15, v15, v15
	v_mul_f32_e32 v3, v3, v3
	v_fmac_f32_e32 v15, v14, v14
	v_fmac_f32_e32 v3, v2, v2
	v_add_f32_e32 v2, v15, v3
	v_mul_f32_e32 v3, v7, v7
	v_mul_f32_e32 v1, v1, v1
	v_fmac_f32_e32 v3, v6, v6
	v_fmac_f32_e32 v1, v0, v0
	v_add_f32_e32 v0, v3, v1
	v_add_f32_e32 v0, v2, v0
	v_mul_f32_e32 v1, v21, v21
	v_mul_f32_e32 v2, v11, v11
	v_fmac_f32_e32 v1, v20, v20
	v_fmac_f32_e32 v2, v10, v10
	v_add_f32_e32 v1, v1, v2
	v_add_f32_e32 v0, v0, v1
	v_mul_f32_e32 v1, v9, v9
	v_mul_f32_e32 v2, v5, v5
	v_fmac_f32_e32 v1, v8, v8
	v_fmac_f32_e32 v2, v4, v4
	v_add_f32_e32 v1, v1, v2
	v_and_b32_e32 v2, 64, v251
	v_add_f32_e32 v0, v0, v1
	v_xor_b32_e32 v1, 16, v251
	v_add_u32_e32 v2, 64, v2
	v_cmp_lt_i32_e32 vcc, v1, v2
	s_nop 1
	v_cndmask_b32_e32 v1, v251, v1, vcc
	v_lshlrev_b32_e32 v1, 2, v1
	ds_bpermute_b32 v1, v1, v0
	s_waitcnt lgkmcnt(0)
	v_add_f32_e32 v0, v0, v1
	v_xor_b32_e32 v1, 32, v251
	v_cmp_lt_i32_e32 vcc, v1, v2
	s_nop 1
	v_cndmask_b32_e32 v1, v251, v1, vcc
	v_lshlrev_b32_e32 v1, 2, v1
	ds_bpermute_b32 v1, v1, v0
	s_and_saveexec_b64 s[8:9], s[4:5]
	s_cbranch_execz .LBB0_1404
	v_lshlrev_b64 v[2:3], 8, v[12:13]
	v_lshl_add_u64 v[2:3], s[14:15], 0, v[2:3]
	v_lshl_add_u64 v[2:3], s[16:17], 2, v[2:3]
	s_lshl_b32 s18, s2, 2
	v_lshl_add_u64 v[2:3], v[2:3], 0, s[18:19]
	s_waitcnt lgkmcnt(0)
	v_add_f32_e32 v0, v0, v1
	global_store_dword v[2:3], v0, off

; __device__ __forceinline__ float bflo(unsigned w) { return __uint_as_float(w << 16); }
; __device__ __forceinline__ float bfhi(unsigned w) { return __uint_as_float(w & 0xffff0000u); }
;     __device__ __forceinline__ void operator()(const f32x4 (&acc)[2][2][4][2], const Unit& u, int wr, int wc, int fr, int fq) const {
;     ...
;                     f32x4 v = acc[ai][bj][m][n];
;                     if (bias) { v = (v + *(const f32x4*)(bias + col0 + cc)) * *(const f32x4*)(scale + col0 + cc); }
;                     f32x4 b;
;                     if (MODE >= 3) b = (f32x4){0.f, 0.f, 0.f, 0.f};
;                     else if (MODE == 0) b = __builtin_bit_cast(f32x4, cur[bj][n]);
;                     else { const unsigned w0 = n ? cur[bj][0].z : cur[bj][0].x, w1 = n ? cur[bj][0].w : cur[bj][0].y; b = (f32x4){bflo(w0), bfhi(w0), bflo(w1), bfhi(w1)}; }
;                     o[n] = b + v;
;                     if (MODE == 2 || MODE == 4) *(f32x4*)(out + off + cc) = o[n];
.LBB0_1435:
	v_lshl_add_u32 v140, s42, 8, v142
	v_lshl_or_b32 v150, s37, 8, v144
	v_ashrrev_i32_e32 v141, 31, v140
	v_ashrrev_i32_e32 v151, 31, v150
	v_lshlrev_b64 v[152:153], 13, v[140:141]
	v_pk_add_f32 v[148:149], v[30:31], 0 op_sel_hi:[1,0]
	v_pk_add_f32 v[146:147], v[28:29], 0 op_sel_hi:[1,0]
	v_lshl_add_u64 v[30:31], s[10:11], 0, v[152:153]
	v_lshlrev_b64 v[28:29], 2, v[150:151]
	v_lshl_add_u64 v[30:31], v[30:31], 0, v[28:29]
	v_pk_add_f32 v[26:27], v[26:27], 0 op_sel_hi:[1,0]
	v_pk_add_f32 v[24:25], v[24:25], 0 op_sel_hi:[1,0]
	global_store_dwordx4 v[30:31], v[24:27], off offset:16 sc0 sc1
	global_store_dwordx4 v[30:31], v[146:149], off sc0 sc1
	v_pk_add_f32 v[18:19], v[18:19], 0 op_sel_hi:[1,0]
	v_pk_add_f32 v[26:27], v[90:91], 0 op_sel_hi:[1,0]
	v_pk_add_f32 v[24:25], v[88:89], 0 op_sel_hi:[1,0]
	global_store_dwordx4 v[30:31], v[24:27], off offset:512 sc0 sc1
	v_pk_add_f32 v[16:17], v[16:17], 0 op_sel_hi:[1,0]
	v_pk_add_f32 v[10:11], v[10:11], 0 op_sel_hi:[1,0]
	v_pk_add_f32 v[26:27], v[94:95], 0 op_sel_hi:[1,0]
	v_pk_add_f32 v[24:25], v[92:93], 0 op_sel_hi:[1,0]
	global_store_dwordx4 v[30:31], v[24:27], off offset:528 sc0 sc1
	v_pk_add_f32 v[8:9], v[8:9], 0 op_sel_hi:[1,0]
	v_pk_add_f32 v[2:3], v[2:3], 0 op_sel_hi:[1,0]
	v_or_b32_e32 v24, 16, v140
	v_ashrrev_i32_e32 v25, 31, v24
	v_lshlrev_b64 v[24:25], 13, v[24:25]
	v_lshl_add_u64 v[24:25], s[10:11], 0, v[24:25]
	v_lshl_add_u64 v[24:25], v[24:25], 0, v[28:29]
	global_store_dwordx4 v[24:25], v[16:19], off sc0 sc1
	v_pk_add_f32 v[0:1], v[0:1], 0 op_sel_hi:[1,0]
	s_mov_b64 s[16:17], 0x100000
	v_pk_add_f32 v[18:19], v[22:23], 0 op_sel_hi:[1,0]
	v_pk_add_f32 v[16:17], v[20:21], 0 op_sel_hi:[1,0]
	global_store_dwordx4 v[24:25], v[16:19], off offset:16 sc0 sc1
	s_nop 1
	v_pk_add_f32 v[18:19], v[82:83], 0 op_sel_hi:[1,0]
	v_pk_add_f32 v[16:17], v[80:81], 0 op_sel_hi:[1,0]
	global_store_dwordx4 v[24:25], v[16:19], off offset:512 sc0 sc1
	s_nop 1
	v_pk_add_f32 v[18:19], v[86:87], 0 op_sel_hi:[1,0]
	v_pk_add_f32 v[16:17], v[84:85], 0 op_sel_hi:[1,0]
	global_store_dwordx4 v[24:25], v[16:19], off offset:528 sc0 sc1
	s_nop 1
	v_or_b32_e32 v16, 32, v140
	v_ashrrev_i32_e32 v17, 31, v16
	v_lshlrev_b64 v[16:17], 13, v[16:17]
	v_lshl_add_u64 v[16:17], s[10:11], 0, v[16:17]
	v_lshl_add_u64 v[16:17], v[16:17], 0, v[28:29]
	global_store_dwordx4 v[16:17], v[8:11], off sc0 sc1
	s_nop 1
	v_pk_add_f32 v[10:11], v[14:15], 0 op_sel_hi:[1,0]
	v_pk_add_f32 v[8:9], v[12:13], 0 op_sel_hi:[1,0]
	global_store_dwordx4 v[16:17], v[8:11], off offset:16 sc0 sc1
	s_nop 1
	v_pk_add_f32 v[10:11], v[70:71], 0 op_sel_hi:[1,0]
	v_pk_add_f32 v[8:9], v[68:69], 0 op_sel_hi:[1,0]
	global_store_dwordx4 v[16:17], v[8:11], off offset:512 sc0 sc1
	s_nop 1
	v_pk_add_f32 v[10:11], v[78:79], 0 op_sel_hi:[1,0]
	v_pk_add_f32 v[8:9], v[76:77], 0 op_sel_hi:[1,0]
	global_store_dwordx4 v[16:17], v[8:11], off offset:528 sc0 sc1
	s_nop 1
	v_or_b32_e32 v8, 48, v140
	v_ashrrev_i32_e32 v9, 31, v8
	v_lshlrev_b64 v[8:9], 13, v[8:9]
	v_lshl_add_u64 v[8:9], s[10:11], 0, v[8:9]
	v_lshl_add_u64 v[8:9], v[8:9], 0, v[28:29]
	global_store_dwordx4 v[8:9], v[0:3], off sc0 sc1
	s_nop 1
	v_pk_add_f32 v[2:3], v[6:7], 0 op_sel_hi:[1,0]
	v_pk_add_f32 v[0:1], v[4:5], 0 op_sel_hi:[1,0]
	global_store_dwordx4 v[8:9], v[0:3], off offset:16 sc0 sc1
	v_add_co_u32_e32 v6, vcc, s58, v30
	s_nop 0
	v_pk_add_f32 v[2:3], v[58:59], 0 op_sel_hi:[1,0]
	v_pk_add_f32 v[0:1], v[56:57], 0 op_sel_hi:[1,0]
	global_store_dwordx4 v[8:9], v[0:3], off offset:512 sc0 sc1
	v_addc_co_u32_e32 v7, vcc, 0, v31, vcc
	s_nop 0
	v_pk_add_f32 v[2:3], v[66:67], 0 op_sel_hi:[1,0]
	v_pk_add_f32 v[0:1], v[64:65], 0 op_sel_hi:[1,0]
	global_store_dwordx4 v[8:9], v[0:3], off offset:528 sc0 sc1
	v_lshl_add_u64 v[4:5], v[30:31], 0, s[16:17]
	s_and_b64 vcc, exec, s[4:5]
	v_pk_add_f32 v[2:3], v[74:75], 0 op_sel_hi:[1,0]
	v_pk_add_f32 v[0:1], v[72:73], 0 op_sel_hi:[1,0]
	global_store_dwordx4 v[6:7], v[0:3], off sc0 sc1
	s_mov_b64 s[4:5], -1
	s_nop 0
	v_pk_add_f32 v[2:3], v[62:63], 0 op_sel_hi:[1,0]
	v_pk_add_f32 v[0:1], v[60:61], 0 op_sel_hi:[1,0]
	global_store_dwordx4 v[4:5], v[0:3], off offset:16 sc0 sc1
	s_nop 1
	v_pk_add_f32 v[2:3], v[124:125], 0 op_sel_hi:[1,0]
	v_pk_add_f32 v[0:1], v[122:123], 0 op_sel_hi:[1,0]
	global_store_dwordx4 v[4:5], v[0:3], off offset:512 sc0 sc1
	s_nop 1
	v_pk_add_f32 v[2:3], v[128:129], 0 op_sel_hi:[1,0]
	v_pk_add_f32 v[0:1], v[126:127], 0 op_sel_hi:[1,0]
	global_store_dwordx4 v[4:5], v[0:3], off offset:528 sc0 sc1
	s_nop 1
	v_add_u32_e32 v0, 0x90, v140
	v_ashrrev_i32_e32 v1, 31, v0
	v_lshlrev_b64 v[4:5], 13, v[0:1]
	v_lshl_add_u64 v[4:5], s[10:11], 0, v[4:5]
; __device__ __forceinline__ float bflo(unsigned w) { return __uint_as_float(w << 16); }
; __device__ __forceinline__ float bfhi(unsigned w) { return __uint_as_float(w & 0xffff0000u); }
;     __device__ __forceinline__ void init_acc(f32x4 (&acc)[2][2][4][2], const Unit& u, int wr, int wc, int fr, int fq) const {
;     ...
;         const int row0 = u.pm * BM + wr * 64 + fr, col0 = u.pn * BM + wc * 32 + 8 * fq;
;         u32x4 raw[2][4][2];
; #pragma unroll
;         for (int ai = 0; ai < 2; ++ai)
; #pragma unroll
;             for (int m = 0; m < 4; ++m)
; #pragma unroll
;                 for (int bj = 0; bj < 2; ++bj) raw[ai][m][bj] = *(const u32x4*)(xb + (size_t)(row0 + ai * HALF + m * 16) * DM + col0 + bj * HALF);
; #pragma unroll
;         for (int ai = 0; ai < 2; ++ai)
; #pragma unroll
;             for (int m = 0; m < 4; ++m)
; #pragma unroll
;                 for (int bj = 0; bj < 2; ++bj) { const u32x4 w = raw[ai][m][bj];
;                     acc[ai][bj][m][0] = (f32x4){bflo(w.x), bfhi(w.x), bflo(w.y), bfhi(w.y)}; acc[ai][bj][m][1] = (f32x4){bflo(w.z), bfhi(w.z), bflo(w.w), bfhi(w.w)}; }
;     __device__ __forceinline__ void operator()(const f32x4 (&acc)[2][2][4][2], const Unit& u, int wr, int wc, int fr, int fq) const {
;     ...
;                     if (MODE >= 3) b = (f32x4){0.f, 0.f, 0.f, 0.f};
;                     else if (MODE == 0) b = __builtin_bit_cast(f32x4, cur[bj][n]);
;                     else { const unsigned w0 = n ? cur[bj][0].z : cur[bj][0].x, w1 = n ? cur[bj][0].w : cur[bj][0].y; b = (f32x4){bflo(w0), bfhi(w0), bflo(w1), bfhi(w1)}; }
;                     o[n] = b + v;
;                     if (MODE == 2 || MODE == 4) *(f32x4*)(out + off + cc) = o[n];
	v_pk_add_f32 v[2:3], v[50:51], 0 op_sel_hi:[1,0]
	v_pk_add_f32 v[0:1], v[48:49], 0 op_sel_hi:[1,0]
	v_lshl_add_u64 v[4:5], v[4:5], 0, v[28:29]
	global_store_dwordx4 v[4:5], v[0:3], off sc0 sc1
	s_nop 1
	v_pk_add_f32 v[2:3], v[54:55], 0 op_sel_hi:[1,0]
	v_pk_add_f32 v[0:1], v[52:53], 0 op_sel_hi:[1,0]
	global_store_dwordx4 v[4:5], v[0:3], off offset:16 sc0 sc1
	s_nop 1
	v_pk_add_f32 v[2:3], v[116:117], 0 op_sel_hi:[1,0]
	v_pk_add_f32 v[0:1], v[114:115], 0 op_sel_hi:[1,0]
	global_store_dwordx4 v[4:5], v[0:3], off offset:512 sc0 sc1
	s_nop 1
	v_pk_add_f32 v[2:3], v[120:121], 0 op_sel_hi:[1,0]
	v_pk_add_f32 v[0:1], v[118:119], 0 op_sel_hi:[1,0]
	global_store_dwordx4 v[4:5], v[0:3], off offset:528 sc0 sc1
	s_nop 1
	v_add_u32_e32 v0, 0xa0, v140
	v_ashrrev_i32_e32 v1, 31, v0
	v_lshlrev_b64 v[4:5], 13, v[0:1]
	v_lshl_add_u64 v[4:5], s[10:11], 0, v[4:5]
	v_pk_add_f32 v[2:3], v[42:43], 0 op_sel_hi:[1,0]
	v_pk_add_f32 v[0:1], v[40:41], 0 op_sel_hi:[1,0]
	v_lshl_add_u64 v[4:5], v[4:5], 0, v[28:29]
	global_store_dwordx4 v[4:5], v[0:3], off sc0 sc1
	s_nop 1
	v_pk_add_f32 v[2:3], v[46:47], 0 op_sel_hi:[1,0]
	v_pk_add_f32 v[0:1], v[44:45], 0 op_sel_hi:[1,0]
	global_store_dwordx4 v[4:5], v[0:3], off offset:16 sc0 sc1
	s_nop 1
	v_pk_add_f32 v[2:3], v[108:109], 0 op_sel_hi:[1,0]
	v_pk_add_f32 v[0:1], v[106:107], 0 op_sel_hi:[1,0]
	global_store_dwordx4 v[4:5], v[0:3], off offset:512 sc0 sc1
	s_nop 1
	v_pk_add_f32 v[2:3], v[112:113], 0 op_sel_hi:[1,0]
	v_pk_add_f32 v[0:1], v[110:111], 0 op_sel_hi:[1,0]
	global_store_dwordx4 v[4:5], v[0:3], off offset:528 sc0 sc1
	s_nop 1
	v_add_u32_e32 v0, 0xb0, v140
	v_ashrrev_i32_e32 v1, 31, v0
	v_lshlrev_b64 v[4:5], 13, v[0:1]
	v_lshl_add_u64 v[4:5], s[10:11], 0, v[4:5]
	v_pk_add_f32 v[2:3], v[34:35], 0 op_sel_hi:[1,0]
	v_pk_add_f32 v[0:1], v[32:33], 0 op_sel_hi:[1,0]
	v_lshl_add_u64 v[4:5], v[4:5], 0, v[28:29]
	global_store_dwordx4 v[4:5], v[0:3], off sc0 sc1
	s_nop 1
	v_pk_add_f32 v[2:3], v[38:39], 0 op_sel_hi:[1,0]
	v_pk_add_f32 v[0:1], v[36:37], 0 op_sel_hi:[1,0]
	global_store_dwordx4 v[4:5], v[0:3], off offset:16 sc0 sc1
	s_nop 1
	v_pk_add_f32 v[2:3], v[100:101], 0 op_sel_hi:[1,0]
	v_pk_add_f32 v[0:1], v[98:99], 0 op_sel_hi:[1,0]
	global_store_dwordx4 v[4:5], v[0:3], off offset:512 sc0 sc1
	s_nop 1
	v_pk_add_f32 v[2:3], v[104:105], 0 op_sel_hi:[1,0]
	v_pk_add_f32 v[0:1], v[102:103], 0 op_sel_hi:[1,0]
	global_store_dwordx4 v[4:5], v[0:3], off offset:528 sc0 sc1
	s_cbranch_vccnz .LBB0_1420
	v_lshl_add_u32 v4, s31, 8, v142
	v_lshl_or_b32 v0, s30, 8, v144
	v_ashrrev_i32_e32 v1, 31, v0
	v_ashrrev_i32_e32 v5, 31, v4
	v_lshl_add_u64 v[6:7], v[0:1], 1, s[8:9]
	v_lshlrev_b64 v[0:1], 12, v[4:5]
	v_lshl_add_u64 v[28:29], v[6:7], 0, v[0:1]
	v_or_b32_e32 v0, 16, v4
	v_ashrrev_i32_e32 v1, 31, v0
	v_lshlrev_b64 v[0:1], 12, v[0:1]
	v_lshl_add_u64 v[0:1], v[6:7], 0, v[0:1]
	global_load_dwordx4 v[24:27], v[28:29], off
	global_load_dwordx4 v[16:19], v[28:29], off offset:256
	global_load_dwordx4 v[20:23], v[0:1], off
	global_load_dwordx4 v[8:11], v[0:1], off offset:256
	v_or_b32_e32 v0, 32, v4
	v_or_b32_e32 v4, 48, v4
	v_ashrrev_i32_e32 v1, 31, v0
	v_ashrrev_i32_e32 v5, 31, v4
	v_lshlrev_b64 v[0:1], 12, v[0:1]
	v_lshlrev_b64 v[4:5], 12, v[4:5]
	v_add_co_u32_e32 v32, vcc, s65, v28
	v_lshl_add_u64 v[0:1], v[6:7], 0, v[0:1]
	v_lshl_add_u64 v[30:31], v[6:7], 0, v[4:5]
	s_mov_b64 s[4:5], 0x80000
	v_addc_co_u32_e32 v33, vcc, 0, v29, vcc
	global_load_dwordx4 v[12:15], v[0:1], off
	s_nop 0
	global_load_dwordx4 v[0:3], v[0:1], off offset:256
	s_nop 0
	global_load_dwordx4 v[4:7], v[30:31], off
	global_load_dwordx4 v[58:61], v[30:31], off offset:256
	v_lshl_add_u64 v[30:31], v[28:29], 0, s[4:5]
	global_load_dwordx4 v[98:101], v[32:33], off
	global_load_dwordx4 v[48:51], v[30:31], off offset:256
	v_add_co_u32_e32 v32, vcc, s66, v28
	s_mov_b64 s[4:5], 0x90000
	s_nop 0
	v_addc_co_u32_e32 v33, vcc, 0, v29, vcc
	v_lshl_add_u64 v[30:31], v[28:29], 0, s[4:5]
	global_load_dwordx4 v[52:55], v[32:33], off
	global_load_dwordx4 v[40:43], v[30:31], off offset:256
	s_mov_b64 s[4:5], 0xa0000
	v_add_co_u32_e32 v32, vcc, 0xa0000, v28
	v_lshl_add_u64 v[30:31], v[28:29], 0, s[4:5]
	s_nop 0
	v_addc_co_u32_e32 v33, vcc, 0, v29, vcc
	s_mov_b64 s[4:5], 0xb0000
	global_load_dwordx4 v[44:47], v[32:33], off
	s_nop 0
	global_load_dwordx4 v[32:35], v[30:31], off offset:256
	v_lshl_add_u64 v[30:31], v[28:29], 0, s[4:5]
	v_add_co_u32_e32 v28, vcc, 0xb0000, v28
	s_nop 1
	v_addc_co_u32_e32 v29, vcc, 0, v29, vcc
	global_load_dwordx4 v[36:39], v[28:29], off
	global_load_dwordx4 v[102:105], v[30:31], off offset:256
	s_andn2_b64 vcc, exec, s[12:13]
	s_cbranch_vccnz .LBB0_1419
	s_barrier
	s_branch .LBB0_1419
